# v18 + removed redundant mid-segment s_setprio 0/1 flip pairs inside each 32-MFMA super-phase
# speedup vs baseline: 1.0099x; 1.0033x over previous
; #define PG8_STAGE(bufoff, gbase, voff) do { _Pragma("unroll") for (int _i = 0; _i < 2; ++_i) \
;         __builtin_amdgcn_global_load_lds((const unsigned*)((const char*)(gbase) + (voff)[_i]), (PG8_LAS unsigned*)(lds + (bufoff) + ldsw + _i * 8192), 16, 0, 0); } while (0)
; #define PG8_LDA(dst, b, h) do { _Pragma("unroll") for (int m = 0; m < 4; ++m) _Pragma("unroll") for (int k = 0; k < 2; ++k) dst[m][k] = *(const PG8_LAS bf16x8*)(lds + PG8_SA(b, h) + aoff + m * 2048 + k * 1024); } while (0)
; #define PG8_LDB(dst, b, h) do { _Pragma("unroll") for (int n = 0; n < 2; ++n) _Pragma("unroll") for (int k = 0; k < 2; ++k) dst[n][k] = *(const PG8_LAS bf16x8*)(lds + PG8_SB(b, h) + boff + n * 2048 + k * 1024); } while (0)
; #define PG8_MMA(ai, bj, At, Bt) do { __builtin_amdgcn_s_setprio(1); _Pragma("unroll") for (int m = 0; m < 4; ++m) _Pragma("unroll") for (int n = 0; n < 2; ++n) _Pragma("unroll") for (int k = 0; k < 2; ++k) \
;         acc[ai][bj][m][n] = __builtin_amdgcn_mfma_f32_16x16x32_bf16(Bt[n][k], At[m][k], acc[ai][bj][m][n], 0, 0, 0); __builtin_amdgcn_s_setprio(0); } while (0)
; #define PG8_WAIT_V(n) asm volatile("s_waitcnt vmcnt(" #n ")" ::: "memory")
; #define PG8_WAIT_L(n) asm volatile("s_waitcnt lgkmcnt(" #n ")" ::: "memory")
; template <class Epi, class Sched, bool ALIGN_EPI = false, bool SP2 = false>
; __device__ __forceinline__ void gemm_phase(PG8_LAS unsigned char* lds, const Gemm g, const Sched& S, const Epi& E) {
;     ...
;             const bool last = (t == nt - 2);
;             const char* a1 = cA + (size_t)(t + 1) * kstep;
;             const char* a2 = last ? nA : cA + (size_t)(t + 2) * kstep; const char* b2 = last ? nB : cB + (size_t)(t + 2) * kstep;
;             const char* a3 = a2 + kstep; const char* b3 = b2 + kstep;
;             if (last && has_next) S.a_ready(nxt);
;             if constexpr (SP2) {
;             PG8_LDB(B0, 0, 0); PG8_LDB(B1, 0, 1); PG8_SCHED; PG8_LDA(At, 0, 0); PG8_STAGE(PG8_SA(1, 1), a1 + hstep, voffA);
;             PG8_WAIT_V(8); PG8_WAIT_L(0); PG8_BAR; PG8_MMA(0, 0, At, B0); PG8_MMA(0, 1, At, B1); PG8_BAR; PG8_SCHED;
;             PG8_LDA(At, 0, 1); PG8_STAGE(PG8_SB(0, 0), b2, voffB); PG8_STAGE(PG8_SB(0, 1), b2 + hstep, voffB); PG8_STAGE(PG8_SA(0, 0), a2, voffA);
;             PG8_WAIT_V(8); PG8_WAIT_L(0); PG8_BAR; PG8_MMA(1, 0, At, B0); PG8_MMA(1, 1, At, B1); PG8_BAR; PG8_SCHED;
.LBB0_202:
	s_add_i32 s78, s38, 2
	s_add_u32 s79, s22, 0x80
	s_addc_u32 s39, s23, 0
	s_cmp_eq_u32 s33, s38
	s_cselect_b32 s39, s7, s39
	s_cselect_b32 s38, s6, s79
	v_add_u32_e32 v0, s19, v150
	s_cselect_b32 s81, s17, s77
	s_cselect_b32 s80, s16, s76
	s_add_i32 s79, 0, 0x14000
	ds_read_b128 v[152:155], v0
	ds_read_b128 v[156:159], v0 offset:1024
	ds_read_b128 v[160:163], v0 offset:2048
	ds_read_b128 v[164:167], v0 offset:3072
	v_add_u32_e32 v0, s79, v150
	ds_read_b128 v[168:171], v0
	ds_read_b128 v[172:175], v0 offset:1024
	ds_read_b128 v[176:179], v0 offset:2048
	ds_read_b128 v[184:187], v0 offset:3072
	v_lshl_add_u64 v[2:3], s[22:23], 0, v[144:145]
	s_add_i32 m0, s42, 0xc000
	ds_read_b128 v[188:191], v151
	ds_read_b128 v[192:195], v151 offset:1024
	ds_read_b128 v[196:199], v151 offset:2048
	ds_read_b128 v[200:203], v151 offset:3072
	ds_read_b128 v[204:207], v151 offset:4096
	ds_read_b128 v[230:233], v151 offset:5120
	ds_read_b128 v[234:237], v151 offset:6144
	ds_read_b128 v[238:241], v151 offset:7168
	global_load_lds_dwordx4 v[2:3], off
	v_lshl_add_u64 v[2:3], s[22:23], 0, v[146:147]
	s_add_i32 m0, s42, 0xe000
	s_nop 0
	global_load_lds_dwordx4 v[2:3], off
	s_waitcnt vmcnt(8)
	s_waitcnt lgkmcnt(0)
	s_barrier
	s_setprio 1
	s_waitcnt lgkmcnt(0)
	v_mfma_f32_16x16x32_bf16 v[132:135], v[152:155], v[188:191], v[132:135]
	v_mfma_f32_16x16x32_bf16 v[132:135], v[156:159], v[192:195], v[132:135]
	v_mfma_f32_16x16x32_bf16 v[116:119], v[152:155], v[196:199], v[116:119]
	v_mfma_f32_16x16x32_bf16 v[116:119], v[156:159], v[200:203], v[116:119]
	v_mfma_f32_16x16x32_bf16 v[100:103], v[152:155], v[204:207], v[100:103]
	v_mfma_f32_16x16x32_bf16 v[100:103], v[156:159], v[230:233], v[100:103]
	v_mfma_f32_16x16x32_bf16 v[84:87], v[152:155], v[234:237], v[84:87]
	v_mfma_f32_16x16x32_bf16 v[84:87], v[156:159], v[238:241], v[84:87]
	v_mfma_f32_16x16x32_bf16 v[80:83], v[160:163], v[234:237], v[80:83]
	v_mfma_f32_16x16x32_bf16 v[80:83], v[164:167], v[238:241], v[80:83]
	v_mfma_f32_16x16x32_bf16 v[96:99], v[160:163], v[204:207], v[96:99]
	v_mfma_f32_16x16x32_bf16 v[96:99], v[164:167], v[230:233], v[96:99]
	v_mfma_f32_16x16x32_bf16 v[112:115], v[160:163], v[196:199], v[112:115]
	v_mfma_f32_16x16x32_bf16 v[112:115], v[164:167], v[200:203], v[112:115]
	v_mfma_f32_16x16x32_bf16 v[128:131], v[160:163], v[188:191], v[128:131]
	v_mfma_f32_16x16x32_bf16 v[128:131], v[164:167], v[192:195], v[128:131]
	v_mfma_f32_16x16x32_bf16 v[124:127], v[168:171], v[188:191], v[124:127]
	v_mfma_f32_16x16x32_bf16 v[124:127], v[172:175], v[192:195], v[124:127]
	v_mfma_f32_16x16x32_bf16 v[108:111], v[168:171], v[196:199], v[108:111]
	v_mfma_f32_16x16x32_bf16 v[108:111], v[172:175], v[200:203], v[108:111]
	v_mfma_f32_16x16x32_bf16 v[92:95], v[168:171], v[204:207], v[92:95]
	v_mfma_f32_16x16x32_bf16 v[92:95], v[172:175], v[230:233], v[92:95]
	v_mfma_f32_16x16x32_bf16 v[76:79], v[168:171], v[234:237], v[76:79]
	v_mfma_f32_16x16x32_bf16 v[76:79], v[172:175], v[238:241], v[76:79]
	v_mfma_f32_16x16x32_bf16 v[72:75], v[176:179], v[234:237], v[72:75]
	v_mfma_f32_16x16x32_bf16 v[72:75], v[184:187], v[238:241], v[72:75]
	v_mfma_f32_16x16x32_bf16 v[88:91], v[176:179], v[204:207], v[88:91]
	v_mfma_f32_16x16x32_bf16 v[88:91], v[184:187], v[230:233], v[88:91]
	v_mfma_f32_16x16x32_bf16 v[104:107], v[176:179], v[196:199], v[104:107]
	v_mfma_f32_16x16x32_bf16 v[104:107], v[184:187], v[200:203], v[104:107]
	v_mfma_f32_16x16x32_bf16 v[120:123], v[176:179], v[188:191], v[120:123]
	v_mfma_f32_16x16x32_bf16 v[120:123], v[184:187], v[192:195], v[120:123]
	s_setprio 0
	s_barrier
	s_add_i32 s82, s19, s20
	v_lshl_add_u64 v[2:3], s[80:81], 0, v[140:141]
	s_mov_b32 m0, s82
	ds_read_b128 v[188:191], v151 offset:16384
	ds_read_b128 v[192:195], v151 offset:17408
	ds_read_b128 v[196:199], v151 offset:18432
	ds_read_b128 v[200:203], v151 offset:19456
	ds_read_b128 v[204:207], v151 offset:20480
	ds_read_b128 v[230:233], v151 offset:21504
	ds_read_b128 v[234:237], v151 offset:22528
	ds_read_b128 v[238:241], v151 offset:23552
	global_load_lds_dwordx4 v[2:3], off
	s_add_i32 m0, s82, 0x2000
	v_lshl_add_u64 v[180:181], s[80:81], 0, v[136:137]
	s_add_u32 s80, s80, s48
	s_addc_u32 s81, s81, s49
	s_add_i32 s79, s79, s20
	global_load_lds_dwordx4 v[180:181], off
	v_lshl_add_u64 v[208:209], s[80:81], 0, v[140:141]
	s_mov_b32 m0, s79
	v_lshl_add_u64 v[216:217], s[80:81], 0, v[136:137]
	global_load_lds_dwordx4 v[208:209], off
	s_add_i32 m0, s79, 0x2000
	v_lshl_add_u64 v[224:225], s[38:39], 0, v[142:143]
	global_load_lds_dwordx4 v[216:217], off
	s_mov_b32 m0, s42
	v_lshl_add_u64 v[226:227], s[38:39], 0, v[138:139]
	global_load_lds_dwordx4 v[224:225], off
	s_mov_b32 m0, s45
	s_nop 0
	global_load_lds_dwordx4 v[226:227], off
	s_waitcnt vmcnt(8)
	s_waitcnt lgkmcnt(0)
	s_barrier
; #define PG8_STAGE(bufoff, gbase, voff) do { _Pragma("unroll") for (int _i = 0; _i < 2; ++_i) \
;         __builtin_amdgcn_global_load_lds((const unsigned*)((const char*)(gbase) + (voff)[_i]), (PG8_LAS unsigned*)(lds + (bufoff) + ldsw + _i * 8192), 16, 0, 0); } while (0)
; #define PG8_LDA(dst, b, h) do { _Pragma("unroll") for (int m = 0; m < 4; ++m) _Pragma("unroll") for (int k = 0; k < 2; ++k) dst[m][k] = *(const PG8_LAS bf16x8*)(lds + PG8_SA(b, h) + aoff + m * 2048 + k * 1024); } while (0)
; #define PG8_LDB(dst, b, h) do { _Pragma("unroll") for (int n = 0; n < 2; ++n) _Pragma("unroll") for (int k = 0; k < 2; ++k) dst[n][k] = *(const PG8_LAS bf16x8*)(lds + PG8_SB(b, h) + boff + n * 2048 + k * 1024); } while (0)
; #define PG8_MMA(ai, bj, At, Bt) do { __builtin_amdgcn_s_setprio(1); _Pragma("unroll") for (int m = 0; m < 4; ++m) _Pragma("unroll") for (int n = 0; n < 2; ++n) _Pragma("unroll") for (int k = 0; k < 2; ++k) \
;         acc[ai][bj][m][n] = __builtin_amdgcn_mfma_f32_16x16x32_bf16(Bt[n][k], At[m][k], acc[ai][bj][m][n], 0, 0, 0); __builtin_amdgcn_s_setprio(0); } while (0)
; #define PG8_WAIT_V(n) asm volatile("s_waitcnt vmcnt(" #n ")" ::: "memory")
; #define PG8_WAIT_L(n) asm volatile("s_waitcnt lgkmcnt(" #n ")" ::: "memory")
; #define PG8_BAR __builtin_amdgcn_s_barrier()
; #define PG8_SCHED __builtin_amdgcn_sched_barrier(0)
; template <class Epi, class Sched, bool ALIGN_EPI = false, bool SP2 = false>
; __device__ __forceinline__ void gemm_phase(PG8_LAS unsigned char* lds, const Gemm g, const Sched& S, const Epi& E) {
;     ...
;             PG8_WAIT_V(8); PG8_WAIT_L(0); PG8_BAR; PG8_MMA(1, 0, At, B0); PG8_MMA(1, 1, At, B1); PG8_BAR; PG8_SCHED;
;             PG8_LDB(B0, 1, 0); PG8_LDB(B1, 1, 1); PG8_SCHED; PG8_LDA(At, 1, 0); PG8_STAGE(PG8_SA(0, 1), a2 + hstep, voffA);
;             PG8_WAIT_V(8); PG8_WAIT_L(0); PG8_BAR; PG8_MMA(0, 0, At, B0); PG8_MMA(0, 1, At, B1); PG8_BAR; PG8_SCHED;
	s_setprio 1
	s_waitcnt lgkmcnt(0)
	v_mfma_f32_16x16x32_bf16 v[68:71], v[152:155], v[188:191], v[68:71]
	v_mfma_f32_16x16x32_bf16 v[68:71], v[156:159], v[192:195], v[68:71]
	v_mfma_f32_16x16x32_bf16 v[52:55], v[152:155], v[196:199], v[52:55]
	v_mfma_f32_16x16x32_bf16 v[52:55], v[156:159], v[200:203], v[52:55]
	v_mfma_f32_16x16x32_bf16 v[36:39], v[152:155], v[204:207], v[36:39]
	v_mfma_f32_16x16x32_bf16 v[36:39], v[156:159], v[230:233], v[36:39]
	v_mfma_f32_16x16x32_bf16 v[20:23], v[152:155], v[234:237], v[20:23]
	v_mfma_f32_16x16x32_bf16 v[20:23], v[156:159], v[238:241], v[20:23]
	v_mfma_f32_16x16x32_bf16 v[16:19], v[160:163], v[234:237], v[16:19]
	v_mfma_f32_16x16x32_bf16 v[16:19], v[164:167], v[238:241], v[16:19]
	v_mfma_f32_16x16x32_bf16 v[32:35], v[160:163], v[204:207], v[32:35]
	v_mfma_f32_16x16x32_bf16 v[32:35], v[164:167], v[230:233], v[32:35]
	v_mfma_f32_16x16x32_bf16 v[48:51], v[160:163], v[196:199], v[48:51]
	v_mfma_f32_16x16x32_bf16 v[48:51], v[164:167], v[200:203], v[48:51]
	v_mfma_f32_16x16x32_bf16 v[64:67], v[160:163], v[188:191], v[64:67]
	v_mfma_f32_16x16x32_bf16 v[64:67], v[164:167], v[192:195], v[64:67]
	v_mfma_f32_16x16x32_bf16 v[60:63], v[168:171], v[188:191], v[60:63]
	v_mfma_f32_16x16x32_bf16 v[60:63], v[172:175], v[192:195], v[60:63]
	v_mfma_f32_16x16x32_bf16 v[44:47], v[168:171], v[196:199], v[44:47]
	v_mfma_f32_16x16x32_bf16 v[44:47], v[172:175], v[200:203], v[44:47]
	v_mfma_f32_16x16x32_bf16 v[28:31], v[168:171], v[204:207], v[28:31]
	v_mfma_f32_16x16x32_bf16 v[28:31], v[172:175], v[230:233], v[28:31]
	v_mfma_f32_16x16x32_bf16 v[12:15], v[168:171], v[234:237], v[12:15]
	v_mfma_f32_16x16x32_bf16 v[12:15], v[172:175], v[238:241], v[12:15]
	v_mfma_f32_16x16x32_bf16 v[8:11], v[176:179], v[234:237], v[8:11]
	v_mfma_f32_16x16x32_bf16 v[8:11], v[184:187], v[238:241], v[8:11]
	v_mfma_f32_16x16x32_bf16 v[24:27], v[176:179], v[204:207], v[24:27]
	v_mfma_f32_16x16x32_bf16 v[24:27], v[184:187], v[230:233], v[24:27]
	v_mfma_f32_16x16x32_bf16 v[40:43], v[176:179], v[196:199], v[40:43]
	v_mfma_f32_16x16x32_bf16 v[40:43], v[184:187], v[200:203], v[40:43]
	v_mfma_f32_16x16x32_bf16 v[56:59], v[176:179], v[188:191], v[56:59]
	v_mfma_f32_16x16x32_bf16 v[56:59], v[184:187], v[192:195], v[56:59]
	s_setprio 0
	s_barrier
	v_add_u32_e32 v0, s91, v150
	s_add_i32 s79, 0, 0x1c000
	ds_read_b128 v[152:155], v0
	ds_read_b128 v[156:159], v0 offset:1024
	ds_read_b128 v[160:163], v0 offset:2048
	ds_read_b128 v[164:167], v0 offset:3072
	v_add_u32_e32 v0, s79, v150
	ds_read_b128 v[168:171], v0
	ds_read_b128 v[172:175], v0 offset:1024
	ds_read_b128 v[176:179], v0 offset:2048
	ds_read_b128 v[184:187], v0 offset:3072
	s_add_u32 s38, s38, s48
	s_addc_u32 s39, s39, s49
	s_mov_b32 m0, s46
	v_lshl_add_u64 v[228:229], s[38:39], 0, v[142:143]
	ds_read_b128 v[188:191], v151 offset:32768
	ds_read_b128 v[192:195], v151 offset:33792
	ds_read_b128 v[196:199], v151 offset:34816
	ds_read_b128 v[200:203], v151 offset:35840
	ds_read_b128 v[204:207], v151 offset:36864
	ds_read_b128 v[230:233], v151 offset:37888
	ds_read_b128 v[234:237], v151 offset:38912
	ds_read_b128 v[238:241], v151 offset:39936
	global_load_lds_dwordx4 v[228:229], off
	v_lshl_add_u64 v[228:229], s[38:39], 0, v[138:139]
	s_mov_b32 m0, s47
	s_nop 0
	global_load_lds_dwordx4 v[228:229], off
	s_waitcnt vmcnt(8)
	s_waitcnt lgkmcnt(0)
	s_barrier
	s_setprio 1
	s_waitcnt lgkmcnt(0)
	v_mfma_f32_16x16x32_bf16 v[132:135], v[152:155], v[188:191], v[132:135]
	v_mfma_f32_16x16x32_bf16 v[132:135], v[156:159], v[192:195], v[132:135]
	v_mfma_f32_16x16x32_bf16 v[116:119], v[152:155], v[196:199], v[116:119]
	v_mfma_f32_16x16x32_bf16 v[116:119], v[156:159], v[200:203], v[116:119]
	v_mfma_f32_16x16x32_bf16 v[100:103], v[152:155], v[204:207], v[100:103]
	v_mfma_f32_16x16x32_bf16 v[100:103], v[156:159], v[230:233], v[100:103]
	v_mfma_f32_16x16x32_bf16 v[84:87], v[152:155], v[234:237], v[84:87]
	v_mfma_f32_16x16x32_bf16 v[84:87], v[156:159], v[238:241], v[84:87]
	v_mfma_f32_16x16x32_bf16 v[80:83], v[160:163], v[234:237], v[80:83]
	v_mfma_f32_16x16x32_bf16 v[80:83], v[164:167], v[238:241], v[80:83]
	v_mfma_f32_16x16x32_bf16 v[96:99], v[160:163], v[204:207], v[96:99]
	v_mfma_f32_16x16x32_bf16 v[96:99], v[164:167], v[230:233], v[96:99]
	v_mfma_f32_16x16x32_bf16 v[112:115], v[160:163], v[196:199], v[112:115]
	v_mfma_f32_16x16x32_bf16 v[112:115], v[164:167], v[200:203], v[112:115]
	v_mfma_f32_16x16x32_bf16 v[128:131], v[160:163], v[188:191], v[128:131]
	v_mfma_f32_16x16x32_bf16 v[128:131], v[164:167], v[192:195], v[128:131]
	v_mfma_f32_16x16x32_bf16 v[124:127], v[168:171], v[188:191], v[124:127]
	v_mfma_f32_16x16x32_bf16 v[124:127], v[172:175], v[192:195], v[124:127]
	v_mfma_f32_16x16x32_bf16 v[108:111], v[168:171], v[196:199], v[108:111]
	v_mfma_f32_16x16x32_bf16 v[108:111], v[172:175], v[200:203], v[108:111]
	v_mfma_f32_16x16x32_bf16 v[92:95], v[168:171], v[204:207], v[92:95]
	v_mfma_f32_16x16x32_bf16 v[92:95], v[172:175], v[230:233], v[92:95]
	v_mfma_f32_16x16x32_bf16 v[76:79], v[168:171], v[234:237], v[76:79]
	v_mfma_f32_16x16x32_bf16 v[76:79], v[172:175], v[238:241], v[76:79]
	v_mfma_f32_16x16x32_bf16 v[72:75], v[176:179], v[234:237], v[72:75]
	v_mfma_f32_16x16x32_bf16 v[72:75], v[184:187], v[238:241], v[72:75]
	v_mfma_f32_16x16x32_bf16 v[88:91], v[176:179], v[204:207], v[88:91]
	v_mfma_f32_16x16x32_bf16 v[88:91], v[184:187], v[230:233], v[88:91]
	v_mfma_f32_16x16x32_bf16 v[104:107], v[176:179], v[196:199], v[104:107]
	v_mfma_f32_16x16x32_bf16 v[104:107], v[184:187], v[200:203], v[104:107]
	v_mfma_f32_16x16x32_bf16 v[120:123], v[176:179], v[188:191], v[120:123]
	v_mfma_f32_16x16x32_bf16 v[120:123], v[184:187], v[192:195], v[120:123]
	s_setprio 0
	s_barrier
; #define PG8_STAGE(bufoff, gbase, voff) do { _Pragma("unroll") for (int _i = 0; _i < 2; ++_i) \
;         __builtin_amdgcn_global_load_lds((const unsigned*)((const char*)(gbase) + (voff)[_i]), (PG8_LAS unsigned*)(lds + (bufoff) + ldsw + _i * 8192), 16, 0, 0); } while (0)
; #define PG8_LDA(dst, b, h) do { _Pragma("unroll") for (int m = 0; m < 4; ++m) _Pragma("unroll") for (int k = 0; k < 2; ++k) dst[m][k] = *(const PG8_LAS bf16x8*)(lds + PG8_SA(b, h) + aoff + m * 2048 + k * 1024); } while (0)
; #define PG8_MMA(ai, bj, At, Bt) do { __builtin_amdgcn_s_setprio(1); _Pragma("unroll") for (int m = 0; m < 4; ++m) _Pragma("unroll") for (int n = 0; n < 2; ++n) _Pragma("unroll") for (int k = 0; k < 2; ++k) \
;         acc[ai][bj][m][n] = __builtin_amdgcn_mfma_f32_16x16x32_bf16(Bt[n][k], At[m][k], acc[ai][bj][m][n], 0, 0, 0); __builtin_amdgcn_s_setprio(0); } while (0)
; #define PG8_WAIT_V(n) asm volatile("s_waitcnt vmcnt(" #n ")" ::: "memory")
; #define PG8_WAIT_L(n) asm volatile("s_waitcnt lgkmcnt(" #n ")" ::: "memory")
; #define PG8_BAR __builtin_amdgcn_s_barrier()
; #define PG8_SCHED __builtin_amdgcn_sched_barrier(0)
; template <class Epi, class Sched, bool ALIGN_EPI = false, bool SP2 = false>
; __device__ __forceinline__ void gemm_phase(PG8_LAS unsigned char* lds, const Gemm g, const Sched& S, const Epi& E) {
;     ...
;             PG8_LDA(At, 1, 1); PG8_STAGE(PG8_SB(1, 0), b3, voffB); PG8_STAGE(PG8_SB(1, 1), b3 + hstep, voffB); PG8_STAGE(PG8_SA(1, 0), a3, voffA);
;             PG8_WAIT_V(8); PG8_WAIT_L(0); PG8_BAR; PG8_MMA(1, 0, At, B0); PG8_MMA(1, 1, At, B1); PG8_BAR; PG8_SCHED;
	s_add_i32 s38, s91, s20
	v_lshl_add_u64 v[2:3], v[2:3], 0, s[24:25]
	s_mov_b32 m0, s38
	ds_read_b128 v[188:191], v151 offset:49152
	ds_read_b128 v[192:195], v151 offset:50176
	ds_read_b128 v[196:199], v151 offset:51200
	ds_read_b128 v[200:203], v151 offset:52224
	ds_read_b128 v[204:207], v151 offset:53248
	ds_read_b128 v[230:233], v151 offset:54272
	ds_read_b128 v[234:237], v151 offset:55296
	ds_read_b128 v[238:241], v151 offset:56320
	global_load_lds_dwordx4 v[2:3], off
	v_lshl_add_u64 v[2:3], v[180:181], 0, s[24:25]
	s_add_i32 m0, s38, 0x2000
	s_add_i32 s38, s79, s20
	global_load_lds_dwordx4 v[2:3], off
	v_lshl_add_u64 v[2:3], v[208:209], 0, s[24:25]
	s_mov_b32 m0, s38
	s_nop 0
	global_load_lds_dwordx4 v[2:3], off
	v_lshl_add_u64 v[2:3], v[216:217], 0, s[24:25]
	s_add_i32 m0, s38, 0x2000
	s_nop 0
	global_load_lds_dwordx4 v[2:3], off
	v_lshl_add_u64 v[2:3], v[224:225], 0, s[24:25]
	s_mov_b32 m0, s52
	s_nop 0
	global_load_lds_dwordx4 v[2:3], off
	v_lshl_add_u64 v[2:3], v[226:227], 0, s[24:25]
	s_mov_b32 m0, s53
	s_nop 0
	global_load_lds_dwordx4 v[2:3], off
	s_waitcnt vmcnt(8)
	s_waitcnt lgkmcnt(0)
	s_barrier
	s_setprio 1
	s_waitcnt lgkmcnt(0)
	v_mfma_f32_16x16x32_bf16 v[68:71], v[152:155], v[188:191], v[68:71]
	v_mfma_f32_16x16x32_bf16 v[68:71], v[156:159], v[192:195], v[68:71]
	v_mfma_f32_16x16x32_bf16 v[52:55], v[152:155], v[196:199], v[52:55]
	v_mfma_f32_16x16x32_bf16 v[52:55], v[156:159], v[200:203], v[52:55]
	v_mfma_f32_16x16x32_bf16 v[36:39], v[152:155], v[204:207], v[36:39]
	v_mfma_f32_16x16x32_bf16 v[36:39], v[156:159], v[230:233], v[36:39]
	v_mfma_f32_16x16x32_bf16 v[20:23], v[152:155], v[234:237], v[20:23]
	v_mfma_f32_16x16x32_bf16 v[20:23], v[156:159], v[238:241], v[20:23]
	v_mfma_f32_16x16x32_bf16 v[16:19], v[160:163], v[234:237], v[16:19]
	v_mfma_f32_16x16x32_bf16 v[16:19], v[164:167], v[238:241], v[16:19]
	v_mfma_f32_16x16x32_bf16 v[32:35], v[160:163], v[204:207], v[32:35]
	v_mfma_f32_16x16x32_bf16 v[32:35], v[164:167], v[230:233], v[32:35]
	v_mfma_f32_16x16x32_bf16 v[48:51], v[160:163], v[196:199], v[48:51]
	v_mfma_f32_16x16x32_bf16 v[48:51], v[164:167], v[200:203], v[48:51]
	v_mfma_f32_16x16x32_bf16 v[64:67], v[160:163], v[188:191], v[64:67]
	v_mfma_f32_16x16x32_bf16 v[64:67], v[164:167], v[192:195], v[64:67]
	v_mfma_f32_16x16x32_bf16 v[60:63], v[168:171], v[188:191], v[60:63]
	v_mfma_f32_16x16x32_bf16 v[60:63], v[172:175], v[192:195], v[60:63]
	v_mfma_f32_16x16x32_bf16 v[44:47], v[168:171], v[196:199], v[44:47]
	v_mfma_f32_16x16x32_bf16 v[44:47], v[172:175], v[200:203], v[44:47]
	v_mfma_f32_16x16x32_bf16 v[28:31], v[168:171], v[204:207], v[28:31]
	v_mfma_f32_16x16x32_bf16 v[28:31], v[172:175], v[230:233], v[28:31]
	v_mfma_f32_16x16x32_bf16 v[12:15], v[168:171], v[234:237], v[12:15]
	v_mfma_f32_16x16x32_bf16 v[12:15], v[172:175], v[238:241], v[12:15]
	v_mfma_f32_16x16x32_bf16 v[8:11], v[176:179], v[234:237], v[8:11]
	v_mfma_f32_16x16x32_bf16 v[8:11], v[184:187], v[238:241], v[8:11]
	v_mfma_f32_16x16x32_bf16 v[24:27], v[176:179], v[204:207], v[24:27]
	v_mfma_f32_16x16x32_bf16 v[24:27], v[184:187], v[230:233], v[24:27]
	v_mfma_f32_16x16x32_bf16 v[40:43], v[176:179], v[196:199], v[40:43]
	v_mfma_f32_16x16x32_bf16 v[40:43], v[184:187], v[200:203], v[40:43]
	v_mfma_f32_16x16x32_bf16 v[56:59], v[176:179], v[188:191], v[56:59]
	v_mfma_f32_16x16x32_bf16 v[56:59], v[184:187], v[192:195], v[56:59]
	s_setprio 0
	s_barrier
	s_add_u32 s22, s22, 0x100
	s_addc_u32 s23, s23, 0
	s_add_u32 s76, s76, 0x100
	s_addc_u32 s77, s77, 0
	s_cmp_ge_u32 s78, s9
	s_mov_b32 s38, s78
	s_cbranch_scc0 .LBB0_202

; #define PG8_STAGE(bufoff, gbase, voff) do { _Pragma("unroll") for (int _i = 0; _i < 2; ++_i) \
;         __builtin_amdgcn_global_load_lds((const unsigned*)((const char*)(gbase) + (voff)[_i]), (PG8_LAS unsigned*)(lds + (bufoff) + ldsw + _i * 8192), 16, 0, 0); } while (0)
; #define PG8_LDA(dst, b, h) do { _Pragma("unroll") for (int m = 0; m < 4; ++m) _Pragma("unroll") for (int k = 0; k < 2; ++k) dst[m][k] = *(const PG8_LAS bf16x8*)(lds + PG8_SA(b, h) + aoff + m * 2048 + k * 1024); } while (0)
; #define PG8_LDB(dst, b, h) do { _Pragma("unroll") for (int n = 0; n < 2; ++n) _Pragma("unroll") for (int k = 0; k < 2; ++k) dst[n][k] = *(const PG8_LAS bf16x8*)(lds + PG8_SB(b, h) + boff + n * 2048 + k * 1024); } while (0)
; #define PG8_MMA(ai, bj, At, Bt) do { __builtin_amdgcn_s_setprio(1); _Pragma("unroll") for (int m = 0; m < 4; ++m) _Pragma("unroll") for (int n = 0; n < 2; ++n) _Pragma("unroll") for (int k = 0; k < 2; ++k) \
;         acc[ai][bj][m][n] = __builtin_amdgcn_mfma_f32_16x16x32_bf16(Bt[n][k], At[m][k], acc[ai][bj][m][n], 0, 0, 0); __builtin_amdgcn_s_setprio(0); } while (0)
; #define PG8_WAIT_V(n) asm volatile("s_waitcnt vmcnt(" #n ")" ::: "memory")
; #define PG8_WAIT_L(n) asm volatile("s_waitcnt lgkmcnt(" #n ")" ::: "memory")
; template <class Epi, class Sched, bool ALIGN_EPI = false, bool SP2 = false>
; __device__ __forceinline__ void gemm_phase(PG8_LAS unsigned char* lds, const Gemm g, const Sched& S, const Epi& E) {
;     ...
;             const bool last = (t == nt - 2);
;             const char* a1 = cA + (size_t)(t + 1) * kstep;
;             const char* a2 = last ? nA : cA + (size_t)(t + 2) * kstep; const char* b2 = last ? nB : cB + (size_t)(t + 2) * kstep;
;             const char* a3 = a2 + kstep; const char* b3 = b2 + kstep;
;             if (last && has_next) S.a_ready(nxt);
;             if constexpr (SP2) {
;             PG8_LDB(B0, 0, 0); PG8_LDB(B1, 0, 1); PG8_SCHED; PG8_LDA(At, 0, 0); PG8_STAGE(PG8_SA(1, 1), a1 + hstep, voffA);
;             PG8_WAIT_V(8); PG8_WAIT_L(0); PG8_BAR; PG8_MMA(0, 0, At, B0); PG8_MMA(0, 1, At, B1); PG8_BAR; PG8_SCHED;
;             PG8_LDA(At, 0, 1); PG8_STAGE(PG8_SB(0, 0), b2, voffB); PG8_STAGE(PG8_SB(0, 1), b2 + hstep, voffB); PG8_STAGE(PG8_SA(0, 0), a2, voffA);
;             PG8_WAIT_V(8); PG8_WAIT_L(0); PG8_BAR; PG8_MMA(1, 0, At, B0); PG8_MMA(1, 1, At, B1); PG8_BAR; PG8_SCHED;
.LBB0_245:
	v_readlane_b32 s22, v252, 59
	v_readlane_b32 s23, v252, 60
	s_andn2_b64 vcc, exec, s[22:23]
	s_cbranch_vccnz .LBB0_252
	s_add_u32 s40, s6, s48
	s_addc_u32 s41, s7, s49
	s_add_u32 s37, s6, 0x100
	s_addc_u32 s80, s7, 0
	s_and_b64 s[22:23], s[12:13], exec
	s_cselect_b32 s23, s5, s80
	s_cselect_b32 s22, s4, s37
	s_add_u32 s37, s10, 0x100
	s_addc_u32 s82, s11, 0
	s_and_b64 s[80:81], s[12:13], exec
	s_cselect_b32 s85, s17, s82
	s_cselect_b32 s84, s16, s37
	s_add_i32 s83, 0, 0x14000
	v_add_u32_e32 v150, s19, v147
	v_add_u32_e32 v151, s83, v147
	ds_read_b128 v[152:155], v150
	ds_read_b128 v[156:159], v150 offset:1024
	ds_read_b128 v[160:163], v150 offset:2048
	ds_read_b128 v[164:167], v150 offset:3072
	ds_read_b128 v[168:171], v151
	ds_read_b128 v[172:175], v151 offset:1024
	ds_read_b128 v[176:179], v151 offset:2048
	ds_read_b128 v[184:187], v151 offset:3072
	v_lshl_add_u64 v[180:181], s[40:41], 0, v[2:3]
	s_add_i32 s37, s47, 0xc000
	v_lshl_add_u64 v[180:181], v[180:181], 0, s[24:25]
	s_mov_b32 m0, s37
	ds_read_b128 v[188:191], v149
	ds_read_b128 v[192:195], v149 offset:1024
	ds_read_b128 v[196:199], v149 offset:2048
	ds_read_b128 v[200:203], v149 offset:3072
	ds_read_b128 v[204:207], v149 offset:4096
	ds_read_b128 v[230:233], v149 offset:5120
	ds_read_b128 v[234:237], v149 offset:6144
	ds_read_b128 v[238:241], v149 offset:7168
	global_load_lds_dwordx4 v[180:181], off
	v_lshl_add_u64 v[180:181], s[40:41], 0, v[136:137]
	s_add_i32 s80, s47, 0xe000
	v_lshl_add_u64 v[180:181], v[180:181], 0, s[24:25]
	s_mov_b32 m0, s80
	s_nop 0
	global_load_lds_dwordx4 v[180:181], off
	s_waitcnt vmcnt(8)
	s_waitcnt lgkmcnt(0)
	s_barrier
	s_setprio 1
	s_waitcnt lgkmcnt(0)
	v_mfma_f32_16x16x32_bf16 v[132:135], v[152:155], v[188:191], v[132:135]
	v_mfma_f32_16x16x32_bf16 v[132:135], v[156:159], v[192:195], v[132:135]
	v_mfma_f32_16x16x32_bf16 v[116:119], v[152:155], v[196:199], v[116:119]
	v_mfma_f32_16x16x32_bf16 v[116:119], v[156:159], v[200:203], v[116:119]
	v_mfma_f32_16x16x32_bf16 v[100:103], v[152:155], v[204:207], v[100:103]
	v_mfma_f32_16x16x32_bf16 v[100:103], v[156:159], v[230:233], v[100:103]
	v_mfma_f32_16x16x32_bf16 v[84:87], v[152:155], v[234:237], v[84:87]
	v_mfma_f32_16x16x32_bf16 v[84:87], v[156:159], v[238:241], v[84:87]
	v_mfma_f32_16x16x32_bf16 v[80:83], v[160:163], v[234:237], v[80:83]
	v_mfma_f32_16x16x32_bf16 v[80:83], v[164:167], v[238:241], v[80:83]
	v_mfma_f32_16x16x32_bf16 v[96:99], v[160:163], v[204:207], v[96:99]
	v_mfma_f32_16x16x32_bf16 v[96:99], v[164:167], v[230:233], v[96:99]
	v_mfma_f32_16x16x32_bf16 v[112:115], v[160:163], v[196:199], v[112:115]
	v_mfma_f32_16x16x32_bf16 v[112:115], v[164:167], v[200:203], v[112:115]
	v_mfma_f32_16x16x32_bf16 v[128:131], v[160:163], v[188:191], v[128:131]
	v_mfma_f32_16x16x32_bf16 v[128:131], v[164:167], v[192:195], v[128:131]
	v_mfma_f32_16x16x32_bf16 v[124:127], v[168:171], v[188:191], v[124:127]
	v_mfma_f32_16x16x32_bf16 v[124:127], v[172:175], v[192:195], v[124:127]
	v_mfma_f32_16x16x32_bf16 v[108:111], v[168:171], v[196:199], v[108:111]
	v_mfma_f32_16x16x32_bf16 v[108:111], v[172:175], v[200:203], v[108:111]
	v_mfma_f32_16x16x32_bf16 v[92:95], v[168:171], v[204:207], v[92:95]
	v_mfma_f32_16x16x32_bf16 v[92:95], v[172:175], v[230:233], v[92:95]
	v_mfma_f32_16x16x32_bf16 v[76:79], v[168:171], v[234:237], v[76:79]
	v_mfma_f32_16x16x32_bf16 v[76:79], v[172:175], v[238:241], v[76:79]
	v_mfma_f32_16x16x32_bf16 v[72:75], v[176:179], v[234:237], v[72:75]
	v_mfma_f32_16x16x32_bf16 v[72:75], v[184:187], v[238:241], v[72:75]
	v_mfma_f32_16x16x32_bf16 v[88:91], v[176:179], v[204:207], v[88:91]
	v_mfma_f32_16x16x32_bf16 v[88:91], v[184:187], v[230:233], v[88:91]
	v_mfma_f32_16x16x32_bf16 v[104:107], v[176:179], v[196:199], v[104:107]
	v_mfma_f32_16x16x32_bf16 v[104:107], v[184:187], v[200:203], v[104:107]
	v_mfma_f32_16x16x32_bf16 v[120:123], v[176:179], v[188:191], v[120:123]
	v_mfma_f32_16x16x32_bf16 v[120:123], v[184:187], v[192:195], v[120:123]
	s_setprio 0
	s_barrier
	s_add_i32 s81, s19, s46
	s_add_i32 s82, s81, 0x2000
	v_lshl_add_u64 v[208:209], s[84:85], 0, v[0:1]
	s_mov_b32 m0, s81
	s_add_u32 s40, s84, s48
	ds_read_b128 v[188:191], v149 offset:16384
	ds_read_b128 v[192:195], v149 offset:17408
	ds_read_b128 v[196:199], v149 offset:18432
	ds_read_b128 v[200:203], v149 offset:19456
	ds_read_b128 v[204:207], v149 offset:20480
	ds_read_b128 v[230:233], v149 offset:21504
	ds_read_b128 v[234:237], v149 offset:22528
	ds_read_b128 v[238:241], v149 offset:23552
	global_load_lds_dwordx4 v[208:209], off
	v_lshl_add_u64 v[216:217], s[84:85], 0, v[138:139]
	s_mov_b32 m0, s82
	s_addc_u32 s41, s85, s49
	s_add_i32 s83, s83, s46
	global_load_lds_dwordx4 v[216:217], off
	v_lshl_add_u64 v[224:225], s[40:41], 0, v[0:1]
	s_mov_b32 m0, s83
	s_add_i32 s84, s83, 0x2000
	global_load_lds_dwordx4 v[224:225], off
	v_lshl_add_u64 v[226:227], s[40:41], 0, v[138:139]
	s_mov_b32 m0, s84
	v_lshl_add_u64 v[228:229], s[22:23], 0, v[2:3]
	global_load_lds_dwordx4 v[226:227], off
	s_mov_b32 m0, s47
	v_lshl_add_u64 v[242:243], s[22:23], 0, v[136:137]
	global_load_lds_dwordx4 v[228:229], off
	s_mov_b32 m0, s52
	s_nop 0
	global_load_lds_dwordx4 v[242:243], off
	s_waitcnt vmcnt(8)
	s_waitcnt lgkmcnt(0)
	s_barrier
; #define PG8_STAGE(bufoff, gbase, voff) do { _Pragma("unroll") for (int _i = 0; _i < 2; ++_i) \
;         __builtin_amdgcn_global_load_lds((const unsigned*)((const char*)(gbase) + (voff)[_i]), (PG8_LAS unsigned*)(lds + (bufoff) + ldsw + _i * 8192), 16, 0, 0); } while (0)
; #define PG8_LDA(dst, b, h) do { _Pragma("unroll") for (int m = 0; m < 4; ++m) _Pragma("unroll") for (int k = 0; k < 2; ++k) dst[m][k] = *(const PG8_LAS bf16x8*)(lds + PG8_SA(b, h) + aoff + m * 2048 + k * 1024); } while (0)
; #define PG8_LDB(dst, b, h) do { _Pragma("unroll") for (int n = 0; n < 2; ++n) _Pragma("unroll") for (int k = 0; k < 2; ++k) dst[n][k] = *(const PG8_LAS bf16x8*)(lds + PG8_SB(b, h) + boff + n * 2048 + k * 1024); } while (0)
; #define PG8_MMA(ai, bj, At, Bt) do { __builtin_amdgcn_s_setprio(1); _Pragma("unroll") for (int m = 0; m < 4; ++m) _Pragma("unroll") for (int n = 0; n < 2; ++n) _Pragma("unroll") for (int k = 0; k < 2; ++k) \
;         acc[ai][bj][m][n] = __builtin_amdgcn_mfma_f32_16x16x32_bf16(Bt[n][k], At[m][k], acc[ai][bj][m][n], 0, 0, 0); __builtin_amdgcn_s_setprio(0); } while (0)
; #define PG8_WAIT_V(n) asm volatile("s_waitcnt vmcnt(" #n ")" ::: "memory")
; #define PG8_WAIT_L(n) asm volatile("s_waitcnt lgkmcnt(" #n ")" ::: "memory")
; #define PG8_BAR __builtin_amdgcn_s_barrier()
; #define PG8_SCHED __builtin_amdgcn_sched_barrier(0)
; template <class Epi, class Sched, bool ALIGN_EPI = false, bool SP2 = false>
; __device__ __forceinline__ void gemm_phase(PG8_LAS unsigned char* lds, const Gemm g, const Sched& S, const Epi& E) {
;     ...
;             PG8_WAIT_V(8); PG8_WAIT_L(0); PG8_BAR; PG8_MMA(1, 0, At, B0); PG8_MMA(1, 1, At, B1); PG8_BAR; PG8_SCHED;
;             PG8_LDB(B0, 1, 0); PG8_LDB(B1, 1, 1); PG8_SCHED; PG8_LDA(At, 1, 0); PG8_STAGE(PG8_SA(0, 1), a2 + hstep, voffA);
;             PG8_WAIT_V(8); PG8_WAIT_L(0); PG8_BAR; PG8_MMA(0, 0, At, B0); PG8_MMA(0, 1, At, B1); PG8_BAR; PG8_SCHED;
	s_setprio 1
	s_waitcnt lgkmcnt(0)
	v_mfma_f32_16x16x32_bf16 v[68:71], v[152:155], v[188:191], v[68:71]
	v_mfma_f32_16x16x32_bf16 v[68:71], v[156:159], v[192:195], v[68:71]
	v_mfma_f32_16x16x32_bf16 v[52:55], v[152:155], v[196:199], v[52:55]
	v_mfma_f32_16x16x32_bf16 v[52:55], v[156:159], v[200:203], v[52:55]
	v_mfma_f32_16x16x32_bf16 v[36:39], v[152:155], v[204:207], v[36:39]
	v_mfma_f32_16x16x32_bf16 v[36:39], v[156:159], v[230:233], v[36:39]
	v_mfma_f32_16x16x32_bf16 v[20:23], v[152:155], v[234:237], v[20:23]
	v_mfma_f32_16x16x32_bf16 v[20:23], v[156:159], v[238:241], v[20:23]
	v_mfma_f32_16x16x32_bf16 v[16:19], v[160:163], v[234:237], v[16:19]
	v_mfma_f32_16x16x32_bf16 v[16:19], v[164:167], v[238:241], v[16:19]
	v_mfma_f32_16x16x32_bf16 v[32:35], v[160:163], v[204:207], v[32:35]
	v_mfma_f32_16x16x32_bf16 v[32:35], v[164:167], v[230:233], v[32:35]
	v_mfma_f32_16x16x32_bf16 v[48:51], v[160:163], v[196:199], v[48:51]
	v_mfma_f32_16x16x32_bf16 v[48:51], v[164:167], v[200:203], v[48:51]
	v_mfma_f32_16x16x32_bf16 v[64:67], v[160:163], v[188:191], v[64:67]
	v_mfma_f32_16x16x32_bf16 v[64:67], v[164:167], v[192:195], v[64:67]
	v_mfma_f32_16x16x32_bf16 v[60:63], v[168:171], v[188:191], v[60:63]
	v_mfma_f32_16x16x32_bf16 v[60:63], v[172:175], v[192:195], v[60:63]
	v_mfma_f32_16x16x32_bf16 v[44:47], v[168:171], v[196:199], v[44:47]
	v_mfma_f32_16x16x32_bf16 v[44:47], v[172:175], v[200:203], v[44:47]
	v_mfma_f32_16x16x32_bf16 v[28:31], v[168:171], v[204:207], v[28:31]
	v_mfma_f32_16x16x32_bf16 v[28:31], v[172:175], v[230:233], v[28:31]
	v_mfma_f32_16x16x32_bf16 v[12:15], v[168:171], v[234:237], v[12:15]
	v_mfma_f32_16x16x32_bf16 v[12:15], v[172:175], v[238:241], v[12:15]
	v_mfma_f32_16x16x32_bf16 v[8:11], v[176:179], v[234:237], v[8:11]
	v_mfma_f32_16x16x32_bf16 v[8:11], v[184:187], v[238:241], v[8:11]
	v_mfma_f32_16x16x32_bf16 v[24:27], v[176:179], v[204:207], v[24:27]
	v_mfma_f32_16x16x32_bf16 v[24:27], v[184:187], v[230:233], v[24:27]
	v_mfma_f32_16x16x32_bf16 v[40:43], v[176:179], v[196:199], v[40:43]
	v_mfma_f32_16x16x32_bf16 v[40:43], v[184:187], v[200:203], v[40:43]
	v_mfma_f32_16x16x32_bf16 v[56:59], v[176:179], v[188:191], v[56:59]
	v_mfma_f32_16x16x32_bf16 v[56:59], v[184:187], v[192:195], v[56:59]
	s_setprio 0
	s_barrier
	s_add_i32 s87, 0, 0x1c000
	v_add_u32_e32 v152, s91, v147
	v_add_u32_e32 v153, s87, v147
	ds_read_b128 v[154:157], v152
	ds_read_b128 v[158:161], v152 offset:1024
	ds_read_b128 v[162:165], v152 offset:2048
	ds_read_b128 v[166:169], v152 offset:3072
	ds_read_b128 v[170:173], v153
	ds_read_b128 v[174:177], v153 offset:1024
	ds_read_b128 v[178:181], v153 offset:2048
	ds_read_b128 v[184:187], v153 offset:3072
	s_add_u32 s22, s22, s48
	s_addc_u32 s23, s23, s49
	s_mov_b32 m0, s53
	v_lshl_add_u64 v[244:245], s[22:23], 0, v[2:3]
	ds_read_b128 v[188:191], v149 offset:32768
	ds_read_b128 v[192:195], v149 offset:33792
	ds_read_b128 v[196:199], v149 offset:34816
	ds_read_b128 v[200:203], v149 offset:35840
	ds_read_b128 v[204:207], v149 offset:36864
	ds_read_b128 v[230:233], v149 offset:37888
	ds_read_b128 v[234:237], v149 offset:38912
	ds_read_b128 v[238:241], v149 offset:39936
	global_load_lds_dwordx4 v[244:245], off
	v_lshl_add_u64 v[244:245], s[22:23], 0, v[136:137]
	s_mov_b32 m0, s72
	s_nop 0
	global_load_lds_dwordx4 v[244:245], off
	s_waitcnt vmcnt(8)
	s_waitcnt lgkmcnt(0)
	s_barrier
	s_setprio 1
	s_waitcnt lgkmcnt(0)
	v_mfma_f32_16x16x32_bf16 v[132:135], v[154:157], v[188:191], v[132:135]
	v_mfma_f32_16x16x32_bf16 v[132:135], v[158:161], v[192:195], v[132:135]
	v_mfma_f32_16x16x32_bf16 v[116:119], v[154:157], v[196:199], v[116:119]
	v_mfma_f32_16x16x32_bf16 v[116:119], v[158:161], v[200:203], v[116:119]
	v_mfma_f32_16x16x32_bf16 v[100:103], v[154:157], v[204:207], v[100:103]
	v_mfma_f32_16x16x32_bf16 v[100:103], v[158:161], v[230:233], v[100:103]
	v_mfma_f32_16x16x32_bf16 v[84:87], v[154:157], v[234:237], v[84:87]
	v_mfma_f32_16x16x32_bf16 v[84:87], v[158:161], v[238:241], v[84:87]
	v_mfma_f32_16x16x32_bf16 v[80:83], v[162:165], v[234:237], v[80:83]
	v_mfma_f32_16x16x32_bf16 v[80:83], v[166:169], v[238:241], v[80:83]
	v_mfma_f32_16x16x32_bf16 v[96:99], v[162:165], v[204:207], v[96:99]
	v_mfma_f32_16x16x32_bf16 v[96:99], v[166:169], v[230:233], v[96:99]
	v_mfma_f32_16x16x32_bf16 v[112:115], v[162:165], v[196:199], v[112:115]
	v_mfma_f32_16x16x32_bf16 v[112:115], v[166:169], v[200:203], v[112:115]
	v_mfma_f32_16x16x32_bf16 v[128:131], v[162:165], v[188:191], v[128:131]
	v_mfma_f32_16x16x32_bf16 v[128:131], v[166:169], v[192:195], v[128:131]
	v_mfma_f32_16x16x32_bf16 v[124:127], v[170:173], v[188:191], v[124:127]
	v_mfma_f32_16x16x32_bf16 v[124:127], v[174:177], v[192:195], v[124:127]
	v_mfma_f32_16x16x32_bf16 v[108:111], v[170:173], v[196:199], v[108:111]
	v_mfma_f32_16x16x32_bf16 v[108:111], v[174:177], v[200:203], v[108:111]
	v_mfma_f32_16x16x32_bf16 v[92:95], v[170:173], v[204:207], v[92:95]
	v_mfma_f32_16x16x32_bf16 v[92:95], v[174:177], v[230:233], v[92:95]
	v_mfma_f32_16x16x32_bf16 v[76:79], v[170:173], v[234:237], v[76:79]
	v_mfma_f32_16x16x32_bf16 v[76:79], v[174:177], v[238:241], v[76:79]
	v_mfma_f32_16x16x32_bf16 v[72:75], v[178:181], v[234:237], v[72:75]
	v_mfma_f32_16x16x32_bf16 v[72:75], v[184:187], v[238:241], v[72:75]
	v_mfma_f32_16x16x32_bf16 v[88:91], v[178:181], v[204:207], v[88:91]
	v_mfma_f32_16x16x32_bf16 v[88:91], v[184:187], v[230:233], v[88:91]
	v_mfma_f32_16x16x32_bf16 v[104:107], v[178:181], v[196:199], v[104:107]
	v_mfma_f32_16x16x32_bf16 v[104:107], v[184:187], v[200:203], v[104:107]
	v_mfma_f32_16x16x32_bf16 v[120:123], v[178:181], v[188:191], v[120:123]
	v_mfma_f32_16x16x32_bf16 v[120:123], v[184:187], v[192:195], v[120:123]
	s_setprio 0
	s_barrier
; #define PG8_STAGE(bufoff, gbase, voff) do { _Pragma("unroll") for (int _i = 0; _i < 2; ++_i) \
;         __builtin_amdgcn_global_load_lds((const unsigned*)((const char*)(gbase) + (voff)[_i]), (PG8_LAS unsigned*)(lds + (bufoff) + ldsw + _i * 8192), 16, 0, 0); } while (0)
; #define PG8_LDA(dst, b, h) do { _Pragma("unroll") for (int m = 0; m < 4; ++m) _Pragma("unroll") for (int k = 0; k < 2; ++k) dst[m][k] = *(const PG8_LAS bf16x8*)(lds + PG8_SA(b, h) + aoff + m * 2048 + k * 1024); } while (0)
; #define PG8_MMA(ai, bj, At, Bt) do { __builtin_amdgcn_s_setprio(1); _Pragma("unroll") for (int m = 0; m < 4; ++m) _Pragma("unroll") for (int n = 0; n < 2; ++n) _Pragma("unroll") for (int k = 0; k < 2; ++k) \
;         acc[ai][bj][m][n] = __builtin_amdgcn_mfma_f32_16x16x32_bf16(Bt[n][k], At[m][k], acc[ai][bj][m][n], 0, 0, 0); __builtin_amdgcn_s_setprio(0); } while (0)
; #define PG8_WAIT_V(n) asm volatile("s_waitcnt vmcnt(" #n ")" ::: "memory")
; #define PG8_WAIT_L(n) asm volatile("s_waitcnt lgkmcnt(" #n ")" ::: "memory")
; #define PG8_BAR __builtin_amdgcn_s_barrier()
; #define PG8_SCHED __builtin_amdgcn_sched_barrier(0)
; template <class Epi, class Sched, bool ALIGN_EPI = false, bool SP2 = false>
; __device__ __forceinline__ void gemm_phase(PG8_LAS unsigned char* lds, const Gemm g, const Sched& S, const Epi& E) {
;     ...
;             if constexpr (Epi::KHOOK) { if ((t & 7) == 0 && t != 0) E.khook(acc, t >> 3, wr, fr, lds); }
;     ...
;             PG8_LDA(At, 1, 1); PG8_STAGE(PG8_SB(1, 0), b3, voffB); PG8_STAGE(PG8_SB(1, 1), b3 + hstep, voffB); PG8_STAGE(PG8_SA(1, 0), a3, voffA);
;             PG8_WAIT_V(8); PG8_WAIT_L(0); PG8_BAR; PG8_MMA(1, 0, At, B0); PG8_MMA(1, 1, At, B1); PG8_BAR; PG8_SCHED;
	s_add_i32 s85, s91, s46
	v_lshl_add_u64 v[208:209], v[208:209], 0, s[24:25]
	s_mov_b32 m0, s85
	s_add_i32 s86, s85, 0x2000
	ds_read_b128 v[188:191], v149 offset:49152
	ds_read_b128 v[192:195], v149 offset:50176
	ds_read_b128 v[196:199], v149 offset:51200
	ds_read_b128 v[200:203], v149 offset:52224
	ds_read_b128 v[204:207], v149 offset:53248
	ds_read_b128 v[230:233], v149 offset:54272
	ds_read_b128 v[234:237], v149 offset:55296
	ds_read_b128 v[238:241], v149 offset:56320
	global_load_lds_dwordx4 v[208:209], off
	v_lshl_add_u64 v[208:209], v[216:217], 0, s[24:25]
	s_mov_b32 m0, s86
	s_add_i32 s87, s87, s46
	global_load_lds_dwordx4 v[208:209], off
	v_lshl_add_u64 v[208:209], v[224:225], 0, s[24:25]
	s_mov_b32 m0, s87
	s_add_i32 s88, s87, 0x2000
	global_load_lds_dwordx4 v[208:209], off
	v_lshl_add_u64 v[208:209], v[226:227], 0, s[24:25]
	s_mov_b32 m0, s88
	s_nop 0
	global_load_lds_dwordx4 v[208:209], off
	v_lshl_add_u64 v[208:209], v[228:229], 0, s[24:25]
	s_mov_b32 m0, s75
	s_nop 0
	global_load_lds_dwordx4 v[208:209], off
	v_lshl_add_u64 v[208:209], v[242:243], 0, s[24:25]
	s_mov_b32 m0, s76
	s_nop 0
	global_load_lds_dwordx4 v[208:209], off
	s_waitcnt vmcnt(8)
	s_waitcnt lgkmcnt(0)
	s_barrier
	s_setprio 1
	s_waitcnt lgkmcnt(0)
	v_mfma_f32_16x16x32_bf16 v[68:71], v[154:157], v[188:191], v[68:71]
	v_mfma_f32_16x16x32_bf16 v[68:71], v[158:161], v[192:195], v[68:71]
	v_mfma_f32_16x16x32_bf16 v[52:55], v[154:157], v[196:199], v[52:55]
	v_mfma_f32_16x16x32_bf16 v[52:55], v[158:161], v[200:203], v[52:55]
	v_mfma_f32_16x16x32_bf16 v[36:39], v[154:157], v[204:207], v[36:39]
	v_mfma_f32_16x16x32_bf16 v[36:39], v[158:161], v[230:233], v[36:39]
	v_mfma_f32_16x16x32_bf16 v[20:23], v[154:157], v[234:237], v[20:23]
	v_mfma_f32_16x16x32_bf16 v[20:23], v[158:161], v[238:241], v[20:23]
	v_mfma_f32_16x16x32_bf16 v[16:19], v[162:165], v[234:237], v[16:19]
	v_mfma_f32_16x16x32_bf16 v[16:19], v[166:169], v[238:241], v[16:19]
	v_mfma_f32_16x16x32_bf16 v[32:35], v[162:165], v[204:207], v[32:35]
	v_mfma_f32_16x16x32_bf16 v[32:35], v[166:169], v[230:233], v[32:35]
	v_mfma_f32_16x16x32_bf16 v[48:51], v[162:165], v[196:199], v[48:51]
	v_mfma_f32_16x16x32_bf16 v[48:51], v[166:169], v[200:203], v[48:51]
	v_mfma_f32_16x16x32_bf16 v[64:67], v[162:165], v[188:191], v[64:67]
	v_mfma_f32_16x16x32_bf16 v[64:67], v[166:169], v[192:195], v[64:67]
	v_mfma_f32_16x16x32_bf16 v[60:63], v[170:173], v[188:191], v[60:63]
	v_mfma_f32_16x16x32_bf16 v[60:63], v[174:177], v[192:195], v[60:63]
	v_mfma_f32_16x16x32_bf16 v[44:47], v[170:173], v[196:199], v[44:47]
	v_mfma_f32_16x16x32_bf16 v[44:47], v[174:177], v[200:203], v[44:47]
	v_mfma_f32_16x16x32_bf16 v[28:31], v[170:173], v[204:207], v[28:31]
	v_mfma_f32_16x16x32_bf16 v[28:31], v[174:177], v[230:233], v[28:31]
	v_mfma_f32_16x16x32_bf16 v[12:15], v[170:173], v[234:237], v[12:15]
	v_mfma_f32_16x16x32_bf16 v[12:15], v[174:177], v[238:241], v[12:15]
	v_mfma_f32_16x16x32_bf16 v[8:11], v[178:181], v[234:237], v[8:11]
	v_mfma_f32_16x16x32_bf16 v[8:11], v[184:187], v[238:241], v[8:11]
	v_mfma_f32_16x16x32_bf16 v[24:27], v[178:181], v[204:207], v[24:27]
	v_mfma_f32_16x16x32_bf16 v[24:27], v[184:187], v[230:233], v[24:27]
	v_mfma_f32_16x16x32_bf16 v[40:43], v[178:181], v[196:199], v[40:43]
	v_mfma_f32_16x16x32_bf16 v[40:43], v[184:187], v[200:203], v[40:43]
	v_mfma_f32_16x16x32_bf16 v[56:59], v[178:181], v[188:191], v[56:59]
	v_mfma_f32_16x16x32_bf16 v[56:59], v[184:187], v[192:195], v[56:59]
	s_setprio 0
	s_barrier
	v_readlane_b32 s22, v252, 42
	v_readlane_b32 s23, v252, 43
	s_andn2_b64 vcc, exec, s[22:23]
	s_cbranch_vccnz .LBB0_251
	s_add_u32 s22, s6, 0x180
	s_addc_u32 s23, s7, 0
	s_add_u32 s89, s10, 0x200
	s_addc_u32 s92, s11, 0
	s_mov_b32 s93, 4
	v_mov_b32_e32 v154, v148
	s_add_i32 s40, s93, -2
	s_and_b32 s40, s40, 6
	s_cmp_lg_u32 s40, 0
	s_cbranch_scc1 .LBB0_250
	s_branch .LBB0_249

; #define PG8_STAGE(bufoff, gbase, voff) do { _Pragma("unroll") for (int _i = 0; _i < 2; ++_i) \
;         __builtin_amdgcn_global_load_lds((const unsigned*)((const char*)(gbase) + (voff)[_i]), (PG8_LAS unsigned*)(lds + (bufoff) + ldsw + _i * 8192), 16, 0, 0); } while (0)
; #define PG8_LDA(dst, b, h) do { _Pragma("unroll") for (int m = 0; m < 4; ++m) _Pragma("unroll") for (int k = 0; k < 2; ++k) dst[m][k] = *(const PG8_LAS bf16x8*)(lds + PG8_SA(b, h) + aoff + m * 2048 + k * 1024); } while (0)
; #define PG8_LDB(dst, b, h) do { _Pragma("unroll") for (int n = 0; n < 2; ++n) _Pragma("unroll") for (int k = 0; k < 2; ++k) dst[n][k] = *(const PG8_LAS bf16x8*)(lds + PG8_SB(b, h) + boff + n * 2048 + k * 1024); } while (0)
; #define PG8_MMA(ai, bj, At, Bt) do { __builtin_amdgcn_s_setprio(1); _Pragma("unroll") for (int m = 0; m < 4; ++m) _Pragma("unroll") for (int n = 0; n < 2; ++n) _Pragma("unroll") for (int k = 0; k < 2; ++k) \
;         acc[ai][bj][m][n] = __builtin_amdgcn_mfma_f32_16x16x32_bf16(Bt[n][k], At[m][k], acc[ai][bj][m][n], 0, 0, 0); __builtin_amdgcn_s_setprio(0); } while (0)
; #define PG8_WAIT_V(n) asm volatile("s_waitcnt vmcnt(" #n ")" ::: "memory")
; #define PG8_WAIT_L(n) asm volatile("s_waitcnt lgkmcnt(" #n ")" ::: "memory")
; template <class Epi, class Sched, bool ALIGN_EPI = false, bool SP2 = false>
; __device__ __forceinline__ void gemm_phase(PG8_LAS unsigned char* lds, const Gemm g, const Sched& S, const Epi& E) {
;     ...
;             const bool last = (t == nt - 2);
;             const char* a1 = cA + (size_t)(t + 1) * kstep;
;             const char* a2 = last ? nA : cA + (size_t)(t + 2) * kstep; const char* b2 = last ? nB : cB + (size_t)(t + 2) * kstep;
;             const char* a3 = a2 + kstep; const char* b3 = b2 + kstep;
;             if (last && has_next) S.a_ready(nxt);
;             if constexpr (SP2) {
;             PG8_LDB(B0, 0, 0); PG8_LDB(B1, 0, 1); PG8_SCHED; PG8_LDA(At, 0, 0); PG8_STAGE(PG8_SA(1, 1), a1 + hstep, voffA);
;             PG8_WAIT_V(8); PG8_WAIT_L(0); PG8_BAR; PG8_MMA(0, 0, At, B0); PG8_MMA(0, 1, At, B1); PG8_BAR; PG8_SCHED;
;             PG8_LDA(At, 0, 1); PG8_STAGE(PG8_SB(0, 0), b2, voffB); PG8_STAGE(PG8_SB(0, 1), b2 + hstep, voffB); PG8_STAGE(PG8_SA(0, 0), a2, voffA);
;             PG8_WAIT_V(8); PG8_WAIT_L(0); PG8_BAR; PG8_MMA(1, 0, At, B0); PG8_MMA(1, 1, At, B1); PG8_BAR; PG8_SCHED;
.LBB0_250:
	ds_read_b128 v[156:159], v150
	ds_read_b128 v[160:163], v150 offset:1024
	ds_read_b128 v[164:167], v150 offset:2048
	ds_read_b128 v[168:171], v150 offset:3072
	ds_read_b128 v[172:175], v151
	ds_read_b128 v[176:179], v151 offset:1024
	ds_read_b128 v[184:187], v151 offset:2048
	ds_read_b128 v[188:191], v151 offset:3072
	s_add_u32 s40, s22, 0x80
	s_addc_u32 s41, s23, 0
	s_cmp_eq_u32 s9, s93
	s_cselect_b32 s40, s4, s40
	s_cselect_b32 s41, s5, s41
	s_cselect_b32 s95, s17, s92
	s_cselect_b32 s94, s16, s89
	s_mov_b32 m0, s37
	v_lshl_add_u64 v[180:181], s[22:23], 0, v[140:141]
	ds_read_b128 v[192:195], v149
	ds_read_b128 v[196:199], v149 offset:1024
	ds_read_b128 v[200:203], v149 offset:2048
	ds_read_b128 v[204:207], v149 offset:3072
	ds_read_b128 v[230:233], v149 offset:4096
	ds_read_b128 v[234:237], v149 offset:5120
	ds_read_b128 v[238:241], v149 offset:6144
	ds_read_b128 v[242:245], v149 offset:7168
	global_load_lds_dwordx4 v[180:181], off
	v_lshl_add_u64 v[180:181], s[22:23], 0, v[142:143]
	s_mov_b32 m0, s80
	s_nop 0
	global_load_lds_dwordx4 v[180:181], off
	s_waitcnt vmcnt(8)
	s_waitcnt lgkmcnt(0)
	s_barrier
	s_setprio 1
	s_waitcnt lgkmcnt(0)
	v_mfma_f32_16x16x32_bf16 v[132:135], v[156:159], v[192:195], v[132:135]
	v_mfma_f32_16x16x32_bf16 v[132:135], v[160:163], v[196:199], v[132:135]
	v_mfma_f32_16x16x32_bf16 v[116:119], v[156:159], v[200:203], v[116:119]
	v_mfma_f32_16x16x32_bf16 v[116:119], v[160:163], v[204:207], v[116:119]
	v_mfma_f32_16x16x32_bf16 v[100:103], v[156:159], v[230:233], v[100:103]
	v_mfma_f32_16x16x32_bf16 v[100:103], v[160:163], v[234:237], v[100:103]
	v_mfma_f32_16x16x32_bf16 v[84:87], v[156:159], v[238:241], v[84:87]
	v_mfma_f32_16x16x32_bf16 v[84:87], v[160:163], v[242:245], v[84:87]
	v_mfma_f32_16x16x32_bf16 v[80:83], v[164:167], v[238:241], v[80:83]
	v_mfma_f32_16x16x32_bf16 v[80:83], v[168:171], v[242:245], v[80:83]
	v_mfma_f32_16x16x32_bf16 v[96:99], v[164:167], v[230:233], v[96:99]
	v_mfma_f32_16x16x32_bf16 v[96:99], v[168:171], v[234:237], v[96:99]
	v_mfma_f32_16x16x32_bf16 v[112:115], v[164:167], v[200:203], v[112:115]
	v_mfma_f32_16x16x32_bf16 v[112:115], v[168:171], v[204:207], v[112:115]
	v_mfma_f32_16x16x32_bf16 v[128:131], v[164:167], v[192:195], v[128:131]
	v_mfma_f32_16x16x32_bf16 v[128:131], v[168:171], v[196:199], v[128:131]
	v_mfma_f32_16x16x32_bf16 v[124:127], v[172:175], v[192:195], v[124:127]
	v_mfma_f32_16x16x32_bf16 v[124:127], v[176:179], v[196:199], v[124:127]
	v_mfma_f32_16x16x32_bf16 v[108:111], v[172:175], v[200:203], v[108:111]
	v_mfma_f32_16x16x32_bf16 v[108:111], v[176:179], v[204:207], v[108:111]
	v_mfma_f32_16x16x32_bf16 v[92:95], v[172:175], v[230:233], v[92:95]
	v_mfma_f32_16x16x32_bf16 v[92:95], v[176:179], v[234:237], v[92:95]
	v_mfma_f32_16x16x32_bf16 v[76:79], v[172:175], v[238:241], v[76:79]
	v_mfma_f32_16x16x32_bf16 v[76:79], v[176:179], v[242:245], v[76:79]
	v_mfma_f32_16x16x32_bf16 v[72:75], v[184:187], v[238:241], v[72:75]
	v_mfma_f32_16x16x32_bf16 v[72:75], v[188:191], v[242:245], v[72:75]
	v_mfma_f32_16x16x32_bf16 v[88:91], v[184:187], v[230:233], v[88:91]
	v_mfma_f32_16x16x32_bf16 v[88:91], v[188:191], v[234:237], v[88:91]
	v_mfma_f32_16x16x32_bf16 v[104:107], v[184:187], v[200:203], v[104:107]
	v_mfma_f32_16x16x32_bf16 v[104:107], v[188:191], v[204:207], v[104:107]
	v_mfma_f32_16x16x32_bf16 v[120:123], v[184:187], v[192:195], v[120:123]
	v_mfma_f32_16x16x32_bf16 v[120:123], v[188:191], v[196:199], v[120:123]
	s_setprio 0
	s_barrier
	s_mov_b32 m0, s81
	v_lshl_add_u64 v[180:181], s[94:95], 0, v[0:1]
	v_lshl_add_u64 v[208:209], s[94:95], 0, v[138:139]
	s_add_u32 s94, s94, s48
	ds_read_b128 v[192:195], v149 offset:16384
	ds_read_b128 v[196:199], v149 offset:17408
	ds_read_b128 v[200:203], v149 offset:18432
	ds_read_b128 v[204:207], v149 offset:19456
	ds_read_b128 v[230:233], v149 offset:20480
	ds_read_b128 v[234:237], v149 offset:21504
	ds_read_b128 v[238:241], v149 offset:22528
	ds_read_b128 v[242:245], v149 offset:23552
	global_load_lds_dwordx4 v[180:181], off
	s_mov_b32 m0, s82
	s_addc_u32 s95, s95, s49
	global_load_lds_dwordx4 v[208:209], off
	v_lshl_add_u64 v[216:217], s[94:95], 0, v[0:1]
	s_mov_b32 m0, s83
	v_lshl_add_u64 v[224:225], s[94:95], 0, v[138:139]
	global_load_lds_dwordx4 v[216:217], off
	s_mov_b32 m0, s84
	v_lshl_add_u64 v[226:227], s[40:41], 0, v[2:3]
	global_load_lds_dwordx4 v[224:225], off
	s_mov_b32 m0, s47
	v_lshl_add_u64 v[228:229], s[40:41], 0, v[136:137]
	global_load_lds_dwordx4 v[226:227], off
	s_mov_b32 m0, s52
	s_nop 0
	global_load_lds_dwordx4 v[228:229], off
	s_waitcnt vmcnt(8)
	s_waitcnt lgkmcnt(0)
	s_barrier
; #define PG8_STAGE(bufoff, gbase, voff) do { _Pragma("unroll") for (int _i = 0; _i < 2; ++_i) \
;         __builtin_amdgcn_global_load_lds((const unsigned*)((const char*)(gbase) + (voff)[_i]), (PG8_LAS unsigned*)(lds + (bufoff) + ldsw + _i * 8192), 16, 0, 0); } while (0)
; #define PG8_LDA(dst, b, h) do { _Pragma("unroll") for (int m = 0; m < 4; ++m) _Pragma("unroll") for (int k = 0; k < 2; ++k) dst[m][k] = *(const PG8_LAS bf16x8*)(lds + PG8_SA(b, h) + aoff + m * 2048 + k * 1024); } while (0)
; #define PG8_LDB(dst, b, h) do { _Pragma("unroll") for (int n = 0; n < 2; ++n) _Pragma("unroll") for (int k = 0; k < 2; ++k) dst[n][k] = *(const PG8_LAS bf16x8*)(lds + PG8_SB(b, h) + boff + n * 2048 + k * 1024); } while (0)
; #define PG8_MMA(ai, bj, At, Bt) do { __builtin_amdgcn_s_setprio(1); _Pragma("unroll") for (int m = 0; m < 4; ++m) _Pragma("unroll") for (int n = 0; n < 2; ++n) _Pragma("unroll") for (int k = 0; k < 2; ++k) \
;         acc[ai][bj][m][n] = __builtin_amdgcn_mfma_f32_16x16x32_bf16(Bt[n][k], At[m][k], acc[ai][bj][m][n], 0, 0, 0); __builtin_amdgcn_s_setprio(0); } while (0)
; #define PG8_WAIT_V(n) asm volatile("s_waitcnt vmcnt(" #n ")" ::: "memory")
; #define PG8_WAIT_L(n) asm volatile("s_waitcnt lgkmcnt(" #n ")" ::: "memory")
; #define PG8_BAR __builtin_amdgcn_s_barrier()
; #define PG8_SCHED __builtin_amdgcn_sched_barrier(0)
; template <class Epi, class Sched, bool ALIGN_EPI = false, bool SP2 = false>
; __device__ __forceinline__ void gemm_phase(PG8_LAS unsigned char* lds, const Gemm g, const Sched& S, const Epi& E) {
;     ...
;             PG8_WAIT_V(8); PG8_WAIT_L(0); PG8_BAR; PG8_MMA(1, 0, At, B0); PG8_MMA(1, 1, At, B1); PG8_BAR; PG8_SCHED;
;             PG8_LDB(B0, 1, 0); PG8_LDB(B1, 1, 1); PG8_SCHED; PG8_LDA(At, 1, 0); PG8_STAGE(PG8_SA(0, 1), a2 + hstep, voffA);
;             PG8_WAIT_V(8); PG8_WAIT_L(0); PG8_BAR; PG8_MMA(0, 0, At, B0); PG8_MMA(0, 1, At, B1); PG8_BAR; PG8_SCHED;
	s_setprio 1
	s_waitcnt lgkmcnt(0)
	v_mfma_f32_16x16x32_bf16 v[68:71], v[156:159], v[192:195], v[68:71]
	v_mfma_f32_16x16x32_bf16 v[68:71], v[160:163], v[196:199], v[68:71]
	v_mfma_f32_16x16x32_bf16 v[52:55], v[156:159], v[200:203], v[52:55]
	v_mfma_f32_16x16x32_bf16 v[52:55], v[160:163], v[204:207], v[52:55]
	v_mfma_f32_16x16x32_bf16 v[36:39], v[156:159], v[230:233], v[36:39]
	v_mfma_f32_16x16x32_bf16 v[36:39], v[160:163], v[234:237], v[36:39]
	v_mfma_f32_16x16x32_bf16 v[20:23], v[156:159], v[238:241], v[20:23]
	v_mfma_f32_16x16x32_bf16 v[20:23], v[160:163], v[242:245], v[20:23]
	v_mfma_f32_16x16x32_bf16 v[16:19], v[164:167], v[238:241], v[16:19]
	v_mfma_f32_16x16x32_bf16 v[16:19], v[168:171], v[242:245], v[16:19]
	v_mfma_f32_16x16x32_bf16 v[32:35], v[164:167], v[230:233], v[32:35]
	v_mfma_f32_16x16x32_bf16 v[32:35], v[168:171], v[234:237], v[32:35]
	v_mfma_f32_16x16x32_bf16 v[48:51], v[164:167], v[200:203], v[48:51]
	v_mfma_f32_16x16x32_bf16 v[48:51], v[168:171], v[204:207], v[48:51]
	v_mfma_f32_16x16x32_bf16 v[64:67], v[164:167], v[192:195], v[64:67]
	v_mfma_f32_16x16x32_bf16 v[64:67], v[168:171], v[196:199], v[64:67]
	v_mfma_f32_16x16x32_bf16 v[60:63], v[172:175], v[192:195], v[60:63]
	v_mfma_f32_16x16x32_bf16 v[60:63], v[176:179], v[196:199], v[60:63]
	v_mfma_f32_16x16x32_bf16 v[44:47], v[172:175], v[200:203], v[44:47]
	v_mfma_f32_16x16x32_bf16 v[44:47], v[176:179], v[204:207], v[44:47]
	v_mfma_f32_16x16x32_bf16 v[28:31], v[172:175], v[230:233], v[28:31]
	v_mfma_f32_16x16x32_bf16 v[28:31], v[176:179], v[234:237], v[28:31]
	v_mfma_f32_16x16x32_bf16 v[12:15], v[172:175], v[238:241], v[12:15]
	v_mfma_f32_16x16x32_bf16 v[12:15], v[176:179], v[242:245], v[12:15]
	v_mfma_f32_16x16x32_bf16 v[8:11], v[184:187], v[238:241], v[8:11]
	v_mfma_f32_16x16x32_bf16 v[8:11], v[188:191], v[242:245], v[8:11]
	v_mfma_f32_16x16x32_bf16 v[24:27], v[184:187], v[230:233], v[24:27]
	v_mfma_f32_16x16x32_bf16 v[24:27], v[188:191], v[234:237], v[24:27]
	v_mfma_f32_16x16x32_bf16 v[40:43], v[184:187], v[200:203], v[40:43]
	v_mfma_f32_16x16x32_bf16 v[40:43], v[188:191], v[204:207], v[40:43]
	v_mfma_f32_16x16x32_bf16 v[56:59], v[184:187], v[192:195], v[56:59]
	v_mfma_f32_16x16x32_bf16 v[56:59], v[188:191], v[196:199], v[56:59]
	s_setprio 0
	s_barrier
	ds_read_b128 v[156:159], v152
	ds_read_b128 v[160:163], v152 offset:1024
	ds_read_b128 v[164:167], v152 offset:2048
	ds_read_b128 v[168:171], v152 offset:3072
	ds_read_b128 v[172:175], v153
	ds_read_b128 v[176:179], v153 offset:1024
	ds_read_b128 v[184:187], v153 offset:2048
	ds_read_b128 v[188:191], v153 offset:3072
	s_add_u32 s40, s40, s48
	s_addc_u32 s41, s41, s49
	s_mov_b32 m0, s53
	v_lshl_add_u64 v[246:247], s[40:41], 0, v[2:3]
	ds_read_b128 v[192:195], v149 offset:32768
	ds_read_b128 v[196:199], v149 offset:33792
	ds_read_b128 v[200:203], v149 offset:34816
	ds_read_b128 v[204:207], v149 offset:35840
	ds_read_b128 v[230:233], v149 offset:36864
	ds_read_b128 v[234:237], v149 offset:37888
	ds_read_b128 v[238:241], v149 offset:38912
	ds_read_b128 v[242:245], v149 offset:39936
	global_load_lds_dwordx4 v[246:247], off
	v_lshl_add_u64 v[246:247], s[40:41], 0, v[136:137]
	s_mov_b32 m0, s72
	s_nop 0
	global_load_lds_dwordx4 v[246:247], off
	s_waitcnt vmcnt(8)
	s_waitcnt lgkmcnt(0)
	s_barrier
	s_setprio 1
	s_waitcnt lgkmcnt(0)
	v_mfma_f32_16x16x32_bf16 v[132:135], v[156:159], v[192:195], v[132:135]
	v_mfma_f32_16x16x32_bf16 v[132:135], v[160:163], v[196:199], v[132:135]
	v_mfma_f32_16x16x32_bf16 v[116:119], v[156:159], v[200:203], v[116:119]
	v_mfma_f32_16x16x32_bf16 v[116:119], v[160:163], v[204:207], v[116:119]
	v_mfma_f32_16x16x32_bf16 v[100:103], v[156:159], v[230:233], v[100:103]
	v_mfma_f32_16x16x32_bf16 v[100:103], v[160:163], v[234:237], v[100:103]
	v_mfma_f32_16x16x32_bf16 v[84:87], v[156:159], v[238:241], v[84:87]
	v_mfma_f32_16x16x32_bf16 v[84:87], v[160:163], v[242:245], v[84:87]
	v_mfma_f32_16x16x32_bf16 v[80:83], v[164:167], v[238:241], v[80:83]
	v_mfma_f32_16x16x32_bf16 v[80:83], v[168:171], v[242:245], v[80:83]
	v_mfma_f32_16x16x32_bf16 v[96:99], v[164:167], v[230:233], v[96:99]
	v_mfma_f32_16x16x32_bf16 v[96:99], v[168:171], v[234:237], v[96:99]
	v_mfma_f32_16x16x32_bf16 v[112:115], v[164:167], v[200:203], v[112:115]
	v_mfma_f32_16x16x32_bf16 v[112:115], v[168:171], v[204:207], v[112:115]
	v_mfma_f32_16x16x32_bf16 v[128:131], v[164:167], v[192:195], v[128:131]
	v_mfma_f32_16x16x32_bf16 v[128:131], v[168:171], v[196:199], v[128:131]
	v_mfma_f32_16x16x32_bf16 v[124:127], v[172:175], v[192:195], v[124:127]
	v_mfma_f32_16x16x32_bf16 v[124:127], v[176:179], v[196:199], v[124:127]
	v_mfma_f32_16x16x32_bf16 v[108:111], v[172:175], v[200:203], v[108:111]
	v_mfma_f32_16x16x32_bf16 v[108:111], v[176:179], v[204:207], v[108:111]
	v_mfma_f32_16x16x32_bf16 v[92:95], v[172:175], v[230:233], v[92:95]
	v_mfma_f32_16x16x32_bf16 v[92:95], v[176:179], v[234:237], v[92:95]
	v_mfma_f32_16x16x32_bf16 v[76:79], v[172:175], v[238:241], v[76:79]
	v_mfma_f32_16x16x32_bf16 v[76:79], v[176:179], v[242:245], v[76:79]
	v_mfma_f32_16x16x32_bf16 v[72:75], v[184:187], v[238:241], v[72:75]
	v_mfma_f32_16x16x32_bf16 v[72:75], v[188:191], v[242:245], v[72:75]
	v_mfma_f32_16x16x32_bf16 v[88:91], v[184:187], v[230:233], v[88:91]
	v_mfma_f32_16x16x32_bf16 v[88:91], v[188:191], v[234:237], v[88:91]
	v_mfma_f32_16x16x32_bf16 v[104:107], v[184:187], v[200:203], v[104:107]
	v_mfma_f32_16x16x32_bf16 v[104:107], v[188:191], v[204:207], v[104:107]
	v_mfma_f32_16x16x32_bf16 v[120:123], v[184:187], v[192:195], v[120:123]
	v_mfma_f32_16x16x32_bf16 v[120:123], v[188:191], v[196:199], v[120:123]
	s_setprio 0
	s_barrier
; #define PG8_STAGE(bufoff, gbase, voff) do { _Pragma("unroll") for (int _i = 0; _i < 2; ++_i) \
;         __builtin_amdgcn_global_load_lds((const unsigned*)((const char*)(gbase) + (voff)[_i]), (PG8_LAS unsigned*)(lds + (bufoff) + ldsw + _i * 8192), 16, 0, 0); } while (0)
; #define PG8_LDA(dst, b, h) do { _Pragma("unroll") for (int m = 0; m < 4; ++m) _Pragma("unroll") for (int k = 0; k < 2; ++k) dst[m][k] = *(const PG8_LAS bf16x8*)(lds + PG8_SA(b, h) + aoff + m * 2048 + k * 1024); } while (0)
; #define PG8_LDB(dst, b, h) do { _Pragma("unroll") for (int n = 0; n < 2; ++n) _Pragma("unroll") for (int k = 0; k < 2; ++k) dst[n][k] = *(const PG8_LAS bf16x8*)(lds + PG8_SB(b, h) + boff + n * 2048 + k * 1024); } while (0)
; #define PG8_MMA(ai, bj, At, Bt) do { __builtin_amdgcn_s_setprio(1); _Pragma("unroll") for (int m = 0; m < 4; ++m) _Pragma("unroll") for (int n = 0; n < 2; ++n) _Pragma("unroll") for (int k = 0; k < 2; ++k) \
;         acc[ai][bj][m][n] = __builtin_amdgcn_mfma_f32_16x16x32_bf16(Bt[n][k], At[m][k], acc[ai][bj][m][n], 0, 0, 0); __builtin_amdgcn_s_setprio(0); } while (0)
; #define PG8_WAIT_V(n) asm volatile("s_waitcnt vmcnt(" #n ")" ::: "memory")
; #define PG8_WAIT_L(n) asm volatile("s_waitcnt lgkmcnt(" #n ")" ::: "memory")
; #define PG8_BAR __builtin_amdgcn_s_barrier()
; #define PG8_SCHED __builtin_amdgcn_sched_barrier(0)
; template <class Epi, class Sched, bool ALIGN_EPI = false, bool SP2 = false>
; __device__ __forceinline__ void gemm_phase(PG8_LAS unsigned char* lds, const Gemm g, const Sched& S, const Epi& E) {
;     ...
;             PG8_LDA(At, 0, 1); PG8_STAGE(PG8_SB(0, 0), b2, voffB); PG8_STAGE(PG8_SB(0, 1), b2 + hstep, voffB); PG8_STAGE(PG8_SA(0, 0), a2, voffA);
;             PG8_WAIT_V(8); PG8_WAIT_L(0); PG8_BAR; PG8_MMA(1, 0, At, B0); PG8_MMA(1, 1, At, B1); PG8_BAR; PG8_SCHED;
;             PG8_LDB(B0, 1, 0); PG8_LDB(B1, 1, 1); PG8_SCHED; PG8_LDA(At, 1, 0); PG8_STAGE(PG8_SA(0, 1), a2 + hstep, voffA);
;             PG8_WAIT_V(8); PG8_WAIT_L(0); PG8_BAR; PG8_MMA(0, 0, At, B0); PG8_MMA(0, 1, At, B1); PG8_BAR; PG8_SCHED;
;             PG8_LDA(At, 1, 1); PG8_STAGE(PG8_SB(1, 0), b3, voffB); PG8_STAGE(PG8_SB(1, 1), b3 + hstep, voffB); PG8_STAGE(PG8_SA(1, 0), a3, voffA);
;             PG8_WAIT_V(8); PG8_WAIT_L(0); PG8_BAR; PG8_MMA(1, 0, At, B0); PG8_MMA(1, 1, At, B1); PG8_BAR; PG8_SCHED;
	s_mov_b32 m0, s85
	v_lshl_add_u64 v[180:181], v[180:181], 0, s[24:25]
	ds_read_b128 v[192:195], v149 offset:49152
	ds_read_b128 v[196:199], v149 offset:50176
	ds_read_b128 v[200:203], v149 offset:51200
	ds_read_b128 v[204:207], v149 offset:52224
	ds_read_b128 v[230:233], v149 offset:53248
	ds_read_b128 v[234:237], v149 offset:54272
	ds_read_b128 v[238:241], v149 offset:55296
	ds_read_b128 v[242:245], v149 offset:56320
	global_load_lds_dwordx4 v[180:181], off
	v_lshl_add_u64 v[180:181], v[208:209], 0, s[24:25]
	s_mov_b32 m0, s86
	s_nop 0
	global_load_lds_dwordx4 v[180:181], off
	v_lshl_add_u64 v[180:181], v[216:217], 0, s[24:25]
	s_mov_b32 m0, s87
	s_nop 0
	global_load_lds_dwordx4 v[180:181], off
	v_lshl_add_u64 v[180:181], v[224:225], 0, s[24:25]
	s_mov_b32 m0, s88
	s_nop 0
	global_load_lds_dwordx4 v[180:181], off
	v_lshl_add_u64 v[180:181], v[226:227], 0, s[24:25]
	s_mov_b32 m0, s75
	s_nop 0
	global_load_lds_dwordx4 v[180:181], off
	v_lshl_add_u64 v[180:181], v[228:229], 0, s[24:25]
	s_mov_b32 m0, s76
	s_nop 0
	global_load_lds_dwordx4 v[180:181], off
	s_waitcnt vmcnt(8)
	s_waitcnt lgkmcnt(0)
	s_barrier
	s_setprio 1
	s_waitcnt lgkmcnt(0)
	v_mfma_f32_16x16x32_bf16 v[68:71], v[156:159], v[192:195], v[68:71]
	v_mfma_f32_16x16x32_bf16 v[68:71], v[160:163], v[196:199], v[68:71]
	v_mfma_f32_16x16x32_bf16 v[52:55], v[156:159], v[200:203], v[52:55]
	v_mfma_f32_16x16x32_bf16 v[52:55], v[160:163], v[204:207], v[52:55]
	v_mfma_f32_16x16x32_bf16 v[36:39], v[156:159], v[230:233], v[36:39]
	v_mfma_f32_16x16x32_bf16 v[36:39], v[160:163], v[234:237], v[36:39]
	v_mfma_f32_16x16x32_bf16 v[20:23], v[156:159], v[238:241], v[20:23]
	v_mfma_f32_16x16x32_bf16 v[20:23], v[160:163], v[242:245], v[20:23]
	v_mfma_f32_16x16x32_bf16 v[16:19], v[164:167], v[238:241], v[16:19]
	v_mfma_f32_16x16x32_bf16 v[16:19], v[168:171], v[242:245], v[16:19]
	v_mfma_f32_16x16x32_bf16 v[32:35], v[164:167], v[230:233], v[32:35]
	v_mfma_f32_16x16x32_bf16 v[32:35], v[168:171], v[234:237], v[32:35]
	v_mfma_f32_16x16x32_bf16 v[48:51], v[164:167], v[200:203], v[48:51]
	v_mfma_f32_16x16x32_bf16 v[48:51], v[168:171], v[204:207], v[48:51]
	v_mfma_f32_16x16x32_bf16 v[64:67], v[164:167], v[192:195], v[64:67]
	v_mfma_f32_16x16x32_bf16 v[64:67], v[168:171], v[196:199], v[64:67]
	v_mfma_f32_16x16x32_bf16 v[60:63], v[172:175], v[192:195], v[60:63]
	v_mfma_f32_16x16x32_bf16 v[60:63], v[176:179], v[196:199], v[60:63]
	v_mfma_f32_16x16x32_bf16 v[44:47], v[172:175], v[200:203], v[44:47]
	v_mfma_f32_16x16x32_bf16 v[44:47], v[176:179], v[204:207], v[44:47]
	v_mfma_f32_16x16x32_bf16 v[28:31], v[172:175], v[230:233], v[28:31]
	v_mfma_f32_16x16x32_bf16 v[28:31], v[176:179], v[234:237], v[28:31]
	v_mfma_f32_16x16x32_bf16 v[12:15], v[172:175], v[238:241], v[12:15]
	v_mfma_f32_16x16x32_bf16 v[12:15], v[176:179], v[242:245], v[12:15]
	v_mfma_f32_16x16x32_bf16 v[8:11], v[184:187], v[238:241], v[8:11]
	v_mfma_f32_16x16x32_bf16 v[8:11], v[188:191], v[242:245], v[8:11]
	v_mfma_f32_16x16x32_bf16 v[24:27], v[184:187], v[230:233], v[24:27]
	v_mfma_f32_16x16x32_bf16 v[24:27], v[188:191], v[234:237], v[24:27]
	v_mfma_f32_16x16x32_bf16 v[40:43], v[184:187], v[200:203], v[40:43]
	v_mfma_f32_16x16x32_bf16 v[40:43], v[188:191], v[204:207], v[40:43]
	v_mfma_f32_16x16x32_bf16 v[56:59], v[184:187], v[192:195], v[56:59]
	v_mfma_f32_16x16x32_bf16 v[56:59], v[188:191], v[196:199], v[56:59]
	s_setprio 0
	s_barrier
	s_add_i32 s40, s93, 2
	s_add_u32 s22, s22, 0x100
	s_addc_u32 s23, s23, 0
	s_add_u32 s89, s89, 0x100
	s_addc_u32 s92, s92, 0
	s_cmp_ge_u32 s93, s9
	v_add_u32_e32 v154, 0x100, v154
	s_cbranch_scc0 .LBB0_248

; #define PG8_STAGE(bufoff, gbase, voff) do { _Pragma("unroll") for (int _i = 0; _i < 2; ++_i) \
;         __builtin_amdgcn_global_load_lds((const unsigned*)((const char*)(gbase) + (voff)[_i]), (PG8_LAS unsigned*)(lds + (bufoff) + ldsw + _i * 8192), 16, 0, 0); } while (0)
; #define PG8_LDA(dst, b, h) do { _Pragma("unroll") for (int m = 0; m < 4; ++m) _Pragma("unroll") for (int k = 0; k < 2; ++k) dst[m][k] = *(const PG8_LAS bf16x8*)(lds + PG8_SA(b, h) + aoff + m * 2048 + k * 1024); } while (0)
; #define PG8_LDB(dst, b, h) do { _Pragma("unroll") for (int n = 0; n < 2; ++n) _Pragma("unroll") for (int k = 0; k < 2; ++k) dst[n][k] = *(const PG8_LAS bf16x8*)(lds + PG8_SB(b, h) + boff + n * 2048 + k * 1024); } while (0)
; #define PG8_WAIT_V(n) asm volatile("s_waitcnt vmcnt(" #n ")" ::: "memory")
; #define PG8_WAIT_L(n) asm volatile("s_waitcnt lgkmcnt(" #n ")" ::: "memory")
; template <class Epi, class Sched, bool ALIGN_EPI = false, bool SP2 = false>
; __device__ __forceinline__ void gemm_phase(PG8_LAS unsigned char* lds, const Gemm g, const Sched& S, const Epi& E) {
;     ...
;         const bool has_next = S.next(ui + 1, nxt);
;         const char* nA = has_next ? (const char*)g.A + (size_t)nxt.pm * tstepA : cA; const char* nB = has_next ? (const char*)g.Bt + (size_t)nxt.pn * tstep : cB;
;         for (int t = 0; t < nt; t += 2) {
;             if constexpr (Epi::KHOOK) { if ((t & 7) == 0 && t != 0) E.khook(acc, t >> 3, wr, fr, lds); }
;             const bool last = (t == nt - 2);
;             const char* a1 = cA + (size_t)(t + 1) * kstep;
;             const char* a2 = last ? nA : cA + (size_t)(t + 2) * kstep; const char* b2 = last ? nB : cB + (size_t)(t + 2) * kstep;
;             const char* a3 = a2 + kstep; const char* b3 = b2 + kstep;
;             if (last && has_next) S.a_ready(nxt);
;             if constexpr (SP2) {
;             PG8_LDB(B0, 0, 0); PG8_LDB(B1, 0, 1); PG8_SCHED; PG8_LDA(At, 0, 0); PG8_STAGE(PG8_SA(1, 1), a1 + hstep, voffA);
;             PG8_WAIT_V(8); PG8_WAIT_L(0); PG8_BAR; PG8_MMA(0, 0, At, B0); PG8_MMA(0, 1, At, B1); PG8_BAR; PG8_SCHED;
;             PG8_LDA(At, 0, 1); PG8_STAGE(PG8_SB(0, 0), b2, voffB); PG8_STAGE(PG8_SB(0, 1), b2 + hstep, voffB); PG8_STAGE(PG8_SA(0, 0), a2, voffA);
;             PG8_WAIT_V(8); PG8_WAIT_L(0); PG8_BAR; PG8_MMA(1, 0, At, B0); PG8_MMA(1, 1, At, B1); PG8_BAR; PG8_SCHED;
.LBB0_294:
	s_add_i32 s81, s40, 2
	s_add_u32 s82, s38, 0x80
	s_addc_u32 s41, s39, 0
	s_cmp_eq_u32 s33, s40
	s_cselect_b32 s41, s7, s41
	s_cselect_b32 s40, s6, s82
	v_add_u32_e32 v0, s19, v151
	s_cselect_b32 s83, s23, s80
	s_cselect_b32 s82, s22, s79
	s_add_i32 s84, 0, 0x14000
	ds_read_b128 v[154:157], v0
	ds_read_b128 v[158:161], v0 offset:1024
	ds_read_b128 v[162:165], v0 offset:2048
	ds_read_b128 v[166:169], v0 offset:3072
	v_add_u32_e32 v0, s84, v151
	ds_read_b128 v[170:173], v0
	ds_read_b128 v[174:177], v0 offset:1024
	ds_read_b128 v[178:181], v0 offset:2048
	ds_read_b128 v[184:187], v0 offset:3072
	v_lshl_add_u64 v[2:3], s[38:39], 0, v[144:145]
	s_add_i32 m0, s46, 0xc000
	ds_read_b128 v[188:191], v152
	ds_read_b128 v[192:195], v152 offset:1024
	ds_read_b128 v[196:199], v152 offset:2048
	ds_read_b128 v[200:203], v152 offset:3072
	ds_read_b128 v[204:207], v152 offset:4096
	ds_read_b128 v[230:233], v152 offset:5120
	ds_read_b128 v[234:237], v152 offset:6144
	ds_read_b128 v[238:241], v152 offset:7168
	global_load_lds_dwordx4 v[2:3], off
	v_lshl_add_u64 v[2:3], s[38:39], 0, v[146:147]
	s_add_i32 m0, s46, 0xe000
	s_nop 0
	global_load_lds_dwordx4 v[2:3], off
	s_waitcnt vmcnt(8)
	s_waitcnt lgkmcnt(0)
	s_barrier
	s_setprio 1
	s_waitcnt lgkmcnt(0)
	v_mfma_f32_16x16x32_bf16 v[8:11], v[154:157], v[188:191], v[8:11]
	v_mfma_f32_16x16x32_bf16 v[8:11], v[158:161], v[192:195], v[8:11]
	v_mfma_f32_16x16x32_bf16 v[48:51], v[154:157], v[196:199], v[48:51]
	v_mfma_f32_16x16x32_bf16 v[48:51], v[158:161], v[200:203], v[48:51]
	v_mfma_f32_16x16x32_bf16 v[96:99], v[154:157], v[204:207], v[96:99]
	v_mfma_f32_16x16x32_bf16 v[96:99], v[158:161], v[230:233], v[96:99]
	v_mfma_f32_16x16x32_bf16 v[120:123], v[154:157], v[234:237], v[120:123]
	v_mfma_f32_16x16x32_bf16 v[120:123], v[158:161], v[238:241], v[120:123]
	v_mfma_f32_16x16x32_bf16 v[124:127], v[162:165], v[234:237], v[124:127]
	v_mfma_f32_16x16x32_bf16 v[124:127], v[166:169], v[238:241], v[124:127]
	v_mfma_f32_16x16x32_bf16 v[100:103], v[162:165], v[204:207], v[100:103]
	v_mfma_f32_16x16x32_bf16 v[100:103], v[166:169], v[230:233], v[100:103]
	v_mfma_f32_16x16x32_bf16 v[52:55], v[162:165], v[196:199], v[52:55]
	v_mfma_f32_16x16x32_bf16 v[52:55], v[166:169], v[200:203], v[52:55]
	v_mfma_f32_16x16x32_bf16 v[12:15], v[162:165], v[188:191], v[12:15]
	v_mfma_f32_16x16x32_bf16 v[12:15], v[166:169], v[192:195], v[12:15]
	v_mfma_f32_16x16x32_bf16 v[24:27], v[170:173], v[188:191], v[24:27]
	v_mfma_f32_16x16x32_bf16 v[24:27], v[174:177], v[192:195], v[24:27]
	v_mfma_f32_16x16x32_bf16 v[72:75], v[170:173], v[196:199], v[72:75]
	v_mfma_f32_16x16x32_bf16 v[72:75], v[174:177], v[200:203], v[72:75]
	v_mfma_f32_16x16x32_bf16 v[112:115], v[170:173], v[204:207], v[112:115]
	v_mfma_f32_16x16x32_bf16 v[112:115], v[174:177], v[230:233], v[112:115]
	v_mfma_f32_16x16x32_bf16 v[128:131], v[170:173], v[234:237], v[128:131]
	v_mfma_f32_16x16x32_bf16 v[128:131], v[174:177], v[238:241], v[128:131]
	v_mfma_f32_16x16x32_bf16 v[132:135], v[178:181], v[234:237], v[132:135]
	v_mfma_f32_16x16x32_bf16 v[132:135], v[184:187], v[238:241], v[132:135]
	v_mfma_f32_16x16x32_bf16 v[116:119], v[178:181], v[204:207], v[116:119]
	v_mfma_f32_16x16x32_bf16 v[116:119], v[184:187], v[230:233], v[116:119]
	v_mfma_f32_16x16x32_bf16 v[76:79], v[178:181], v[196:199], v[76:79]
	v_mfma_f32_16x16x32_bf16 v[76:79], v[184:187], v[200:203], v[76:79]
	v_mfma_f32_16x16x32_bf16 v[28:31], v[178:181], v[188:191], v[28:31]
	v_mfma_f32_16x16x32_bf16 v[28:31], v[184:187], v[192:195], v[28:31]
	s_setprio 0
	s_barrier
	s_add_i32 s85, s19, s37
	v_lshl_add_u64 v[2:3], s[82:83], 0, v[140:141]
	s_mov_b32 m0, s85
	ds_read_b128 v[188:191], v152 offset:16384
	ds_read_b128 v[192:195], v152 offset:17408
	ds_read_b128 v[196:199], v152 offset:18432
	ds_read_b128 v[200:203], v152 offset:19456
	ds_read_b128 v[204:207], v152 offset:20480
	ds_read_b128 v[230:233], v152 offset:21504
	ds_read_b128 v[234:237], v152 offset:22528
	ds_read_b128 v[238:241], v152 offset:23552
	global_load_lds_dwordx4 v[2:3], off
	s_add_i32 m0, s85, 0x2000
	v_lshl_add_u64 v[208:209], s[82:83], 0, v[136:137]
	s_add_u32 s82, s82, s48
	s_addc_u32 s83, s83, s49
	s_add_i32 s84, s84, s37
	global_load_lds_dwordx4 v[208:209], off
	v_lshl_add_u64 v[216:217], s[82:83], 0, v[140:141]
	s_mov_b32 m0, s84
	v_lshl_add_u64 v[224:225], s[82:83], 0, v[136:137]
	global_load_lds_dwordx4 v[216:217], off
	s_add_i32 m0, s84, 0x2000
	v_lshl_add_u64 v[226:227], s[40:41], 0, v[142:143]
	global_load_lds_dwordx4 v[224:225], off
	s_mov_b32 m0, s46
	v_lshl_add_u64 v[228:229], s[40:41], 0, v[138:139]
	global_load_lds_dwordx4 v[226:227], off
	s_mov_b32 m0, s47
	s_nop 0
	global_load_lds_dwordx4 v[228:229], off
	s_waitcnt vmcnt(8)
	s_waitcnt lgkmcnt(0)
	s_barrier
; #define PG8_STAGE(bufoff, gbase, voff) do { _Pragma("unroll") for (int _i = 0; _i < 2; ++_i) \
;         __builtin_amdgcn_global_load_lds((const unsigned*)((const char*)(gbase) + (voff)[_i]), (PG8_LAS unsigned*)(lds + (bufoff) + ldsw + _i * 8192), 16, 0, 0); } while (0)
; #define PG8_LDA(dst, b, h) do { _Pragma("unroll") for (int m = 0; m < 4; ++m) _Pragma("unroll") for (int k = 0; k < 2; ++k) dst[m][k] = *(const PG8_LAS bf16x8*)(lds + PG8_SA(b, h) + aoff + m * 2048 + k * 1024); } while (0)
; #define PG8_LDB(dst, b, h) do { _Pragma("unroll") for (int n = 0; n < 2; ++n) _Pragma("unroll") for (int k = 0; k < 2; ++k) dst[n][k] = *(const PG8_LAS bf16x8*)(lds + PG8_SB(b, h) + boff + n * 2048 + k * 1024); } while (0)
; #define PG8_MMA(ai, bj, At, Bt) do { __builtin_amdgcn_s_setprio(1); _Pragma("unroll") for (int m = 0; m < 4; ++m) _Pragma("unroll") for (int n = 0; n < 2; ++n) _Pragma("unroll") for (int k = 0; k < 2; ++k) \
;         acc[ai][bj][m][n] = __builtin_amdgcn_mfma_f32_16x16x32_bf16(Bt[n][k], At[m][k], acc[ai][bj][m][n], 0, 0, 0); __builtin_amdgcn_s_setprio(0); } while (0)
; #define PG8_WAIT_V(n) asm volatile("s_waitcnt vmcnt(" #n ")" ::: "memory")
; #define PG8_WAIT_L(n) asm volatile("s_waitcnt lgkmcnt(" #n ")" ::: "memory")
; #define PG8_BAR __builtin_amdgcn_s_barrier()
; #define PG8_SCHED __builtin_amdgcn_sched_barrier(0)
; template <class Epi, class Sched, bool ALIGN_EPI = false, bool SP2 = false>
; __device__ __forceinline__ void gemm_phase(PG8_LAS unsigned char* lds, const Gemm g, const Sched& S, const Epi& E) {
;     ...
;             PG8_WAIT_V(8); PG8_WAIT_L(0); PG8_BAR; PG8_MMA(1, 0, At, B0); PG8_MMA(1, 1, At, B1); PG8_BAR; PG8_SCHED;
;             PG8_LDB(B0, 1, 0); PG8_LDB(B1, 1, 1); PG8_SCHED; PG8_LDA(At, 1, 0); PG8_STAGE(PG8_SA(0, 1), a2 + hstep, voffA);
;             PG8_WAIT_V(8); PG8_WAIT_L(0); PG8_BAR; PG8_MMA(0, 0, At, B0); PG8_MMA(0, 1, At, B1); PG8_BAR; PG8_SCHED;
	s_setprio 1
	s_waitcnt lgkmcnt(0)
	v_mfma_f32_16x16x32_bf16 v[16:19], v[154:157], v[188:191], v[16:19]
	v_mfma_f32_16x16x32_bf16 v[16:19], v[158:161], v[192:195], v[16:19]
	v_mfma_f32_16x16x32_bf16 v[56:59], v[154:157], v[196:199], v[56:59]
	v_mfma_f32_16x16x32_bf16 v[56:59], v[158:161], v[200:203], v[56:59]
	v_mfma_f32_16x16x32_bf16 v[104:107], v[154:157], v[204:207], v[104:107]
	v_mfma_f32_16x16x32_bf16 v[104:107], v[158:161], v[230:233], v[104:107]
	v_mfma_f32_16x16x32_bf16 v[68:71], v[154:157], v[234:237], v[68:71]
	v_mfma_f32_16x16x32_bf16 v[68:71], v[158:161], v[238:241], v[68:71]
	v_mfma_f32_16x16x32_bf16 v[64:67], v[162:165], v[234:237], v[64:67]
	v_mfma_f32_16x16x32_bf16 v[64:67], v[166:169], v[238:241], v[64:67]
	v_mfma_f32_16x16x32_bf16 v[108:111], v[162:165], v[204:207], v[108:111]
	v_mfma_f32_16x16x32_bf16 v[108:111], v[166:169], v[230:233], v[108:111]
	v_mfma_f32_16x16x32_bf16 v[60:63], v[162:165], v[196:199], v[60:63]
	v_mfma_f32_16x16x32_bf16 v[60:63], v[166:169], v[200:203], v[60:63]
	v_mfma_f32_16x16x32_bf16 v[20:23], v[162:165], v[188:191], v[20:23]
	v_mfma_f32_16x16x32_bf16 v[20:23], v[166:169], v[192:195], v[20:23]
	v_mfma_f32_16x16x32_bf16 v[40:43], v[170:173], v[188:191], v[40:43]
	v_mfma_f32_16x16x32_bf16 v[40:43], v[174:177], v[192:195], v[40:43]
	v_mfma_f32_16x16x32_bf16 v[88:91], v[170:173], v[196:199], v[88:91]
	v_mfma_f32_16x16x32_bf16 v[88:91], v[174:177], v[200:203], v[88:91]
	v_mfma_f32_16x16x32_bf16 v[84:87], v[170:173], v[204:207], v[84:87]
	v_mfma_f32_16x16x32_bf16 v[84:87], v[174:177], v[230:233], v[84:87]
	v_mfma_f32_16x16x32_bf16 v[36:39], v[170:173], v[234:237], v[36:39]
	v_mfma_f32_16x16x32_bf16 v[36:39], v[174:177], v[238:241], v[36:39]
	v_mfma_f32_16x16x32_bf16 v[32:35], v[178:181], v[234:237], v[32:35]
	v_mfma_f32_16x16x32_bf16 v[32:35], v[184:187], v[238:241], v[32:35]
	v_mfma_f32_16x16x32_bf16 v[80:83], v[178:181], v[204:207], v[80:83]
	v_mfma_f32_16x16x32_bf16 v[80:83], v[184:187], v[230:233], v[80:83]
	v_mfma_f32_16x16x32_bf16 v[92:95], v[178:181], v[196:199], v[92:95]
	v_mfma_f32_16x16x32_bf16 v[92:95], v[184:187], v[200:203], v[92:95]
	v_mfma_f32_16x16x32_bf16 v[44:47], v[178:181], v[188:191], v[44:47]
	v_mfma_f32_16x16x32_bf16 v[44:47], v[184:187], v[192:195], v[44:47]
	s_setprio 0
	s_barrier
	v_add_u32_e32 v0, s91, v151
	s_add_i32 s82, 0, 0x1c000
	ds_read_b128 v[154:157], v0
	ds_read_b128 v[158:161], v0 offset:1024
	ds_read_b128 v[162:165], v0 offset:2048
	ds_read_b128 v[166:169], v0 offset:3072
	v_add_u32_e32 v0, s82, v151
	ds_read_b128 v[170:173], v0
	ds_read_b128 v[174:177], v0 offset:1024
	ds_read_b128 v[178:181], v0 offset:2048
	ds_read_b128 v[184:187], v0 offset:3072
	s_add_u32 s40, s40, s48
	s_addc_u32 s41, s41, s49
	s_mov_b32 m0, s52
	v_lshl_add_u64 v[242:243], s[40:41], 0, v[142:143]
	ds_read_b128 v[188:191], v152 offset:32768
	ds_read_b128 v[192:195], v152 offset:33792
	ds_read_b128 v[196:199], v152 offset:34816
	ds_read_b128 v[200:203], v152 offset:35840
	ds_read_b128 v[204:207], v152 offset:36864
	ds_read_b128 v[230:233], v152 offset:37888
	ds_read_b128 v[234:237], v152 offset:38912
	ds_read_b128 v[238:241], v152 offset:39936
	global_load_lds_dwordx4 v[242:243], off
	v_lshl_add_u64 v[242:243], s[40:41], 0, v[138:139]
	s_mov_b32 m0, s53
	s_nop 0
	global_load_lds_dwordx4 v[242:243], off
	s_waitcnt vmcnt(8)
	s_waitcnt lgkmcnt(0)
	s_barrier
	s_setprio 1
	s_waitcnt lgkmcnt(0)
	v_mfma_f32_16x16x32_bf16 v[8:11], v[154:157], v[188:191], v[8:11]
	v_mfma_f32_16x16x32_bf16 v[8:11], v[158:161], v[192:195], v[8:11]
	v_mfma_f32_16x16x32_bf16 v[48:51], v[154:157], v[196:199], v[48:51]
	v_mfma_f32_16x16x32_bf16 v[48:51], v[158:161], v[200:203], v[48:51]
	v_mfma_f32_16x16x32_bf16 v[96:99], v[154:157], v[204:207], v[96:99]
	v_mfma_f32_16x16x32_bf16 v[96:99], v[158:161], v[230:233], v[96:99]
	v_mfma_f32_16x16x32_bf16 v[120:123], v[154:157], v[234:237], v[120:123]
	v_mfma_f32_16x16x32_bf16 v[120:123], v[158:161], v[238:241], v[120:123]
	v_mfma_f32_16x16x32_bf16 v[124:127], v[162:165], v[234:237], v[124:127]
	v_mfma_f32_16x16x32_bf16 v[124:127], v[166:169], v[238:241], v[124:127]
	v_mfma_f32_16x16x32_bf16 v[100:103], v[162:165], v[204:207], v[100:103]
	v_mfma_f32_16x16x32_bf16 v[100:103], v[166:169], v[230:233], v[100:103]
	v_mfma_f32_16x16x32_bf16 v[52:55], v[162:165], v[196:199], v[52:55]
	v_mfma_f32_16x16x32_bf16 v[52:55], v[166:169], v[200:203], v[52:55]
	v_mfma_f32_16x16x32_bf16 v[12:15], v[162:165], v[188:191], v[12:15]
	v_mfma_f32_16x16x32_bf16 v[12:15], v[166:169], v[192:195], v[12:15]
	v_mfma_f32_16x16x32_bf16 v[24:27], v[170:173], v[188:191], v[24:27]
	v_mfma_f32_16x16x32_bf16 v[24:27], v[174:177], v[192:195], v[24:27]
	v_mfma_f32_16x16x32_bf16 v[72:75], v[170:173], v[196:199], v[72:75]
	v_mfma_f32_16x16x32_bf16 v[72:75], v[174:177], v[200:203], v[72:75]
	v_mfma_f32_16x16x32_bf16 v[112:115], v[170:173], v[204:207], v[112:115]
	v_mfma_f32_16x16x32_bf16 v[112:115], v[174:177], v[230:233], v[112:115]
	v_mfma_f32_16x16x32_bf16 v[128:131], v[170:173], v[234:237], v[128:131]
	v_mfma_f32_16x16x32_bf16 v[128:131], v[174:177], v[238:241], v[128:131]
	v_mfma_f32_16x16x32_bf16 v[132:135], v[178:181], v[234:237], v[132:135]
	v_mfma_f32_16x16x32_bf16 v[132:135], v[184:187], v[238:241], v[132:135]
	v_mfma_f32_16x16x32_bf16 v[116:119], v[178:181], v[204:207], v[116:119]
	v_mfma_f32_16x16x32_bf16 v[116:119], v[184:187], v[230:233], v[116:119]
	v_mfma_f32_16x16x32_bf16 v[76:79], v[178:181], v[196:199], v[76:79]
	v_mfma_f32_16x16x32_bf16 v[76:79], v[184:187], v[200:203], v[76:79]
	v_mfma_f32_16x16x32_bf16 v[28:31], v[178:181], v[188:191], v[28:31]
	v_mfma_f32_16x16x32_bf16 v[28:31], v[184:187], v[192:195], v[28:31]
	s_setprio 0
	s_barrier
; #define PG8_STAGE(bufoff, gbase, voff) do { _Pragma("unroll") for (int _i = 0; _i < 2; ++_i) \
;         __builtin_amdgcn_global_load_lds((const unsigned*)((const char*)(gbase) + (voff)[_i]), (PG8_LAS unsigned*)(lds + (bufoff) + ldsw + _i * 8192), 16, 0, 0); } while (0)
; #define PG8_LDA(dst, b, h) do { _Pragma("unroll") for (int m = 0; m < 4; ++m) _Pragma("unroll") for (int k = 0; k < 2; ++k) dst[m][k] = *(const PG8_LAS bf16x8*)(lds + PG8_SA(b, h) + aoff + m * 2048 + k * 1024); } while (0)
; #define PG8_MMA(ai, bj, At, Bt) do { __builtin_amdgcn_s_setprio(1); _Pragma("unroll") for (int m = 0; m < 4; ++m) _Pragma("unroll") for (int n = 0; n < 2; ++n) _Pragma("unroll") for (int k = 0; k < 2; ++k) \
;         acc[ai][bj][m][n] = __builtin_amdgcn_mfma_f32_16x16x32_bf16(Bt[n][k], At[m][k], acc[ai][bj][m][n], 0, 0, 0); __builtin_amdgcn_s_setprio(0); } while (0)
; #define PG8_WAIT_V(n) asm volatile("s_waitcnt vmcnt(" #n ")" ::: "memory")
; #define PG8_WAIT_L(n) asm volatile("s_waitcnt lgkmcnt(" #n ")" ::: "memory")
; #define PG8_BAR __builtin_amdgcn_s_barrier()
; #define PG8_SCHED __builtin_amdgcn_sched_barrier(0)
; template <class Epi, class Sched, bool ALIGN_EPI = false, bool SP2 = false>
; __device__ __forceinline__ void gemm_phase(PG8_LAS unsigned char* lds, const Gemm g, const Sched& S, const Epi& E) {
;     ...
;         for (int t = 0; t < nt; t += 2) {
;     ...
;             PG8_LDA(At, 1, 1); PG8_STAGE(PG8_SB(1, 0), b3, voffB); PG8_STAGE(PG8_SB(1, 1), b3 + hstep, voffB); PG8_STAGE(PG8_SA(1, 0), a3, voffA);
;             PG8_WAIT_V(8); PG8_WAIT_L(0); PG8_BAR; PG8_MMA(1, 0, At, B0); PG8_MMA(1, 1, At, B1); PG8_BAR; PG8_SCHED;
	s_add_i32 s40, s91, s37
	v_lshl_add_u64 v[2:3], v[2:3], 0, s[24:25]
	s_mov_b32 m0, s40
	ds_read_b128 v[188:191], v152 offset:49152
	ds_read_b128 v[192:195], v152 offset:50176
	ds_read_b128 v[196:199], v152 offset:51200
	ds_read_b128 v[200:203], v152 offset:52224
	ds_read_b128 v[204:207], v152 offset:53248
	ds_read_b128 v[230:233], v152 offset:54272
	ds_read_b128 v[234:237], v152 offset:55296
	ds_read_b128 v[238:241], v152 offset:56320
	global_load_lds_dwordx4 v[2:3], off
	v_lshl_add_u64 v[2:3], v[208:209], 0, s[24:25]
	s_add_i32 m0, s40, 0x2000
	s_add_i32 s40, s82, s37
	global_load_lds_dwordx4 v[2:3], off
	v_lshl_add_u64 v[2:3], v[216:217], 0, s[24:25]
	s_mov_b32 m0, s40
	s_nop 0
	global_load_lds_dwordx4 v[2:3], off
	v_lshl_add_u64 v[2:3], v[224:225], 0, s[24:25]
	s_add_i32 m0, s40, 0x2000
	s_nop 0
	global_load_lds_dwordx4 v[2:3], off
	v_lshl_add_u64 v[2:3], v[226:227], 0, s[24:25]
	s_mov_b32 m0, s73
	s_nop 0
	global_load_lds_dwordx4 v[2:3], off
	v_lshl_add_u64 v[2:3], v[228:229], 0, s[24:25]
	s_mov_b32 m0, s74
	s_nop 0
	global_load_lds_dwordx4 v[2:3], off
	s_waitcnt vmcnt(8)
	s_waitcnt lgkmcnt(0)
	s_barrier
	s_setprio 1
	s_waitcnt lgkmcnt(0)
	v_mfma_f32_16x16x32_bf16 v[16:19], v[154:157], v[188:191], v[16:19]
	v_mfma_f32_16x16x32_bf16 v[16:19], v[158:161], v[192:195], v[16:19]
	v_mfma_f32_16x16x32_bf16 v[56:59], v[154:157], v[196:199], v[56:59]
	v_mfma_f32_16x16x32_bf16 v[56:59], v[158:161], v[200:203], v[56:59]
	v_mfma_f32_16x16x32_bf16 v[104:107], v[154:157], v[204:207], v[104:107]
	v_mfma_f32_16x16x32_bf16 v[104:107], v[158:161], v[230:233], v[104:107]
	v_mfma_f32_16x16x32_bf16 v[68:71], v[154:157], v[234:237], v[68:71]
	v_mfma_f32_16x16x32_bf16 v[68:71], v[158:161], v[238:241], v[68:71]
	v_mfma_f32_16x16x32_bf16 v[64:67], v[162:165], v[234:237], v[64:67]
	v_mfma_f32_16x16x32_bf16 v[64:67], v[166:169], v[238:241], v[64:67]
	v_mfma_f32_16x16x32_bf16 v[108:111], v[162:165], v[204:207], v[108:111]
	v_mfma_f32_16x16x32_bf16 v[108:111], v[166:169], v[230:233], v[108:111]
	v_mfma_f32_16x16x32_bf16 v[60:63], v[162:165], v[196:199], v[60:63]
	v_mfma_f32_16x16x32_bf16 v[60:63], v[166:169], v[200:203], v[60:63]
	v_mfma_f32_16x16x32_bf16 v[20:23], v[162:165], v[188:191], v[20:23]
	v_mfma_f32_16x16x32_bf16 v[20:23], v[166:169], v[192:195], v[20:23]
	v_mfma_f32_16x16x32_bf16 v[40:43], v[170:173], v[188:191], v[40:43]
	v_mfma_f32_16x16x32_bf16 v[40:43], v[174:177], v[192:195], v[40:43]
	v_mfma_f32_16x16x32_bf16 v[88:91], v[170:173], v[196:199], v[88:91]
	v_mfma_f32_16x16x32_bf16 v[88:91], v[174:177], v[200:203], v[88:91]
	v_mfma_f32_16x16x32_bf16 v[84:87], v[170:173], v[204:207], v[84:87]
	v_mfma_f32_16x16x32_bf16 v[84:87], v[174:177], v[230:233], v[84:87]
	v_mfma_f32_16x16x32_bf16 v[36:39], v[170:173], v[234:237], v[36:39]
	v_mfma_f32_16x16x32_bf16 v[36:39], v[174:177], v[238:241], v[36:39]
	v_mfma_f32_16x16x32_bf16 v[32:35], v[178:181], v[234:237], v[32:35]
	v_mfma_f32_16x16x32_bf16 v[32:35], v[184:187], v[238:241], v[32:35]
	v_mfma_f32_16x16x32_bf16 v[80:83], v[178:181], v[204:207], v[80:83]
	v_mfma_f32_16x16x32_bf16 v[80:83], v[184:187], v[230:233], v[80:83]
	v_mfma_f32_16x16x32_bf16 v[92:95], v[178:181], v[196:199], v[92:95]
	v_mfma_f32_16x16x32_bf16 v[92:95], v[184:187], v[200:203], v[92:95]
	v_mfma_f32_16x16x32_bf16 v[44:47], v[178:181], v[188:191], v[44:47]
	v_mfma_f32_16x16x32_bf16 v[44:47], v[184:187], v[192:195], v[44:47]
	s_setprio 0
	s_barrier
	s_add_u32 s38, s38, 0x100
	s_addc_u32 s39, s39, 0
	s_add_u32 s79, s79, 0x100
	s_addc_u32 s80, s80, 0
	s_cmp_ge_u32 s81, s9
	s_mov_b32 s40, s81
	s_cbranch_scc0 .LBB0_294

; #define PG8_STAGE(bufoff, gbase, voff) do { _Pragma("unroll") for (int _i = 0; _i < 2; ++_i) \
;         __builtin_amdgcn_global_load_lds((const unsigned*)((const char*)(gbase) + (voff)[_i]), (PG8_LAS unsigned*)(lds + (bufoff) + ldsw + _i * 8192), 16, 0, 0); } while (0)
; #define PG8_LDA(dst, b, h) do { _Pragma("unroll") for (int m = 0; m < 4; ++m) _Pragma("unroll") for (int k = 0; k < 2; ++k) dst[m][k] = *(const PG8_LAS bf16x8*)(lds + PG8_SA(b, h) + aoff + m * 2048 + k * 1024); } while (0)
; #define PG8_LDB(dst, b, h) do { _Pragma("unroll") for (int n = 0; n < 2; ++n) _Pragma("unroll") for (int k = 0; k < 2; ++k) dst[n][k] = *(const PG8_LAS bf16x8*)(lds + PG8_SB(b, h) + boff + n * 2048 + k * 1024); } while (0)
; #define PG8_WAIT_V(n) asm volatile("s_waitcnt vmcnt(" #n ")" ::: "memory")
; #define PG8_WAIT_L(n) asm volatile("s_waitcnt lgkmcnt(" #n ")" ::: "memory")
; template <class Epi, class Sched, bool ALIGN_EPI = false, bool SP2 = false>
; __device__ __forceinline__ void gemm_phase(PG8_LAS unsigned char* lds, const Gemm g, const Sched& S, const Epi& E) {
;     ...
;         const bool has_next = S.next(ui + 1, nxt);
;         const char* nA = has_next ? (const char*)g.A + (size_t)nxt.pm * tstepA : cA; const char* nB = has_next ? (const char*)g.Bt + (size_t)nxt.pn * tstep : cB;
;         for (int t = 0; t < nt; t += 2) {
;             if constexpr (Epi::KHOOK) { if ((t & 7) == 0 && t != 0) E.khook(acc, t >> 3, wr, fr, lds); }
;             const bool last = (t == nt - 2);
;             const char* a1 = cA + (size_t)(t + 1) * kstep;
;             const char* a2 = last ? nA : cA + (size_t)(t + 2) * kstep; const char* b2 = last ? nB : cB + (size_t)(t + 2) * kstep;
;             const char* a3 = a2 + kstep; const char* b3 = b2 + kstep;
;             if (last && has_next) S.a_ready(nxt);
;             if constexpr (SP2) {
;             PG8_LDB(B0, 0, 0); PG8_LDB(B1, 0, 1); PG8_SCHED; PG8_LDA(At, 0, 0); PG8_STAGE(PG8_SA(1, 1), a1 + hstep, voffA);
;             PG8_WAIT_V(8); PG8_WAIT_L(0); PG8_BAR; PG8_MMA(0, 0, At, B0); PG8_MMA(0, 1, At, B1); PG8_BAR; PG8_SCHED;
;             PG8_LDA(At, 0, 1); PG8_STAGE(PG8_SB(0, 0), b2, voffB); PG8_STAGE(PG8_SB(0, 1), b2 + hstep, voffB); PG8_STAGE(PG8_SA(0, 0), a2, voffA);
;             PG8_WAIT_V(8); PG8_WAIT_L(0); PG8_BAR; PG8_MMA(1, 0, At, B0); PG8_MMA(1, 1, At, B1); PG8_BAR; PG8_SCHED;
.LBB0_365:
	s_add_i32 s88, s86, 2
	s_add_u32 s89, s0, 0x80
	s_addc_u32 s87, s1, 0
	s_cmp_eq_u32 s33, s86
	s_cselect_b32 s87, s3, s87
	s_cselect_b32 s86, s2, s89
	v_add_u32_e32 v0, s19, v230
	s_cselect_b32 vcc_hi, s85, s73
	s_cselect_b32 vcc_lo, s84, s72
	s_add_i32 s89, 0, 0x14000
	ds_read_b128 v[120:123], v0
	ds_read_b128 v[124:127], v0 offset:1024
	ds_read_b128 v[128:131], v0 offset:2048
	ds_read_b128 v[132:135], v0 offset:3072
	v_add_u32_e32 v0, s89, v230
	ds_read_b128 v[136:139], v0
	ds_read_b128 v[140:143], v0 offset:1024
	ds_read_b128 v[162:165], v0 offset:2048
	ds_read_b128 v[166:169], v0 offset:3072
	v_lshl_add_u64 v[144:145], s[0:1], 0, v[184:185]
	s_add_i32 m0, s93, 0xc000
	ds_read_b128 v[170:173], v238
	ds_read_b128 v[188:191], v238 offset:1024
	ds_read_b128 v[192:195], v238 offset:2048
	ds_read_b128 v[196:199], v238 offset:3072
	ds_read_b128 v[200:203], v238 offset:4096
	ds_read_b128 v[204:207], v238 offset:5120
	ds_read_b128 v[242:245], v238 offset:6144
	ds_read_b128 v[246:249], v238 offset:7168
	global_load_lds_dwordx4 v[144:145], off
	v_lshl_add_u64 v[144:145], s[0:1], 0, v[186:187]
	s_add_i32 m0, s93, 0xe000
	s_nop 0
	global_load_lds_dwordx4 v[144:145], off
	s_waitcnt vmcnt(8)
	s_waitcnt lgkmcnt(0)
	s_barrier
	s_setprio 1
	s_waitcnt lgkmcnt(0)
	v_mfma_f32_16x16x32_bf16 v[158:161], v[120:123], v[170:173], v[158:161]
	v_mfma_f32_16x16x32_bf16 v[158:161], v[124:127], v[188:191], v[158:161]
	v_mfma_f32_16x16x32_bf16 v[150:153], v[120:123], v[192:195], v[150:153]
	v_mfma_f32_16x16x32_bf16 v[150:153], v[124:127], v[196:199], v[150:153]
	v_mfma_f32_16x16x32_bf16 v[100:103], v[120:123], v[200:203], v[100:103]
	v_mfma_f32_16x16x32_bf16 v[100:103], v[124:127], v[204:207], v[100:103]
	v_mfma_f32_16x16x32_bf16 v[116:119], v[120:123], v[242:245], v[116:119]
	v_mfma_f32_16x16x32_bf16 v[116:119], v[124:127], v[246:249], v[116:119]
	v_mfma_f32_16x16x32_bf16 v[68:71], v[128:131], v[242:245], v[68:71]
	v_mfma_f32_16x16x32_bf16 v[68:71], v[132:135], v[246:249], v[68:71]
	v_mfma_f32_16x16x32_bf16 v[36:39], v[128:131], v[200:203], v[36:39]
	v_mfma_f32_16x16x32_bf16 v[36:39], v[132:135], v[204:207], v[36:39]
	v_mfma_f32_16x16x32_bf16 v[52:55], v[128:131], v[192:195], v[52:55]
	v_mfma_f32_16x16x32_bf16 v[52:55], v[132:135], v[196:199], v[52:55]
	v_mfma_f32_16x16x32_bf16 v[60:63], v[128:131], v[170:173], v[60:63]
	v_mfma_f32_16x16x32_bf16 v[60:63], v[132:135], v[188:191], v[60:63]
	v_mfma_f32_16x16x32_bf16 v[154:157], v[136:139], v[170:173], v[154:157]
	v_mfma_f32_16x16x32_bf16 v[154:157], v[140:143], v[188:191], v[154:157]
	v_mfma_f32_16x16x32_bf16 v[144:147], v[136:139], v[192:195], v[146:149]
	v_mfma_f32_16x16x32_bf16 v[144:147], v[140:143], v[196:199], v[144:147]
	v_mfma_f32_16x16x32_bf16 v[96:99], v[136:139], v[200:203], v[96:99]
	v_mfma_f32_16x16x32_bf16 v[96:99], v[140:143], v[204:207], v[96:99]
	v_mfma_f32_16x16x32_bf16 v[112:115], v[136:139], v[242:245], v[112:115]
	v_mfma_f32_16x16x32_bf16 v[112:115], v[140:143], v[246:249], v[112:115]
	v_mfma_f32_16x16x32_bf16 v[64:67], v[162:165], v[242:245], v[64:67]
	v_mfma_f32_16x16x32_bf16 v[64:67], v[166:169], v[246:249], v[64:67]
	v_mfma_f32_16x16x32_bf16 v[32:35], v[162:165], v[200:203], v[32:35]
	v_mfma_f32_16x16x32_bf16 v[32:35], v[166:169], v[204:207], v[32:35]
	v_mfma_f32_16x16x32_bf16 v[48:51], v[162:165], v[192:195], v[48:51]
	v_mfma_f32_16x16x32_bf16 v[48:51], v[166:169], v[196:199], v[48:51]
	v_mfma_f32_16x16x32_bf16 v[56:59], v[162:165], v[170:173], v[56:59]
	v_mfma_f32_16x16x32_bf16 v[56:59], v[166:169], v[188:191], v[56:59]
	s_setprio 0
	s_barrier
	s_add_i32 s38, s19, s92
	v_lshl_add_u64 v[174:175], vcc, 0, v[176:177]
	s_mov_b32 m0, s38
	ds_read_b128 v[170:173], v238 offset:16384
	ds_read_b128 v[188:191], v238 offset:17408
	ds_read_b128 v[192:195], v238 offset:18432
	ds_read_b128 v[196:199], v238 offset:19456
	ds_read_b128 v[200:203], v238 offset:20480
	ds_read_b128 v[204:207], v238 offset:21504
	ds_read_b128 v[242:245], v238 offset:22528
	ds_read_b128 v[246:249], v238 offset:23552
	global_load_lds_dwordx4 v[174:175], off
	s_add_i32 m0, s38, 0x2000
	v_lshl_add_u64 v[208:209], vcc, 0, v[180:181]
	s_add_u32 vcc_lo, vcc_lo, s48
	s_addc_u32 vcc_hi, vcc_hi, s49
	s_add_i32 s38, s89, s92
	global_load_lds_dwordx4 v[208:209], off
	v_lshl_add_u64 v[216:217], vcc, 0, v[176:177]
	s_mov_b32 m0, s38
	v_lshl_add_u64 v[224:225], vcc, 0, v[180:181]
	global_load_lds_dwordx4 v[216:217], off
	s_add_i32 m0, s38, 0x2000
	v_lshl_add_u64 v[226:227], s[86:87], 0, v[2:3]
	global_load_lds_dwordx4 v[224:225], off
	s_mov_b32 m0, s93
	v_lshl_add_u64 v[228:229], s[86:87], 0, v[178:179]
	global_load_lds_dwordx4 v[226:227], off
	s_mov_b32 m0, s94
	s_nop 0
	global_load_lds_dwordx4 v[228:229], off
	s_waitcnt vmcnt(8)
	s_waitcnt lgkmcnt(0)
	s_barrier
; #define PG8_STAGE(bufoff, gbase, voff) do { _Pragma("unroll") for (int _i = 0; _i < 2; ++_i) \
;         __builtin_amdgcn_global_load_lds((const unsigned*)((const char*)(gbase) + (voff)[_i]), (PG8_LAS unsigned*)(lds + (bufoff) + ldsw + _i * 8192), 16, 0, 0); } while (0)
; #define PG8_LDA(dst, b, h) do { _Pragma("unroll") for (int m = 0; m < 4; ++m) _Pragma("unroll") for (int k = 0; k < 2; ++k) dst[m][k] = *(const PG8_LAS bf16x8*)(lds + PG8_SA(b, h) + aoff + m * 2048 + k * 1024); } while (0)
; #define PG8_LDB(dst, b, h) do { _Pragma("unroll") for (int n = 0; n < 2; ++n) _Pragma("unroll") for (int k = 0; k < 2; ++k) dst[n][k] = *(const PG8_LAS bf16x8*)(lds + PG8_SB(b, h) + boff + n * 2048 + k * 1024); } while (0)
; #define PG8_MMA(ai, bj, At, Bt) do { __builtin_amdgcn_s_setprio(1); _Pragma("unroll") for (int m = 0; m < 4; ++m) _Pragma("unroll") for (int n = 0; n < 2; ++n) _Pragma("unroll") for (int k = 0; k < 2; ++k) \
;         acc[ai][bj][m][n] = __builtin_amdgcn_mfma_f32_16x16x32_bf16(Bt[n][k], At[m][k], acc[ai][bj][m][n], 0, 0, 0); __builtin_amdgcn_s_setprio(0); } while (0)
; #define PG8_WAIT_V(n) asm volatile("s_waitcnt vmcnt(" #n ")" ::: "memory")
; #define PG8_WAIT_L(n) asm volatile("s_waitcnt lgkmcnt(" #n ")" ::: "memory")
; #define PG8_BAR __builtin_amdgcn_s_barrier()
; #define PG8_SCHED __builtin_amdgcn_sched_barrier(0)
; template <class Epi, class Sched, bool ALIGN_EPI = false, bool SP2 = false>
; __device__ __forceinline__ void gemm_phase(PG8_LAS unsigned char* lds, const Gemm g, const Sched& S, const Epi& E) {
;     ...
;             PG8_WAIT_V(8); PG8_WAIT_L(0); PG8_BAR; PG8_MMA(1, 0, At, B0); PG8_MMA(1, 1, At, B1); PG8_BAR; PG8_SCHED;
;             PG8_LDB(B0, 1, 0); PG8_LDB(B1, 1, 1); PG8_SCHED; PG8_LDA(At, 1, 0); PG8_STAGE(PG8_SA(0, 1), a2 + hstep, voffA);
;             PG8_WAIT_V(8); PG8_WAIT_L(0); PG8_BAR; PG8_MMA(0, 0, At, B0); PG8_MMA(0, 1, At, B1); PG8_BAR; PG8_SCHED;
	s_setprio 1
	s_waitcnt lgkmcnt(0)
	v_mfma_f32_16x16x32_bf16 v[92:95], v[120:123], v[170:173], v[92:95]
	v_mfma_f32_16x16x32_bf16 v[92:95], v[124:127], v[188:191], v[92:95]
	v_mfma_f32_16x16x32_bf16 v[84:87], v[120:123], v[192:195], v[84:87]
	v_mfma_f32_16x16x32_bf16 v[84:87], v[124:127], v[196:199], v[84:87]
	v_mfma_f32_16x16x32_bf16 v[76:79], v[120:123], v[200:203], v[76:79]
	v_mfma_f32_16x16x32_bf16 v[76:79], v[124:127], v[204:207], v[76:79]
	v_mfma_f32_16x16x32_bf16 v[108:111], v[120:123], v[242:245], v[108:111]
	v_mfma_f32_16x16x32_bf16 v[108:111], v[124:127], v[246:249], v[108:111]
	v_mfma_f32_16x16x32_bf16 v[44:47], v[128:131], v[242:245], v[44:47]
	v_mfma_f32_16x16x32_bf16 v[44:47], v[132:135], v[246:249], v[44:47]
	v_mfma_f32_16x16x32_bf16 v[12:15], v[128:131], v[200:203], v[12:15]
	v_mfma_f32_16x16x32_bf16 v[12:15], v[132:135], v[204:207], v[12:15]
	v_mfma_f32_16x16x32_bf16 v[20:23], v[128:131], v[192:195], v[20:23]
	v_mfma_f32_16x16x32_bf16 v[20:23], v[132:135], v[196:199], v[20:23]
	v_mfma_f32_16x16x32_bf16 v[28:31], v[128:131], v[170:173], v[28:31]
	v_mfma_f32_16x16x32_bf16 v[28:31], v[132:135], v[188:191], v[28:31]
	v_mfma_f32_16x16x32_bf16 v[88:91], v[136:139], v[170:173], v[88:91]
	v_mfma_f32_16x16x32_bf16 v[88:91], v[140:143], v[188:191], v[88:91]
	v_mfma_f32_16x16x32_bf16 v[80:83], v[136:139], v[192:195], v[80:83]
	v_mfma_f32_16x16x32_bf16 v[80:83], v[140:143], v[196:199], v[80:83]
	v_mfma_f32_16x16x32_bf16 v[72:75], v[136:139], v[200:203], v[72:75]
	v_mfma_f32_16x16x32_bf16 v[72:75], v[140:143], v[204:207], v[72:75]
	v_mfma_f32_16x16x32_bf16 v[104:107], v[136:139], v[242:245], v[104:107]
	v_mfma_f32_16x16x32_bf16 v[104:107], v[140:143], v[246:249], v[104:107]
	v_mfma_f32_16x16x32_bf16 v[40:43], v[162:165], v[242:245], v[40:43]
	v_mfma_f32_16x16x32_bf16 v[40:43], v[166:169], v[246:249], v[40:43]
	v_mfma_f32_16x16x32_bf16 v[8:11], v[162:165], v[200:203], v[8:11]
	v_mfma_f32_16x16x32_bf16 v[8:11], v[166:169], v[204:207], v[8:11]
	v_mfma_f32_16x16x32_bf16 v[16:19], v[162:165], v[192:195], v[16:19]
	v_mfma_f32_16x16x32_bf16 v[16:19], v[166:169], v[196:199], v[16:19]
	v_mfma_f32_16x16x32_bf16 v[24:27], v[162:165], v[170:173], v[24:27]
	v_mfma_f32_16x16x32_bf16 v[24:27], v[166:169], v[188:191], v[24:27]
	s_setprio 0
	s_barrier
	v_add_u32_e32 v0, s91, v230
	s_add_i32 s38, 0, 0x1c000
	ds_read_b128 v[120:123], v0
	ds_read_b128 v[124:127], v0 offset:1024
	ds_read_b128 v[128:131], v0 offset:2048
	ds_read_b128 v[132:135], v0 offset:3072
	v_add_u32_e32 v0, s38, v230
	ds_read_b128 v[136:139], v0
	ds_read_b128 v[140:143], v0 offset:1024
	ds_read_b128 v[162:165], v0 offset:2048
	ds_read_b128 v[166:169], v0 offset:3072
	s_add_u32 s86, s86, s48
	s_addc_u32 s87, s87, s49
	s_mov_b32 m0, s95
	v_lshl_add_u64 v[148:149], s[86:87], 0, v[2:3]
	ds_read_b128 v[170:173], v238 offset:32768
	ds_read_b128 v[188:191], v238 offset:33792
	ds_read_b128 v[192:195], v238 offset:34816
	ds_read_b128 v[196:199], v238 offset:35840
	ds_read_b128 v[200:203], v238 offset:36864
	ds_read_b128 v[204:207], v238 offset:37888
	ds_read_b128 v[242:245], v238 offset:38912
	ds_read_b128 v[246:249], v238 offset:39936
	global_load_lds_dwordx4 v[148:149], off
	v_lshl_add_u64 v[148:149], s[86:87], 0, v[178:179]
	s_mov_b32 m0, s96
	s_nop 0
	global_load_lds_dwordx4 v[148:149], off
	s_waitcnt vmcnt(8)
	s_waitcnt lgkmcnt(0)
	s_barrier
	s_setprio 1
	s_waitcnt lgkmcnt(0)
	v_mfma_f32_16x16x32_bf16 v[158:161], v[120:123], v[170:173], v[158:161]
	v_mfma_f32_16x16x32_bf16 v[158:161], v[124:127], v[188:191], v[158:161]
	v_mfma_f32_16x16x32_bf16 v[148:151], v[120:123], v[192:195], v[150:153]
	v_mfma_f32_16x16x32_bf16 v[150:153], v[124:127], v[196:199], v[148:151]
	v_mfma_f32_16x16x32_bf16 v[100:103], v[120:123], v[200:203], v[100:103]
	v_mfma_f32_16x16x32_bf16 v[100:103], v[124:127], v[204:207], v[100:103]
	v_mfma_f32_16x16x32_bf16 v[116:119], v[120:123], v[242:245], v[116:119]
	v_mfma_f32_16x16x32_bf16 v[116:119], v[124:127], v[246:249], v[116:119]
	v_mfma_f32_16x16x32_bf16 v[68:71], v[128:131], v[242:245], v[68:71]
	v_mfma_f32_16x16x32_bf16 v[68:71], v[132:135], v[246:249], v[68:71]
	v_mfma_f32_16x16x32_bf16 v[36:39], v[128:131], v[200:203], v[36:39]
	v_mfma_f32_16x16x32_bf16 v[36:39], v[132:135], v[204:207], v[36:39]
	v_mfma_f32_16x16x32_bf16 v[52:55], v[128:131], v[192:195], v[52:55]
	v_mfma_f32_16x16x32_bf16 v[52:55], v[132:135], v[196:199], v[52:55]
	v_mfma_f32_16x16x32_bf16 v[60:63], v[128:131], v[170:173], v[60:63]
	v_mfma_f32_16x16x32_bf16 v[60:63], v[132:135], v[188:191], v[60:63]
	v_mfma_f32_16x16x32_bf16 v[154:157], v[136:139], v[170:173], v[154:157]
	v_mfma_f32_16x16x32_bf16 v[154:157], v[140:143], v[188:191], v[154:157]
	v_mfma_f32_16x16x32_bf16 v[144:147], v[136:139], v[192:195], v[144:147]
	v_mfma_f32_16x16x32_bf16 v[146:149], v[140:143], v[196:199], v[144:147]
	v_mfma_f32_16x16x32_bf16 v[96:99], v[136:139], v[200:203], v[96:99]
	v_mfma_f32_16x16x32_bf16 v[96:99], v[140:143], v[204:207], v[96:99]
	v_mfma_f32_16x16x32_bf16 v[112:115], v[136:139], v[242:245], v[112:115]
	v_mfma_f32_16x16x32_bf16 v[112:115], v[140:143], v[246:249], v[112:115]
	v_mfma_f32_16x16x32_bf16 v[64:67], v[162:165], v[242:245], v[64:67]
	v_mfma_f32_16x16x32_bf16 v[64:67], v[166:169], v[246:249], v[64:67]
	v_mfma_f32_16x16x32_bf16 v[32:35], v[162:165], v[200:203], v[32:35]
	v_mfma_f32_16x16x32_bf16 v[32:35], v[166:169], v[204:207], v[32:35]
	v_mfma_f32_16x16x32_bf16 v[48:51], v[162:165], v[192:195], v[48:51]
	v_mfma_f32_16x16x32_bf16 v[48:51], v[166:169], v[196:199], v[48:51]
	v_mfma_f32_16x16x32_bf16 v[56:59], v[162:165], v[170:173], v[56:59]
	v_mfma_f32_16x16x32_bf16 v[56:59], v[166:169], v[188:191], v[56:59]
	s_setprio 0
	s_barrier
; #define PG8_STAGE(bufoff, gbase, voff) do { _Pragma("unroll") for (int _i = 0; _i < 2; ++_i) \
;         __builtin_amdgcn_global_load_lds((const unsigned*)((const char*)(gbase) + (voff)[_i]), (PG8_LAS unsigned*)(lds + (bufoff) + ldsw + _i * 8192), 16, 0, 0); } while (0)
; #define PG8_LDA(dst, b, h) do { _Pragma("unroll") for (int m = 0; m < 4; ++m) _Pragma("unroll") for (int k = 0; k < 2; ++k) dst[m][k] = *(const PG8_LAS bf16x8*)(lds + PG8_SA(b, h) + aoff + m * 2048 + k * 1024); } while (0)
; #define PG8_MMA(ai, bj, At, Bt) do { __builtin_amdgcn_s_setprio(1); _Pragma("unroll") for (int m = 0; m < 4; ++m) _Pragma("unroll") for (int n = 0; n < 2; ++n) _Pragma("unroll") for (int k = 0; k < 2; ++k) \
;         acc[ai][bj][m][n] = __builtin_amdgcn_mfma_f32_16x16x32_bf16(Bt[n][k], At[m][k], acc[ai][bj][m][n], 0, 0, 0); __builtin_amdgcn_s_setprio(0); } while (0)
; #define PG8_WAIT_V(n) asm volatile("s_waitcnt vmcnt(" #n ")" ::: "memory")
; #define PG8_WAIT_L(n) asm volatile("s_waitcnt lgkmcnt(" #n ")" ::: "memory")
; #define PG8_BAR __builtin_amdgcn_s_barrier()
; #define PG8_SCHED __builtin_amdgcn_sched_barrier(0)
; template <class Epi, class Sched, bool ALIGN_EPI = false, bool SP2 = false>
; __device__ __forceinline__ void gemm_phase(PG8_LAS unsigned char* lds, const Gemm g, const Sched& S, const Epi& E) {
;     ...
;         for (int t = 0; t < nt; t += 2) {
;     ...
;             PG8_LDA(At, 1, 1); PG8_STAGE(PG8_SB(1, 0), b3, voffB); PG8_STAGE(PG8_SB(1, 1), b3 + hstep, voffB); PG8_STAGE(PG8_SA(1, 0), a3, voffA);
;             PG8_WAIT_V(8); PG8_WAIT_L(0); PG8_BAR; PG8_MMA(1, 0, At, B0); PG8_MMA(1, 1, At, B1); PG8_BAR; PG8_SCHED;
	s_add_i32 s39, s91, s92
	v_lshl_add_u64 v[144:145], v[174:175], 0, s[24:25]
	s_mov_b32 m0, s39
	ds_read_b128 v[170:173], v238 offset:49152
	ds_read_b128 v[188:191], v238 offset:50176
	ds_read_b128 v[192:195], v238 offset:51200
	ds_read_b128 v[196:199], v238 offset:52224
	ds_read_b128 v[200:203], v238 offset:53248
	ds_read_b128 v[204:207], v238 offset:54272
	ds_read_b128 v[242:245], v238 offset:55296
	ds_read_b128 v[246:249], v238 offset:56320
	global_load_lds_dwordx4 v[144:145], off
	v_lshl_add_u64 v[144:145], v[208:209], 0, s[24:25]
	s_add_i32 m0, s39, 0x2000
	s_add_i32 s38, s38, s92
	global_load_lds_dwordx4 v[144:145], off
	v_lshl_add_u64 v[144:145], v[216:217], 0, s[24:25]
	s_mov_b32 m0, s38
	s_nop 0
	global_load_lds_dwordx4 v[144:145], off
	v_lshl_add_u64 v[144:145], v[224:225], 0, s[24:25]
	s_add_i32 m0, s38, 0x2000
	s_nop 0
	global_load_lds_dwordx4 v[144:145], off
	v_lshl_add_u64 v[144:145], v[226:227], 0, s[24:25]
	s_mov_b32 m0, s10
	s_nop 0
	global_load_lds_dwordx4 v[144:145], off
	v_lshl_add_u64 v[144:145], v[228:229], 0, s[24:25]
	s_mov_b32 m0, s11
	s_nop 0
	global_load_lds_dwordx4 v[144:145], off
	s_waitcnt vmcnt(8)
	s_waitcnt lgkmcnt(0)
	s_barrier
	s_setprio 1
	s_waitcnt lgkmcnt(0)
	v_mfma_f32_16x16x32_bf16 v[92:95], v[120:123], v[170:173], v[92:95]
	v_mfma_f32_16x16x32_bf16 v[92:95], v[124:127], v[188:191], v[92:95]
	v_mfma_f32_16x16x32_bf16 v[84:87], v[120:123], v[192:195], v[84:87]
	v_mfma_f32_16x16x32_bf16 v[84:87], v[124:127], v[196:199], v[84:87]
	v_mfma_f32_16x16x32_bf16 v[76:79], v[120:123], v[200:203], v[76:79]
	v_mfma_f32_16x16x32_bf16 v[76:79], v[124:127], v[204:207], v[76:79]
	v_mfma_f32_16x16x32_bf16 v[108:111], v[120:123], v[242:245], v[108:111]
	v_mfma_f32_16x16x32_bf16 v[108:111], v[124:127], v[246:249], v[108:111]
	v_mfma_f32_16x16x32_bf16 v[44:47], v[128:131], v[242:245], v[44:47]
	v_mfma_f32_16x16x32_bf16 v[44:47], v[132:135], v[246:249], v[44:47]
	v_mfma_f32_16x16x32_bf16 v[12:15], v[128:131], v[200:203], v[12:15]
	v_mfma_f32_16x16x32_bf16 v[12:15], v[132:135], v[204:207], v[12:15]
	v_mfma_f32_16x16x32_bf16 v[20:23], v[128:131], v[192:195], v[20:23]
	v_mfma_f32_16x16x32_bf16 v[20:23], v[132:135], v[196:199], v[20:23]
	v_mfma_f32_16x16x32_bf16 v[28:31], v[128:131], v[170:173], v[28:31]
	v_mfma_f32_16x16x32_bf16 v[28:31], v[132:135], v[188:191], v[28:31]
	v_mfma_f32_16x16x32_bf16 v[88:91], v[136:139], v[170:173], v[88:91]
	v_mfma_f32_16x16x32_bf16 v[88:91], v[140:143], v[188:191], v[88:91]
	v_mfma_f32_16x16x32_bf16 v[80:83], v[136:139], v[192:195], v[80:83]
	v_mfma_f32_16x16x32_bf16 v[80:83], v[140:143], v[196:199], v[80:83]
	v_mfma_f32_16x16x32_bf16 v[72:75], v[136:139], v[200:203], v[72:75]
	v_mfma_f32_16x16x32_bf16 v[72:75], v[140:143], v[204:207], v[72:75]
	v_mfma_f32_16x16x32_bf16 v[104:107], v[136:139], v[242:245], v[104:107]
	v_mfma_f32_16x16x32_bf16 v[104:107], v[140:143], v[246:249], v[104:107]
	v_mfma_f32_16x16x32_bf16 v[40:43], v[162:165], v[242:245], v[40:43]
	v_mfma_f32_16x16x32_bf16 v[40:43], v[166:169], v[246:249], v[40:43]
	v_mfma_f32_16x16x32_bf16 v[8:11], v[162:165], v[200:203], v[8:11]
	v_mfma_f32_16x16x32_bf16 v[8:11], v[166:169], v[204:207], v[8:11]
	v_mfma_f32_16x16x32_bf16 v[16:19], v[162:165], v[192:195], v[16:19]
	v_mfma_f32_16x16x32_bf16 v[16:19], v[166:169], v[196:199], v[16:19]
	v_mfma_f32_16x16x32_bf16 v[24:27], v[162:165], v[170:173], v[24:27]
	v_mfma_f32_16x16x32_bf16 v[24:27], v[166:169], v[188:191], v[24:27]
	s_setprio 0
	s_barrier
	s_add_u32 s0, s0, 0x100
	s_addc_u32 s1, s1, 0
	s_add_u32 s72, s72, 0x100
	s_addc_u32 s73, s73, 0
	s_cmp_ge_u32 s88, s9
	s_mov_b32 s86, s88
	s_cbranch_scc0 .LBB0_365

; #define PG8_STAGE(bufoff, gbase, voff) do { _Pragma("unroll") for (int _i = 0; _i < 2; ++_i) \
;         __builtin_amdgcn_global_load_lds((const unsigned*)((const char*)(gbase) + (voff)[_i]), (PG8_LAS unsigned*)(lds + (bufoff) + ldsw + _i * 8192), 16, 0, 0); } while (0)
; #define PG8_LDA(dst, b, h) do { _Pragma("unroll") for (int m = 0; m < 4; ++m) _Pragma("unroll") for (int k = 0; k < 2; ++k) dst[m][k] = *(const PG8_LAS bf16x8*)(lds + PG8_SA(b, h) + aoff + m * 2048 + k * 1024); } while (0)
; #define PG8_LDB(dst, b, h) do { _Pragma("unroll") for (int n = 0; n < 2; ++n) _Pragma("unroll") for (int k = 0; k < 2; ++k) dst[n][k] = *(const PG8_LAS bf16x8*)(lds + PG8_SB(b, h) + boff + n * 2048 + k * 1024); } while (0)
; #define PG8_WAIT_V(n) asm volatile("s_waitcnt vmcnt(" #n ")" ::: "memory")
; #define PG8_WAIT_L(n) asm volatile("s_waitcnt lgkmcnt(" #n ")" ::: "memory")
; template <class Epi, class Sched, bool ALIGN_EPI = false, bool SP2 = false>
; __device__ __forceinline__ void gemm_phase(PG8_LAS unsigned char* lds, const Gemm g, const Sched& S, const Epi& E) {
;     ...
;         const bool has_next = S.next(ui + 1, nxt);
;         const char* nA = has_next ? (const char*)g.A + (size_t)nxt.pm * tstepA : cA; const char* nB = has_next ? (const char*)g.Bt + (size_t)nxt.pn * tstep : cB;
;         for (int t = 0; t < nt; t += 2) {
;             if constexpr (Epi::KHOOK) { if ((t & 7) == 0 && t != 0) E.khook(acc, t >> 3, wr, fr, lds); }
;             const bool last = (t == nt - 2);
;             const char* a1 = cA + (size_t)(t + 1) * kstep;
;             const char* a2 = last ? nA : cA + (size_t)(t + 2) * kstep; const char* b2 = last ? nB : cB + (size_t)(t + 2) * kstep;
;             const char* a3 = a2 + kstep; const char* b3 = b2 + kstep;
;             if (last && has_next) S.a_ready(nxt);
;             if constexpr (SP2) {
;             PG8_LDB(B0, 0, 0); PG8_LDB(B1, 0, 1); PG8_SCHED; PG8_LDA(At, 0, 0); PG8_STAGE(PG8_SA(1, 1), a1 + hstep, voffA);
;             PG8_WAIT_V(8); PG8_WAIT_L(0); PG8_BAR; PG8_MMA(0, 0, At, B0); PG8_MMA(0, 1, At, B1); PG8_BAR; PG8_SCHED;
;             PG8_LDA(At, 0, 1); PG8_STAGE(PG8_SB(0, 0), b2, voffB); PG8_STAGE(PG8_SB(0, 1), b2 + hstep, voffB); PG8_STAGE(PG8_SA(0, 0), a2, voffA);
;             PG8_WAIT_V(8); PG8_WAIT_L(0); PG8_BAR; PG8_MMA(1, 0, At, B0); PG8_MMA(1, 1, At, B1); PG8_BAR; PG8_SCHED;
.LBB0_468:
	s_add_i32 s78, s38, 2
	s_add_u32 s79, s0, 0x80
	s_addc_u32 s39, s1, 0
	s_cmp_eq_u32 s33, s38
	s_cselect_b32 s39, s7, s39
	s_cselect_b32 s38, s6, s79
	s_cselect_b32 s81, s23, s41
	s_cselect_b32 s80, s22, s40
	s_add_i32 s79, 0, 0x14000
	v_add_u32_e32 v148, s19, v162
	v_add_u32_e32 v171, s79, v162
	ds_read_b128 v[136:139], v148
	ds_read_b128 v[140:143], v148 offset:1024
	ds_read_b128 v[144:147], v148 offset:2048
	ds_read_b128 v[148:151], v148 offset:3072
	ds_read_b128 v[172:175], v171
	ds_read_b128 v[176:179], v171 offset:1024
	ds_read_b128 v[184:187], v171 offset:2048
	ds_read_b128 v[188:191], v171 offset:3072
	v_lshl_add_u64 v[180:181], s[0:1], 0, v[158:159]
	s_add_i32 m0, s46, 0xc000
	ds_read_b128 v[192:195], v167
	ds_read_b128 v[196:199], v167 offset:1024
	ds_read_b128 v[200:203], v167 offset:2048
	ds_read_b128 v[204:207], v167 offset:3072
	ds_read_b128 v[230:233], v167 offset:4096
	ds_read_b128 v[234:237], v167 offset:5120
	ds_read_b128 v[238:241], v167 offset:6144
	ds_read_b128 v[242:245], v167 offset:7168
	global_load_lds_dwordx4 v[180:181], off
	v_lshl_add_u64 v[180:181], s[0:1], 0, v[160:161]
	s_add_i32 m0, s46, 0xe000
	s_nop 0
	global_load_lds_dwordx4 v[180:181], off
	s_waitcnt vmcnt(8)
	s_waitcnt lgkmcnt(0)
	s_barrier
	s_setprio 1
	s_waitcnt lgkmcnt(0)
	v_mfma_f32_16x16x32_bf16 v[132:135], v[136:139], v[192:195], v[132:135]
	v_mfma_f32_16x16x32_bf16 v[132:135], v[140:143], v[196:199], v[132:135]
	v_mfma_f32_16x16x32_bf16 v[116:119], v[136:139], v[200:203], v[116:119]
	v_mfma_f32_16x16x32_bf16 v[116:119], v[140:143], v[204:207], v[116:119]
	v_mfma_f32_16x16x32_bf16 v[100:103], v[136:139], v[230:233], v[100:103]
	v_mfma_f32_16x16x32_bf16 v[100:103], v[140:143], v[234:237], v[100:103]
	v_mfma_f32_16x16x32_bf16 v[84:87], v[136:139], v[238:241], v[84:87]
	v_mfma_f32_16x16x32_bf16 v[84:87], v[140:143], v[242:245], v[84:87]
	v_mfma_f32_16x16x32_bf16 v[80:83], v[144:147], v[238:241], v[80:83]
	v_mfma_f32_16x16x32_bf16 v[80:83], v[148:151], v[242:245], v[80:83]
	v_mfma_f32_16x16x32_bf16 v[96:99], v[144:147], v[230:233], v[96:99]
	v_mfma_f32_16x16x32_bf16 v[96:99], v[148:151], v[234:237], v[96:99]
	v_mfma_f32_16x16x32_bf16 v[112:115], v[144:147], v[200:203], v[112:115]
	v_mfma_f32_16x16x32_bf16 v[112:115], v[148:151], v[204:207], v[112:115]
	v_mfma_f32_16x16x32_bf16 v[128:131], v[144:147], v[192:195], v[128:131]
	v_mfma_f32_16x16x32_bf16 v[128:131], v[148:151], v[196:199], v[128:131]
	v_mfma_f32_16x16x32_bf16 v[124:127], v[172:175], v[192:195], v[124:127]
	v_mfma_f32_16x16x32_bf16 v[124:127], v[176:179], v[196:199], v[124:127]
	v_mfma_f32_16x16x32_bf16 v[108:111], v[172:175], v[200:203], v[108:111]
	v_mfma_f32_16x16x32_bf16 v[108:111], v[176:179], v[204:207], v[108:111]
	v_mfma_f32_16x16x32_bf16 v[92:95], v[172:175], v[230:233], v[92:95]
	v_mfma_f32_16x16x32_bf16 v[92:95], v[176:179], v[234:237], v[92:95]
	v_mfma_f32_16x16x32_bf16 v[76:79], v[172:175], v[238:241], v[76:79]
	v_mfma_f32_16x16x32_bf16 v[76:79], v[176:179], v[242:245], v[76:79]
	v_mfma_f32_16x16x32_bf16 v[72:75], v[184:187], v[238:241], v[72:75]
	v_mfma_f32_16x16x32_bf16 v[72:75], v[188:191], v[242:245], v[72:75]
	v_mfma_f32_16x16x32_bf16 v[88:91], v[184:187], v[230:233], v[88:91]
	v_mfma_f32_16x16x32_bf16 v[88:91], v[188:191], v[234:237], v[88:91]
	v_mfma_f32_16x16x32_bf16 v[104:107], v[184:187], v[200:203], v[104:107]
	v_mfma_f32_16x16x32_bf16 v[104:107], v[188:191], v[204:207], v[104:107]
	v_mfma_f32_16x16x32_bf16 v[120:123], v[184:187], v[192:195], v[120:123]
	v_mfma_f32_16x16x32_bf16 v[120:123], v[188:191], v[196:199], v[120:123]
	s_setprio 0
	s_barrier
	s_add_i32 s82, s19, s42
	v_lshl_add_u64 v[180:181], s[80:81], 0, v[154:155]
	s_mov_b32 m0, s82
	ds_read_b128 v[192:195], v167 offset:16384
	ds_read_b128 v[196:199], v167 offset:17408
	ds_read_b128 v[200:203], v167 offset:18432
	ds_read_b128 v[204:207], v167 offset:19456
	ds_read_b128 v[230:233], v167 offset:20480
	ds_read_b128 v[234:237], v167 offset:21504
	ds_read_b128 v[238:241], v167 offset:22528
	ds_read_b128 v[242:245], v167 offset:23552
	global_load_lds_dwordx4 v[180:181], off
	s_add_i32 m0, s82, 0x2000
	v_lshl_add_u64 v[208:209], s[80:81], 0, v[2:3]
	s_add_u32 s80, s80, s48
	s_addc_u32 s81, s81, s49
	s_add_i32 s79, s79, s42
	global_load_lds_dwordx4 v[208:209], off
	v_lshl_add_u64 v[216:217], s[80:81], 0, v[154:155]
	s_mov_b32 m0, s79
	v_lshl_add_u64 v[224:225], s[80:81], 0, v[2:3]
	global_load_lds_dwordx4 v[216:217], off
	s_add_i32 m0, s79, 0x2000
	v_lshl_add_u64 v[226:227], s[38:39], 0, v[156:157]
	global_load_lds_dwordx4 v[224:225], off
	s_mov_b32 m0, s46
	v_lshl_add_u64 v[246:247], s[38:39], 0, v[152:153]
	global_load_lds_dwordx4 v[226:227], off
	s_mov_b32 m0, s47
	s_nop 0
	global_load_lds_dwordx4 v[246:247], off
	s_waitcnt vmcnt(8)
	s_waitcnt lgkmcnt(0)
	s_barrier
; #define PG8_STAGE(bufoff, gbase, voff) do { _Pragma("unroll") for (int _i = 0; _i < 2; ++_i) \
;         __builtin_amdgcn_global_load_lds((const unsigned*)((const char*)(gbase) + (voff)[_i]), (PG8_LAS unsigned*)(lds + (bufoff) + ldsw + _i * 8192), 16, 0, 0); } while (0)
; #define PG8_LDA(dst, b, h) do { _Pragma("unroll") for (int m = 0; m < 4; ++m) _Pragma("unroll") for (int k = 0; k < 2; ++k) dst[m][k] = *(const PG8_LAS bf16x8*)(lds + PG8_SA(b, h) + aoff + m * 2048 + k * 1024); } while (0)
; #define PG8_LDB(dst, b, h) do { _Pragma("unroll") for (int n = 0; n < 2; ++n) _Pragma("unroll") for (int k = 0; k < 2; ++k) dst[n][k] = *(const PG8_LAS bf16x8*)(lds + PG8_SB(b, h) + boff + n * 2048 + k * 1024); } while (0)
; #define PG8_MMA(ai, bj, At, Bt) do { __builtin_amdgcn_s_setprio(1); _Pragma("unroll") for (int m = 0; m < 4; ++m) _Pragma("unroll") for (int n = 0; n < 2; ++n) _Pragma("unroll") for (int k = 0; k < 2; ++k) \
;         acc[ai][bj][m][n] = __builtin_amdgcn_mfma_f32_16x16x32_bf16(Bt[n][k], At[m][k], acc[ai][bj][m][n], 0, 0, 0); __builtin_amdgcn_s_setprio(0); } while (0)
; #define PG8_WAIT_V(n) asm volatile("s_waitcnt vmcnt(" #n ")" ::: "memory")
; #define PG8_WAIT_L(n) asm volatile("s_waitcnt lgkmcnt(" #n ")" ::: "memory")
; #define PG8_BAR __builtin_amdgcn_s_barrier()
; #define PG8_SCHED __builtin_amdgcn_sched_barrier(0)
; template <class Epi, class Sched, bool ALIGN_EPI = false, bool SP2 = false>
; __device__ __forceinline__ void gemm_phase(PG8_LAS unsigned char* lds, const Gemm g, const Sched& S, const Epi& E) {
;     ...
;             PG8_WAIT_V(8); PG8_WAIT_L(0); PG8_BAR; PG8_MMA(1, 0, At, B0); PG8_MMA(1, 1, At, B1); PG8_BAR; PG8_SCHED;
;             PG8_LDB(B0, 1, 0); PG8_LDB(B1, 1, 1); PG8_SCHED; PG8_LDA(At, 1, 0); PG8_STAGE(PG8_SA(0, 1), a2 + hstep, voffA);
;             PG8_WAIT_V(8); PG8_WAIT_L(0); PG8_BAR; PG8_MMA(0, 0, At, B0); PG8_MMA(0, 1, At, B1); PG8_BAR; PG8_SCHED;
	s_setprio 1
	s_waitcnt lgkmcnt(0)
	v_mfma_f32_16x16x32_bf16 v[68:71], v[136:139], v[192:195], v[68:71]
	v_mfma_f32_16x16x32_bf16 v[68:71], v[140:143], v[196:199], v[68:71]
	v_mfma_f32_16x16x32_bf16 v[52:55], v[136:139], v[200:203], v[52:55]
	v_mfma_f32_16x16x32_bf16 v[52:55], v[140:143], v[204:207], v[52:55]
	v_mfma_f32_16x16x32_bf16 v[36:39], v[136:139], v[230:233], v[36:39]
	v_mfma_f32_16x16x32_bf16 v[36:39], v[140:143], v[234:237], v[36:39]
	v_mfma_f32_16x16x32_bf16 v[20:23], v[136:139], v[238:241], v[20:23]
	v_mfma_f32_16x16x32_bf16 v[20:23], v[140:143], v[242:245], v[20:23]
	v_mfma_f32_16x16x32_bf16 v[16:19], v[144:147], v[238:241], v[16:19]
	v_mfma_f32_16x16x32_bf16 v[16:19], v[148:151], v[242:245], v[16:19]
	v_mfma_f32_16x16x32_bf16 v[32:35], v[144:147], v[230:233], v[32:35]
	v_mfma_f32_16x16x32_bf16 v[32:35], v[148:151], v[234:237], v[32:35]
	v_mfma_f32_16x16x32_bf16 v[48:51], v[144:147], v[200:203], v[48:51]
	v_mfma_f32_16x16x32_bf16 v[48:51], v[148:151], v[204:207], v[48:51]
	v_mfma_f32_16x16x32_bf16 v[64:67], v[144:147], v[192:195], v[64:67]
	v_mfma_f32_16x16x32_bf16 v[64:67], v[148:151], v[196:199], v[64:67]
	v_mfma_f32_16x16x32_bf16 v[60:63], v[172:175], v[192:195], v[60:63]
	v_mfma_f32_16x16x32_bf16 v[60:63], v[176:179], v[196:199], v[60:63]
	v_mfma_f32_16x16x32_bf16 v[44:47], v[172:175], v[200:203], v[44:47]
	v_mfma_f32_16x16x32_bf16 v[44:47], v[176:179], v[204:207], v[44:47]
	v_mfma_f32_16x16x32_bf16 v[28:31], v[172:175], v[230:233], v[28:31]
	v_mfma_f32_16x16x32_bf16 v[28:31], v[176:179], v[234:237], v[28:31]
	v_mfma_f32_16x16x32_bf16 v[12:15], v[172:175], v[238:241], v[12:15]
	v_mfma_f32_16x16x32_bf16 v[12:15], v[176:179], v[242:245], v[12:15]
	v_mfma_f32_16x16x32_bf16 v[8:11], v[184:187], v[238:241], v[8:11]
	v_mfma_f32_16x16x32_bf16 v[8:11], v[188:191], v[242:245], v[8:11]
	v_mfma_f32_16x16x32_bf16 v[24:27], v[184:187], v[230:233], v[24:27]
	v_mfma_f32_16x16x32_bf16 v[24:27], v[188:191], v[234:237], v[24:27]
	v_mfma_f32_16x16x32_bf16 v[40:43], v[184:187], v[200:203], v[40:43]
	v_mfma_f32_16x16x32_bf16 v[40:43], v[188:191], v[204:207], v[40:43]
	v_mfma_f32_16x16x32_bf16 v[56:59], v[184:187], v[192:195], v[56:59]
	v_mfma_f32_16x16x32_bf16 v[56:59], v[188:191], v[196:199], v[56:59]
	s_setprio 0
	s_barrier
	s_add_i32 s79, 0, 0x1c000
	v_add_u32_e32 v148, s91, v162
	v_add_u32_e32 v171, s79, v162
	ds_read_b128 v[136:139], v148
	ds_read_b128 v[140:143], v148 offset:1024
	ds_read_b128 v[144:147], v148 offset:2048
	ds_read_b128 v[148:151], v148 offset:3072
	ds_read_b128 v[172:175], v171
	ds_read_b128 v[176:179], v171 offset:1024
	ds_read_b128 v[184:187], v171 offset:2048
	ds_read_b128 v[188:191], v171 offset:3072
	s_add_u32 s38, s38, s48
	s_addc_u32 s39, s39, s49
	s_mov_b32 m0, s52
	v_lshl_add_u64 v[248:249], s[38:39], 0, v[156:157]
	ds_read_b128 v[192:195], v167 offset:32768
	ds_read_b128 v[196:199], v167 offset:33792
	ds_read_b128 v[200:203], v167 offset:34816
	ds_read_b128 v[204:207], v167 offset:35840
	ds_read_b128 v[230:233], v167 offset:36864
	ds_read_b128 v[234:237], v167 offset:37888
	ds_read_b128 v[238:241], v167 offset:38912
	ds_read_b128 v[242:245], v167 offset:39936
	global_load_lds_dwordx4 v[248:249], off
	v_lshl_add_u64 v[248:249], s[38:39], 0, v[152:153]
	s_mov_b32 m0, s53
	s_nop 0
	global_load_lds_dwordx4 v[248:249], off
	s_waitcnt vmcnt(8)
	s_waitcnt lgkmcnt(0)
	s_barrier
	s_setprio 1
	s_waitcnt lgkmcnt(0)
	v_mfma_f32_16x16x32_bf16 v[132:135], v[136:139], v[192:195], v[132:135]
	v_mfma_f32_16x16x32_bf16 v[132:135], v[140:143], v[196:199], v[132:135]
	v_mfma_f32_16x16x32_bf16 v[116:119], v[136:139], v[200:203], v[116:119]
	v_mfma_f32_16x16x32_bf16 v[116:119], v[140:143], v[204:207], v[116:119]
	v_mfma_f32_16x16x32_bf16 v[100:103], v[136:139], v[230:233], v[100:103]
	v_mfma_f32_16x16x32_bf16 v[100:103], v[140:143], v[234:237], v[100:103]
	v_mfma_f32_16x16x32_bf16 v[84:87], v[136:139], v[238:241], v[84:87]
	v_mfma_f32_16x16x32_bf16 v[84:87], v[140:143], v[242:245], v[84:87]
	v_mfma_f32_16x16x32_bf16 v[80:83], v[144:147], v[238:241], v[80:83]
	v_mfma_f32_16x16x32_bf16 v[80:83], v[148:151], v[242:245], v[80:83]
	v_mfma_f32_16x16x32_bf16 v[96:99], v[144:147], v[230:233], v[96:99]
	v_mfma_f32_16x16x32_bf16 v[96:99], v[148:151], v[234:237], v[96:99]
	v_mfma_f32_16x16x32_bf16 v[112:115], v[144:147], v[200:203], v[112:115]
	v_mfma_f32_16x16x32_bf16 v[112:115], v[148:151], v[204:207], v[112:115]
	v_mfma_f32_16x16x32_bf16 v[128:131], v[144:147], v[192:195], v[128:131]
	v_mfma_f32_16x16x32_bf16 v[128:131], v[148:151], v[196:199], v[128:131]
	v_mfma_f32_16x16x32_bf16 v[124:127], v[172:175], v[192:195], v[124:127]
	v_mfma_f32_16x16x32_bf16 v[124:127], v[176:179], v[196:199], v[124:127]
	v_mfma_f32_16x16x32_bf16 v[108:111], v[172:175], v[200:203], v[108:111]
	v_mfma_f32_16x16x32_bf16 v[108:111], v[176:179], v[204:207], v[108:111]
	v_mfma_f32_16x16x32_bf16 v[92:95], v[172:175], v[230:233], v[92:95]
	v_mfma_f32_16x16x32_bf16 v[92:95], v[176:179], v[234:237], v[92:95]
	v_mfma_f32_16x16x32_bf16 v[76:79], v[172:175], v[238:241], v[76:79]
	v_mfma_f32_16x16x32_bf16 v[76:79], v[176:179], v[242:245], v[76:79]
	v_mfma_f32_16x16x32_bf16 v[72:75], v[184:187], v[238:241], v[72:75]
	v_mfma_f32_16x16x32_bf16 v[72:75], v[188:191], v[242:245], v[72:75]
	v_mfma_f32_16x16x32_bf16 v[88:91], v[184:187], v[230:233], v[88:91]
	v_mfma_f32_16x16x32_bf16 v[88:91], v[188:191], v[234:237], v[88:91]
	v_mfma_f32_16x16x32_bf16 v[104:107], v[184:187], v[200:203], v[104:107]
	v_mfma_f32_16x16x32_bf16 v[104:107], v[188:191], v[204:207], v[104:107]
	v_mfma_f32_16x16x32_bf16 v[120:123], v[184:187], v[192:195], v[120:123]
	v_mfma_f32_16x16x32_bf16 v[120:123], v[188:191], v[196:199], v[120:123]
	s_setprio 0
	s_barrier
; #define PG8_STAGE(bufoff, gbase, voff) do { _Pragma("unroll") for (int _i = 0; _i < 2; ++_i) \
;         __builtin_amdgcn_global_load_lds((const unsigned*)((const char*)(gbase) + (voff)[_i]), (PG8_LAS unsigned*)(lds + (bufoff) + ldsw + _i * 8192), 16, 0, 0); } while (0)
; #define PG8_LDA(dst, b, h) do { _Pragma("unroll") for (int m = 0; m < 4; ++m) _Pragma("unroll") for (int k = 0; k < 2; ++k) dst[m][k] = *(const PG8_LAS bf16x8*)(lds + PG8_SA(b, h) + aoff + m * 2048 + k * 1024); } while (0)
; #define PG8_MMA(ai, bj, At, Bt) do { __builtin_amdgcn_s_setprio(1); _Pragma("unroll") for (int m = 0; m < 4; ++m) _Pragma("unroll") for (int n = 0; n < 2; ++n) _Pragma("unroll") for (int k = 0; k < 2; ++k) \
;         acc[ai][bj][m][n] = __builtin_amdgcn_mfma_f32_16x16x32_bf16(Bt[n][k], At[m][k], acc[ai][bj][m][n], 0, 0, 0); __builtin_amdgcn_s_setprio(0); } while (0)
; #define PG8_WAIT_V(n) asm volatile("s_waitcnt vmcnt(" #n ")" ::: "memory")
; #define PG8_WAIT_L(n) asm volatile("s_waitcnt lgkmcnt(" #n ")" ::: "memory")
; #define PG8_BAR __builtin_amdgcn_s_barrier()
; #define PG8_SCHED __builtin_amdgcn_sched_barrier(0)
; template <class Epi, class Sched, bool ALIGN_EPI = false, bool SP2 = false>
; __device__ __forceinline__ void gemm_phase(PG8_LAS unsigned char* lds, const Gemm g, const Sched& S, const Epi& E) {
;     ...
;         for (int t = 0; t < nt; t += 2) {
;     ...
;             PG8_LDA(At, 1, 1); PG8_STAGE(PG8_SB(1, 0), b3, voffB); PG8_STAGE(PG8_SB(1, 1), b3 + hstep, voffB); PG8_STAGE(PG8_SA(1, 0), a3, voffA);
;             PG8_WAIT_V(8); PG8_WAIT_L(0); PG8_BAR; PG8_MMA(1, 0, At, B0); PG8_MMA(1, 1, At, B1); PG8_BAR; PG8_SCHED;
	s_add_i32 s38, s91, s42
	v_lshl_add_u64 v[180:181], v[180:181], 0, s[24:25]
	s_mov_b32 m0, s38
	ds_read_b128 v[192:195], v167 offset:49152
	ds_read_b128 v[196:199], v167 offset:50176
	ds_read_b128 v[200:203], v167 offset:51200
	ds_read_b128 v[204:207], v167 offset:52224
	ds_read_b128 v[230:233], v167 offset:53248
	ds_read_b128 v[234:237], v167 offset:54272
	ds_read_b128 v[238:241], v167 offset:55296
	ds_read_b128 v[242:245], v167 offset:56320
	global_load_lds_dwordx4 v[180:181], off
	v_lshl_add_u64 v[180:181], v[208:209], 0, s[24:25]
	s_add_i32 m0, s38, 0x2000
	s_add_i32 s38, s79, s42
	global_load_lds_dwordx4 v[180:181], off
	v_lshl_add_u64 v[180:181], v[216:217], 0, s[24:25]
	s_mov_b32 m0, s38
	s_nop 0
	global_load_lds_dwordx4 v[180:181], off
	v_lshl_add_u64 v[180:181], v[224:225], 0, s[24:25]
	s_add_i32 m0, s38, 0x2000
	s_nop 0
	global_load_lds_dwordx4 v[180:181], off
	v_lshl_add_u64 v[180:181], v[226:227], 0, s[24:25]
	s_mov_b32 m0, s72
	s_nop 0
	global_load_lds_dwordx4 v[180:181], off
	v_lshl_add_u64 v[180:181], v[246:247], 0, s[24:25]
	s_mov_b32 m0, s73
	s_nop 0
	global_load_lds_dwordx4 v[180:181], off
	s_waitcnt vmcnt(8)
	s_waitcnt lgkmcnt(0)
	s_barrier
	s_setprio 1
	s_waitcnt lgkmcnt(0)
	v_mfma_f32_16x16x32_bf16 v[68:71], v[136:139], v[192:195], v[68:71]
	v_mfma_f32_16x16x32_bf16 v[68:71], v[140:143], v[196:199], v[68:71]
	v_mfma_f32_16x16x32_bf16 v[52:55], v[136:139], v[200:203], v[52:55]
	v_mfma_f32_16x16x32_bf16 v[52:55], v[140:143], v[204:207], v[52:55]
	v_mfma_f32_16x16x32_bf16 v[36:39], v[136:139], v[230:233], v[36:39]
	v_mfma_f32_16x16x32_bf16 v[36:39], v[140:143], v[234:237], v[36:39]
	v_mfma_f32_16x16x32_bf16 v[20:23], v[136:139], v[238:241], v[20:23]
	v_mfma_f32_16x16x32_bf16 v[20:23], v[140:143], v[242:245], v[20:23]
	v_mfma_f32_16x16x32_bf16 v[16:19], v[144:147], v[238:241], v[16:19]
	v_mfma_f32_16x16x32_bf16 v[16:19], v[148:151], v[242:245], v[16:19]
	v_mfma_f32_16x16x32_bf16 v[32:35], v[144:147], v[230:233], v[32:35]
	v_mfma_f32_16x16x32_bf16 v[32:35], v[148:151], v[234:237], v[32:35]
	v_mfma_f32_16x16x32_bf16 v[48:51], v[144:147], v[200:203], v[48:51]
	v_mfma_f32_16x16x32_bf16 v[48:51], v[148:151], v[204:207], v[48:51]
	v_mfma_f32_16x16x32_bf16 v[64:67], v[144:147], v[192:195], v[64:67]
	v_mfma_f32_16x16x32_bf16 v[64:67], v[148:151], v[196:199], v[64:67]
	v_mfma_f32_16x16x32_bf16 v[60:63], v[172:175], v[192:195], v[60:63]
	v_mfma_f32_16x16x32_bf16 v[60:63], v[176:179], v[196:199], v[60:63]
	v_mfma_f32_16x16x32_bf16 v[44:47], v[172:175], v[200:203], v[44:47]
	v_mfma_f32_16x16x32_bf16 v[44:47], v[176:179], v[204:207], v[44:47]
	v_mfma_f32_16x16x32_bf16 v[28:31], v[172:175], v[230:233], v[28:31]
	v_mfma_f32_16x16x32_bf16 v[28:31], v[176:179], v[234:237], v[28:31]
	v_mfma_f32_16x16x32_bf16 v[12:15], v[172:175], v[238:241], v[12:15]
	v_mfma_f32_16x16x32_bf16 v[12:15], v[176:179], v[242:245], v[12:15]
	v_mfma_f32_16x16x32_bf16 v[8:11], v[184:187], v[238:241], v[8:11]
	v_mfma_f32_16x16x32_bf16 v[8:11], v[188:191], v[242:245], v[8:11]
	v_mfma_f32_16x16x32_bf16 v[24:27], v[184:187], v[230:233], v[24:27]
	v_mfma_f32_16x16x32_bf16 v[24:27], v[188:191], v[234:237], v[24:27]
	v_mfma_f32_16x16x32_bf16 v[40:43], v[184:187], v[200:203], v[40:43]
	v_mfma_f32_16x16x32_bf16 v[40:43], v[188:191], v[204:207], v[40:43]
	v_mfma_f32_16x16x32_bf16 v[56:59], v[184:187], v[192:195], v[56:59]
	v_mfma_f32_16x16x32_bf16 v[56:59], v[188:191], v[196:199], v[56:59]
	s_setprio 0
	s_barrier
	s_add_u32 s0, s0, 0x100
	s_addc_u32 s1, s1, 0
	s_add_u32 s40, s40, 0x100
	s_addc_u32 s41, s41, 0
	s_cmp_ge_u32 s78, s9
	s_mov_b32 s38, s78
	s_cbranch_scc0 .LBB0_468

; #define PG8_STAGE(bufoff, gbase, voff) do { _Pragma("unroll") for (int _i = 0; _i < 2; ++_i) \
;         __builtin_amdgcn_global_load_lds((const unsigned*)((const char*)(gbase) + (voff)[_i]), (PG8_LAS unsigned*)(lds + (bufoff) + ldsw + _i * 8192), 16, 0, 0); } while (0)
; #define PG8_LDA(dst, b, h) do { _Pragma("unroll") for (int m = 0; m < 4; ++m) _Pragma("unroll") for (int k = 0; k < 2; ++k) dst[m][k] = *(const PG8_LAS bf16x8*)(lds + PG8_SA(b, h) + aoff + m * 2048 + k * 1024); } while (0)
; #define PG8_LDB(dst, b, h) do { _Pragma("unroll") for (int n = 0; n < 2; ++n) _Pragma("unroll") for (int k = 0; k < 2; ++k) dst[n][k] = *(const PG8_LAS bf16x8*)(lds + PG8_SB(b, h) + boff + n * 2048 + k * 1024); } while (0)
; #define PG8_WAIT_V(n) asm volatile("s_waitcnt vmcnt(" #n ")" ::: "memory")
; #define PG8_WAIT_L(n) asm volatile("s_waitcnt lgkmcnt(" #n ")" ::: "memory")
; template <class Epi, class Sched, bool ALIGN_EPI = false, bool SP2 = false>
; __device__ __forceinline__ void gemm_phase(PG8_LAS unsigned char* lds, const Gemm g, const Sched& S, const Epi& E) {
;     ...
;         const bool has_next = S.next(ui + 1, nxt);
;         const char* nA = has_next ? (const char*)g.A + (size_t)nxt.pm * tstepA : cA; const char* nB = has_next ? (const char*)g.Bt + (size_t)nxt.pn * tstep : cB;
;         for (int t = 0; t < nt; t += 2) {
;             if constexpr (Epi::KHOOK) { if ((t & 7) == 0 && t != 0) E.khook(acc, t >> 3, wr, fr, lds); }
;             const bool last = (t == nt - 2);
;             const char* a1 = cA + (size_t)(t + 1) * kstep;
;             const char* a2 = last ? nA : cA + (size_t)(t + 2) * kstep; const char* b2 = last ? nB : cB + (size_t)(t + 2) * kstep;
;             const char* a3 = a2 + kstep; const char* b3 = b2 + kstep;
;             if (last && has_next) S.a_ready(nxt);
;             if constexpr (SP2) {
;             PG8_LDB(B0, 0, 0); PG8_LDB(B1, 0, 1); PG8_SCHED; PG8_LDA(At, 0, 0); PG8_STAGE(PG8_SA(1, 1), a1 + hstep, voffA);
;             PG8_WAIT_V(8); PG8_WAIT_L(0); PG8_BAR; PG8_MMA(0, 0, At, B0); PG8_MMA(0, 1, At, B1); PG8_BAR; PG8_SCHED;
;             PG8_LDA(At, 0, 1); PG8_STAGE(PG8_SB(0, 0), b2, voffB); PG8_STAGE(PG8_SB(0, 1), b2 + hstep, voffB); PG8_STAGE(PG8_SA(0, 0), a2, voffA);
;             PG8_WAIT_V(8); PG8_WAIT_L(0); PG8_BAR; PG8_MMA(1, 0, At, B0); PG8_MMA(1, 1, At, B1); PG8_BAR; PG8_SCHED;
.LBB0_501:
	s_add_i32 s80, s4, 2
	s_add_u32 s81, s0, 0x80
	s_addc_u32 s5, s1, 0
	s_cmp_eq_u32 s33, s4
	s_cselect_b32 s5, s23, s5
	s_cselect_b32 s4, s22, s81
	s_cselect_b32 s83, s41, s43
	s_cselect_b32 s82, s40, s42
	s_add_i32 s81, 0, 0x14000
	v_add_u32_e32 v148, s19, v164
	v_add_u32_e32 v162, s81, v164
	ds_read_b128 v[136:139], v148
	ds_read_b128 v[140:143], v148 offset:1024
	ds_read_b128 v[144:147], v148 offset:2048
	ds_read_b128 v[148:151], v148 offset:3072
	ds_read_b128 v[174:177], v162
	ds_read_b128 v[178:181], v162 offset:1024
	ds_read_b128 v[184:187], v162 offset:2048
	ds_read_b128 v[188:191], v162 offset:3072
	v_lshl_add_u64 v[162:163], s[0:1], 0, v[158:159]
	s_add_i32 m0, s45, 0xc000
	ds_read_b128 v[192:195], v170
	ds_read_b128 v[196:199], v170 offset:1024
	ds_read_b128 v[200:203], v170 offset:2048
	ds_read_b128 v[204:207], v170 offset:3072
	ds_read_b128 v[230:233], v170 offset:4096
	ds_read_b128 v[234:237], v170 offset:5120
	ds_read_b128 v[238:241], v170 offset:6144
	ds_read_b128 v[242:245], v170 offset:7168
	global_load_lds_dwordx4 v[162:163], off
	v_lshl_add_u64 v[162:163], s[0:1], 0, v[160:161]
	s_add_i32 m0, s45, 0xe000
	s_nop 0
	global_load_lds_dwordx4 v[162:163], off
	s_waitcnt vmcnt(8)
	s_waitcnt lgkmcnt(0)
	s_barrier
	s_setprio 1
	s_waitcnt lgkmcnt(0)
	v_mfma_f32_16x16x32_bf16 v[132:135], v[136:139], v[192:195], v[132:135]
	v_mfma_f32_16x16x32_bf16 v[132:135], v[140:143], v[196:199], v[132:135]
	v_mfma_f32_16x16x32_bf16 v[116:119], v[136:139], v[200:203], v[116:119]
	v_mfma_f32_16x16x32_bf16 v[116:119], v[140:143], v[204:207], v[116:119]
	v_mfma_f32_16x16x32_bf16 v[100:103], v[136:139], v[230:233], v[100:103]
	v_mfma_f32_16x16x32_bf16 v[100:103], v[140:143], v[234:237], v[100:103]
	v_mfma_f32_16x16x32_bf16 v[84:87], v[136:139], v[238:241], v[84:87]
	v_mfma_f32_16x16x32_bf16 v[84:87], v[140:143], v[242:245], v[84:87]
	v_mfma_f32_16x16x32_bf16 v[80:83], v[144:147], v[238:241], v[80:83]
	v_mfma_f32_16x16x32_bf16 v[80:83], v[148:151], v[242:245], v[80:83]
	v_mfma_f32_16x16x32_bf16 v[96:99], v[144:147], v[230:233], v[96:99]
	v_mfma_f32_16x16x32_bf16 v[96:99], v[148:151], v[234:237], v[96:99]
	v_mfma_f32_16x16x32_bf16 v[112:115], v[144:147], v[200:203], v[112:115]
	v_mfma_f32_16x16x32_bf16 v[112:115], v[148:151], v[204:207], v[112:115]
	v_mfma_f32_16x16x32_bf16 v[128:131], v[144:147], v[192:195], v[128:131]
	v_mfma_f32_16x16x32_bf16 v[128:131], v[148:151], v[196:199], v[128:131]
	v_mfma_f32_16x16x32_bf16 v[124:127], v[174:177], v[192:195], v[124:127]
	v_mfma_f32_16x16x32_bf16 v[124:127], v[178:181], v[196:199], v[124:127]
	v_mfma_f32_16x16x32_bf16 v[108:111], v[174:177], v[200:203], v[108:111]
	v_mfma_f32_16x16x32_bf16 v[108:111], v[178:181], v[204:207], v[108:111]
	v_mfma_f32_16x16x32_bf16 v[92:95], v[174:177], v[230:233], v[92:95]
	v_mfma_f32_16x16x32_bf16 v[92:95], v[178:181], v[234:237], v[92:95]
	v_mfma_f32_16x16x32_bf16 v[76:79], v[174:177], v[238:241], v[76:79]
	v_mfma_f32_16x16x32_bf16 v[76:79], v[178:181], v[242:245], v[76:79]
	v_mfma_f32_16x16x32_bf16 v[72:75], v[184:187], v[238:241], v[72:75]
	v_mfma_f32_16x16x32_bf16 v[72:75], v[188:191], v[242:245], v[72:75]
	v_mfma_f32_16x16x32_bf16 v[88:91], v[184:187], v[230:233], v[88:91]
	v_mfma_f32_16x16x32_bf16 v[88:91], v[188:191], v[234:237], v[88:91]
	v_mfma_f32_16x16x32_bf16 v[104:107], v[184:187], v[200:203], v[104:107]
	v_mfma_f32_16x16x32_bf16 v[104:107], v[188:191], v[204:207], v[104:107]
	v_mfma_f32_16x16x32_bf16 v[120:123], v[184:187], v[192:195], v[120:123]
	v_mfma_f32_16x16x32_bf16 v[120:123], v[188:191], v[196:199], v[120:123]
	s_setprio 0
	s_barrier
	s_add_i32 s84, s19, s44
	v_lshl_add_u64 v[162:163], s[82:83], 0, v[152:153]
	s_mov_b32 m0, s84
	ds_read_b128 v[192:195], v170 offset:16384
	ds_read_b128 v[196:199], v170 offset:17408
	ds_read_b128 v[200:203], v170 offset:18432
	ds_read_b128 v[204:207], v170 offset:19456
	ds_read_b128 v[230:233], v170 offset:20480
	ds_read_b128 v[234:237], v170 offset:21504
	ds_read_b128 v[238:241], v170 offset:22528
	ds_read_b128 v[242:245], v170 offset:23552
	global_load_lds_dwordx4 v[162:163], off
	s_add_i32 m0, s84, 0x2000
	v_lshl_add_u64 v[208:209], s[82:83], 0, v[156:157]
	s_add_u32 s82, s82, s48
	s_addc_u32 s83, s83, s49
	s_add_i32 s81, s81, s44
	global_load_lds_dwordx4 v[208:209], off
	v_lshl_add_u64 v[246:247], s[82:83], 0, v[152:153]
	s_mov_b32 m0, s81
	v_lshl_add_u64 v[248:249], s[82:83], 0, v[156:157]
	global_load_lds_dwordx4 v[246:247], off
	s_add_i32 m0, s81, 0x2000
	v_lshl_add_u64 v[216:217], s[4:5], 0, v[2:3]
	global_load_lds_dwordx4 v[248:249], off
	s_mov_b32 m0, s45
	v_lshl_add_u64 v[224:225], s[4:5], 0, v[154:155]
	global_load_lds_dwordx4 v[216:217], off
	s_mov_b32 m0, s46
	s_nop 0
	global_load_lds_dwordx4 v[224:225], off
	s_waitcnt vmcnt(8)
	s_waitcnt lgkmcnt(0)
	s_barrier
; #define PG8_STAGE(bufoff, gbase, voff) do { _Pragma("unroll") for (int _i = 0; _i < 2; ++_i) \
;         __builtin_amdgcn_global_load_lds((const unsigned*)((const char*)(gbase) + (voff)[_i]), (PG8_LAS unsigned*)(lds + (bufoff) + ldsw + _i * 8192), 16, 0, 0); } while (0)
; #define PG8_LDA(dst, b, h) do { _Pragma("unroll") for (int m = 0; m < 4; ++m) _Pragma("unroll") for (int k = 0; k < 2; ++k) dst[m][k] = *(const PG8_LAS bf16x8*)(lds + PG8_SA(b, h) + aoff + m * 2048 + k * 1024); } while (0)
; #define PG8_LDB(dst, b, h) do { _Pragma("unroll") for (int n = 0; n < 2; ++n) _Pragma("unroll") for (int k = 0; k < 2; ++k) dst[n][k] = *(const PG8_LAS bf16x8*)(lds + PG8_SB(b, h) + boff + n * 2048 + k * 1024); } while (0)
; #define PG8_MMA(ai, bj, At, Bt) do { __builtin_amdgcn_s_setprio(1); _Pragma("unroll") for (int m = 0; m < 4; ++m) _Pragma("unroll") for (int n = 0; n < 2; ++n) _Pragma("unroll") for (int k = 0; k < 2; ++k) \
;         acc[ai][bj][m][n] = __builtin_amdgcn_mfma_f32_16x16x32_bf16(Bt[n][k], At[m][k], acc[ai][bj][m][n], 0, 0, 0); __builtin_amdgcn_s_setprio(0); } while (0)
; #define PG8_WAIT_V(n) asm volatile("s_waitcnt vmcnt(" #n ")" ::: "memory")
; #define PG8_WAIT_L(n) asm volatile("s_waitcnt lgkmcnt(" #n ")" ::: "memory")
; #define PG8_BAR __builtin_amdgcn_s_barrier()
; #define PG8_SCHED __builtin_amdgcn_sched_barrier(0)
; template <class Epi, class Sched, bool ALIGN_EPI = false, bool SP2 = false>
; __device__ __forceinline__ void gemm_phase(PG8_LAS unsigned char* lds, const Gemm g, const Sched& S, const Epi& E) {
;     ...
;             PG8_WAIT_V(8); PG8_WAIT_L(0); PG8_BAR; PG8_MMA(1, 0, At, B0); PG8_MMA(1, 1, At, B1); PG8_BAR; PG8_SCHED;
;             PG8_LDB(B0, 1, 0); PG8_LDB(B1, 1, 1); PG8_SCHED; PG8_LDA(At, 1, 0); PG8_STAGE(PG8_SA(0, 1), a2 + hstep, voffA);
;             PG8_WAIT_V(8); PG8_WAIT_L(0); PG8_BAR; PG8_MMA(0, 0, At, B0); PG8_MMA(0, 1, At, B1); PG8_BAR; PG8_SCHED;
	s_setprio 1
	s_waitcnt lgkmcnt(0)
	v_mfma_f32_16x16x32_bf16 v[68:71], v[136:139], v[192:195], v[68:71]
	v_mfma_f32_16x16x32_bf16 v[68:71], v[140:143], v[196:199], v[68:71]
	v_mfma_f32_16x16x32_bf16 v[52:55], v[136:139], v[200:203], v[52:55]
	v_mfma_f32_16x16x32_bf16 v[52:55], v[140:143], v[204:207], v[52:55]
	v_mfma_f32_16x16x32_bf16 v[36:39], v[136:139], v[230:233], v[36:39]
	v_mfma_f32_16x16x32_bf16 v[36:39], v[140:143], v[234:237], v[36:39]
	v_mfma_f32_16x16x32_bf16 v[20:23], v[136:139], v[238:241], v[20:23]
	v_mfma_f32_16x16x32_bf16 v[20:23], v[140:143], v[242:245], v[20:23]
	v_mfma_f32_16x16x32_bf16 v[16:19], v[144:147], v[238:241], v[16:19]
	v_mfma_f32_16x16x32_bf16 v[16:19], v[148:151], v[242:245], v[16:19]
	v_mfma_f32_16x16x32_bf16 v[32:35], v[144:147], v[230:233], v[32:35]
	v_mfma_f32_16x16x32_bf16 v[32:35], v[148:151], v[234:237], v[32:35]
	v_mfma_f32_16x16x32_bf16 v[48:51], v[144:147], v[200:203], v[48:51]
	v_mfma_f32_16x16x32_bf16 v[48:51], v[148:151], v[204:207], v[48:51]
	v_mfma_f32_16x16x32_bf16 v[64:67], v[144:147], v[192:195], v[64:67]
	v_mfma_f32_16x16x32_bf16 v[64:67], v[148:151], v[196:199], v[64:67]
	v_mfma_f32_16x16x32_bf16 v[60:63], v[174:177], v[192:195], v[60:63]
	v_mfma_f32_16x16x32_bf16 v[60:63], v[178:181], v[196:199], v[60:63]
	v_mfma_f32_16x16x32_bf16 v[44:47], v[174:177], v[200:203], v[44:47]
	v_mfma_f32_16x16x32_bf16 v[44:47], v[178:181], v[204:207], v[44:47]
	v_mfma_f32_16x16x32_bf16 v[28:31], v[174:177], v[230:233], v[28:31]
	v_mfma_f32_16x16x32_bf16 v[28:31], v[178:181], v[234:237], v[28:31]
	v_mfma_f32_16x16x32_bf16 v[12:15], v[174:177], v[238:241], v[12:15]
	v_mfma_f32_16x16x32_bf16 v[12:15], v[178:181], v[242:245], v[12:15]
	v_mfma_f32_16x16x32_bf16 v[8:11], v[184:187], v[238:241], v[8:11]
	v_mfma_f32_16x16x32_bf16 v[8:11], v[188:191], v[242:245], v[8:11]
	v_mfma_f32_16x16x32_bf16 v[24:27], v[184:187], v[230:233], v[24:27]
	v_mfma_f32_16x16x32_bf16 v[24:27], v[188:191], v[234:237], v[24:27]
	v_mfma_f32_16x16x32_bf16 v[40:43], v[184:187], v[200:203], v[40:43]
	v_mfma_f32_16x16x32_bf16 v[40:43], v[188:191], v[204:207], v[40:43]
	v_mfma_f32_16x16x32_bf16 v[56:59], v[184:187], v[192:195], v[56:59]
	v_mfma_f32_16x16x32_bf16 v[56:59], v[188:191], v[196:199], v[56:59]
	s_setprio 0
	s_barrier
	s_add_i32 s81, 0, 0x1c000
	v_add_u32_e32 v148, s91, v164
	v_add_u32_e32 v173, s81, v164
	ds_read_b128 v[136:139], v148
	ds_read_b128 v[140:143], v148 offset:1024
	ds_read_b128 v[144:147], v148 offset:2048
	ds_read_b128 v[148:151], v148 offset:3072
	ds_read_b128 v[174:177], v173
	ds_read_b128 v[178:181], v173 offset:1024
	ds_read_b128 v[184:187], v173 offset:2048
	ds_read_b128 v[188:191], v173 offset:3072
	s_add_u32 s4, s4, s48
	s_addc_u32 s5, s5, s49
	s_mov_b32 m0, s47
	v_lshl_add_u64 v[226:227], s[4:5], 0, v[2:3]
	ds_read_b128 v[192:195], v170 offset:32768
	ds_read_b128 v[196:199], v170 offset:33792
	ds_read_b128 v[200:203], v170 offset:34816
	ds_read_b128 v[204:207], v170 offset:35840
	ds_read_b128 v[230:233], v170 offset:36864
	ds_read_b128 v[234:237], v170 offset:37888
	ds_read_b128 v[238:241], v170 offset:38912
	ds_read_b128 v[242:245], v170 offset:39936
	global_load_lds_dwordx4 v[226:227], off
	v_lshl_add_u64 v[226:227], s[4:5], 0, v[154:155]
	s_mov_b32 m0, s52
	s_nop 0
	global_load_lds_dwordx4 v[226:227], off
	s_waitcnt vmcnt(8)
	s_waitcnt lgkmcnt(0)
	s_barrier
	s_setprio 1
	s_waitcnt lgkmcnt(0)
	v_mfma_f32_16x16x32_bf16 v[132:135], v[136:139], v[192:195], v[132:135]
	v_mfma_f32_16x16x32_bf16 v[132:135], v[140:143], v[196:199], v[132:135]
	v_mfma_f32_16x16x32_bf16 v[116:119], v[136:139], v[200:203], v[116:119]
	v_mfma_f32_16x16x32_bf16 v[116:119], v[140:143], v[204:207], v[116:119]
	v_mfma_f32_16x16x32_bf16 v[100:103], v[136:139], v[230:233], v[100:103]
	v_mfma_f32_16x16x32_bf16 v[100:103], v[140:143], v[234:237], v[100:103]
	v_mfma_f32_16x16x32_bf16 v[84:87], v[136:139], v[238:241], v[84:87]
	v_mfma_f32_16x16x32_bf16 v[84:87], v[140:143], v[242:245], v[84:87]
	v_mfma_f32_16x16x32_bf16 v[80:83], v[144:147], v[238:241], v[80:83]
	v_mfma_f32_16x16x32_bf16 v[80:83], v[148:151], v[242:245], v[80:83]
	v_mfma_f32_16x16x32_bf16 v[96:99], v[144:147], v[230:233], v[96:99]
	v_mfma_f32_16x16x32_bf16 v[96:99], v[148:151], v[234:237], v[96:99]
	v_mfma_f32_16x16x32_bf16 v[112:115], v[144:147], v[200:203], v[112:115]
	v_mfma_f32_16x16x32_bf16 v[112:115], v[148:151], v[204:207], v[112:115]
	v_mfma_f32_16x16x32_bf16 v[128:131], v[144:147], v[192:195], v[128:131]
	v_mfma_f32_16x16x32_bf16 v[128:131], v[148:151], v[196:199], v[128:131]
	v_mfma_f32_16x16x32_bf16 v[124:127], v[174:177], v[192:195], v[124:127]
	v_mfma_f32_16x16x32_bf16 v[124:127], v[178:181], v[196:199], v[124:127]
	v_mfma_f32_16x16x32_bf16 v[108:111], v[174:177], v[200:203], v[108:111]
	v_mfma_f32_16x16x32_bf16 v[108:111], v[178:181], v[204:207], v[108:111]
	v_mfma_f32_16x16x32_bf16 v[92:95], v[174:177], v[230:233], v[92:95]
	v_mfma_f32_16x16x32_bf16 v[92:95], v[178:181], v[234:237], v[92:95]
	v_mfma_f32_16x16x32_bf16 v[76:79], v[174:177], v[238:241], v[76:79]
	v_mfma_f32_16x16x32_bf16 v[76:79], v[178:181], v[242:245], v[76:79]
	v_mfma_f32_16x16x32_bf16 v[72:75], v[184:187], v[238:241], v[72:75]
	v_mfma_f32_16x16x32_bf16 v[72:75], v[188:191], v[242:245], v[72:75]
	v_mfma_f32_16x16x32_bf16 v[88:91], v[184:187], v[230:233], v[88:91]
	v_mfma_f32_16x16x32_bf16 v[88:91], v[188:191], v[234:237], v[88:91]
	v_mfma_f32_16x16x32_bf16 v[104:107], v[184:187], v[200:203], v[104:107]
	v_mfma_f32_16x16x32_bf16 v[104:107], v[188:191], v[204:207], v[104:107]
	v_mfma_f32_16x16x32_bf16 v[120:123], v[184:187], v[192:195], v[120:123]
	v_mfma_f32_16x16x32_bf16 v[120:123], v[188:191], v[196:199], v[120:123]
	s_setprio 0
	s_barrier
; #define PG8_STAGE(bufoff, gbase, voff) do { _Pragma("unroll") for (int _i = 0; _i < 2; ++_i) \
;         __builtin_amdgcn_global_load_lds((const unsigned*)((const char*)(gbase) + (voff)[_i]), (PG8_LAS unsigned*)(lds + (bufoff) + ldsw + _i * 8192), 16, 0, 0); } while (0)
; #define PG8_LDA(dst, b, h) do { _Pragma("unroll") for (int m = 0; m < 4; ++m) _Pragma("unroll") for (int k = 0; k < 2; ++k) dst[m][k] = *(const PG8_LAS bf16x8*)(lds + PG8_SA(b, h) + aoff + m * 2048 + k * 1024); } while (0)
; #define PG8_MMA(ai, bj, At, Bt) do { __builtin_amdgcn_s_setprio(1); _Pragma("unroll") for (int m = 0; m < 4; ++m) _Pragma("unroll") for (int n = 0; n < 2; ++n) _Pragma("unroll") for (int k = 0; k < 2; ++k) \
;         acc[ai][bj][m][n] = __builtin_amdgcn_mfma_f32_16x16x32_bf16(Bt[n][k], At[m][k], acc[ai][bj][m][n], 0, 0, 0); __builtin_amdgcn_s_setprio(0); } while (0)
; #define PG8_WAIT_V(n) asm volatile("s_waitcnt vmcnt(" #n ")" ::: "memory")
; #define PG8_WAIT_L(n) asm volatile("s_waitcnt lgkmcnt(" #n ")" ::: "memory")
; #define PG8_BAR __builtin_amdgcn_s_barrier()
; #define PG8_SCHED __builtin_amdgcn_sched_barrier(0)
; template <class Epi, class Sched, bool ALIGN_EPI = false, bool SP2 = false>
; __device__ __forceinline__ void gemm_phase(PG8_LAS unsigned char* lds, const Gemm g, const Sched& S, const Epi& E) {
;     ...
;         for (int t = 0; t < nt; t += 2) {
;     ...
;             PG8_LDA(At, 1, 1); PG8_STAGE(PG8_SB(1, 0), b3, voffB); PG8_STAGE(PG8_SB(1, 1), b3 + hstep, voffB); PG8_STAGE(PG8_SA(1, 0), a3, voffA);
;             PG8_WAIT_V(8); PG8_WAIT_L(0); PG8_BAR; PG8_MMA(1, 0, At, B0); PG8_MMA(1, 1, At, B1); PG8_BAR; PG8_SCHED;
	s_add_i32 s4, s91, s44
	v_lshl_add_u64 v[162:163], v[162:163], 0, s[24:25]
	s_mov_b32 m0, s4
	ds_read_b128 v[192:195], v170 offset:49152
	ds_read_b128 v[196:199], v170 offset:50176
	ds_read_b128 v[200:203], v170 offset:51200
	ds_read_b128 v[204:207], v170 offset:52224
	ds_read_b128 v[230:233], v170 offset:53248
	ds_read_b128 v[234:237], v170 offset:54272
	ds_read_b128 v[238:241], v170 offset:55296
	ds_read_b128 v[242:245], v170 offset:56320
	global_load_lds_dwordx4 v[162:163], off
	v_lshl_add_u64 v[162:163], v[208:209], 0, s[24:25]
	s_add_i32 m0, s4, 0x2000
	s_add_i32 s4, s81, s44
	global_load_lds_dwordx4 v[162:163], off
	v_lshl_add_u64 v[162:163], v[246:247], 0, s[24:25]
	s_mov_b32 m0, s4
	s_nop 0
	global_load_lds_dwordx4 v[162:163], off
	v_lshl_add_u64 v[162:163], v[248:249], 0, s[24:25]
	s_add_i32 m0, s4, 0x2000
	s_nop 0
	global_load_lds_dwordx4 v[162:163], off
	v_lshl_add_u64 v[162:163], v[216:217], 0, s[24:25]
	s_mov_b32 m0, s53
	s_nop 0
	global_load_lds_dwordx4 v[162:163], off
	v_lshl_add_u64 v[162:163], v[224:225], 0, s[24:25]
	s_mov_b32 m0, s72
	s_nop 0
	global_load_lds_dwordx4 v[162:163], off
	s_waitcnt vmcnt(8)
	s_waitcnt lgkmcnt(0)
	s_barrier
	s_setprio 1
	s_waitcnt lgkmcnt(0)
	v_mfma_f32_16x16x32_bf16 v[68:71], v[136:139], v[192:195], v[68:71]
	v_mfma_f32_16x16x32_bf16 v[68:71], v[140:143], v[196:199], v[68:71]
	v_mfma_f32_16x16x32_bf16 v[52:55], v[136:139], v[200:203], v[52:55]
	v_mfma_f32_16x16x32_bf16 v[52:55], v[140:143], v[204:207], v[52:55]
	v_mfma_f32_16x16x32_bf16 v[36:39], v[136:139], v[230:233], v[36:39]
	v_mfma_f32_16x16x32_bf16 v[36:39], v[140:143], v[234:237], v[36:39]
	v_mfma_f32_16x16x32_bf16 v[20:23], v[136:139], v[238:241], v[20:23]
	v_mfma_f32_16x16x32_bf16 v[20:23], v[140:143], v[242:245], v[20:23]
	v_mfma_f32_16x16x32_bf16 v[16:19], v[144:147], v[238:241], v[16:19]
	v_mfma_f32_16x16x32_bf16 v[16:19], v[148:151], v[242:245], v[16:19]
	v_mfma_f32_16x16x32_bf16 v[32:35], v[144:147], v[230:233], v[32:35]
	v_mfma_f32_16x16x32_bf16 v[32:35], v[148:151], v[234:237], v[32:35]
	v_mfma_f32_16x16x32_bf16 v[48:51], v[144:147], v[200:203], v[48:51]
	v_mfma_f32_16x16x32_bf16 v[48:51], v[148:151], v[204:207], v[48:51]
	v_mfma_f32_16x16x32_bf16 v[64:67], v[144:147], v[192:195], v[64:67]
	v_mfma_f32_16x16x32_bf16 v[64:67], v[148:151], v[196:199], v[64:67]
	v_mfma_f32_16x16x32_bf16 v[60:63], v[174:177], v[192:195], v[60:63]
	v_mfma_f32_16x16x32_bf16 v[60:63], v[178:181], v[196:199], v[60:63]
	v_mfma_f32_16x16x32_bf16 v[44:47], v[174:177], v[200:203], v[44:47]
	v_mfma_f32_16x16x32_bf16 v[44:47], v[178:181], v[204:207], v[44:47]
	v_mfma_f32_16x16x32_bf16 v[28:31], v[174:177], v[230:233], v[28:31]
	v_mfma_f32_16x16x32_bf16 v[28:31], v[178:181], v[234:237], v[28:31]
	v_mfma_f32_16x16x32_bf16 v[12:15], v[174:177], v[238:241], v[12:15]
	v_mfma_f32_16x16x32_bf16 v[12:15], v[178:181], v[242:245], v[12:15]
	v_mfma_f32_16x16x32_bf16 v[8:11], v[184:187], v[238:241], v[8:11]
	v_mfma_f32_16x16x32_bf16 v[8:11], v[188:191], v[242:245], v[8:11]
	v_mfma_f32_16x16x32_bf16 v[24:27], v[184:187], v[230:233], v[24:27]
	v_mfma_f32_16x16x32_bf16 v[24:27], v[188:191], v[234:237], v[24:27]
	v_mfma_f32_16x16x32_bf16 v[40:43], v[184:187], v[200:203], v[40:43]
	v_mfma_f32_16x16x32_bf16 v[40:43], v[188:191], v[204:207], v[40:43]
	v_mfma_f32_16x16x32_bf16 v[56:59], v[184:187], v[192:195], v[56:59]
	v_mfma_f32_16x16x32_bf16 v[56:59], v[188:191], v[196:199], v[56:59]
	s_setprio 0
	s_barrier
	s_add_u32 s0, s0, 0x100
	s_addc_u32 s1, s1, 0
	s_add_u32 s42, s42, 0x100
	s_addc_u32 s43, s43, 0
	s_cmp_ge_u32 s80, s9
	s_mov_b32 s4, s80
	s_cbranch_scc0 .LBB0_501
